# rstd of the 8 rows computed inside the K loop (iterations 5,6) instead of in the serial epilogue; plus gain-once fix in mixer output sections
# baseline (speedup 1.0000x reference)
.LBB0_159:
	ds_read_b128 v[144:147], v156
	ds_read_b128 v[148:151], v156 offset:1024
	ds_read_b128 v[160:163], v156 offset:2048
	ds_read_b128 v[164:167], v156 offset:3072
	s_add_u32 s52, s8, 0xfffc0080
	s_addc_u32 s53, s9, -1
	s_cmp_eq_u32 s68, 12
	s_cselect_b32 s55, s7, s53
	s_cselect_b32 s54, s45, s52
	s_cselect_b32 s53, s43, s67
	s_cselect_b32 s52, s65, s66
	v_lshl_add_u64 v[200:201], s[8:9], 0, v[136:137]
	s_add_i32 m0, s33, 0xc000
	ds_read_b128 v[168:171], v157
	ds_read_b128 v[172:175], v157 offset:1024
	ds_read_b128 v[176:179], v157 offset:2048
	ds_read_b128 v[180:183], v157 offset:3072
	ds_read_b128 v[184:187], v157 offset:4096
	ds_read_b128 v[188:191], v157 offset:5120
	ds_read_b128 v[192:195], v157 offset:6144
	ds_read_b128 v[196:199], v157 offset:7168
	global_load_lds_dwordx4 v[200:201], off
	v_lshl_add_u64 v[200:201], s[8:9], 0, v[138:139]
	s_add_i32 m0, s33, 0xe000
	s_nop 0
	global_load_lds_dwordx4 v[200:201], off
	s_waitcnt lgkmcnt(8)
	s_barrier
	s_waitcnt lgkmcnt(0)
	s_setprio 1
	s_waitcnt lgkmcnt(0)
	v_mfma_f32_16x16x32_bf16 v[124:127], v[144:147], v[168:171], v[124:127]
	v_mfma_f32_16x16x32_bf16 v[120:123], v[160:163], v[168:171], v[120:123]
	v_mfma_f32_16x16x32_bf16 v[116:119], v[144:147], v[176:179], v[116:119]
	v_mfma_f32_16x16x32_bf16 v[108:111], v[160:163], v[176:179], v[108:111]
	v_mfma_f32_16x16x32_bf16 v[100:103], v[144:147], v[184:187], v[100:103]
	v_mfma_f32_16x16x32_bf16 v[92:95], v[160:163], v[184:187], v[92:95]
	v_mfma_f32_16x16x32_bf16 v[84:87], v[144:147], v[192:195], v[84:87]
	v_mfma_f32_16x16x32_bf16 v[76:79], v[160:163], v[192:195], v[76:79]
	v_mfma_f32_16x16x32_bf16 v[124:127], v[148:151], v[172:175], v[124:127]
	v_mfma_f32_16x16x32_bf16 v[120:123], v[164:167], v[172:175], v[120:123]
	v_mfma_f32_16x16x32_bf16 v[116:119], v[148:151], v[180:183], v[116:119]
	v_mfma_f32_16x16x32_bf16 v[108:111], v[164:167], v[180:183], v[108:111]
	v_mfma_f32_16x16x32_bf16 v[100:103], v[148:151], v[188:191], v[100:103]
	v_mfma_f32_16x16x32_bf16 v[92:95], v[164:167], v[188:191], v[92:95]
	v_mfma_f32_16x16x32_bf16 v[84:87], v[148:151], v[196:199], v[84:87]
	v_mfma_f32_16x16x32_bf16 v[76:79], v[164:167], v[196:199], v[76:79]
	s_setprio 0
	s_barrier
	s_add_i32 s69, s60, s1
	v_lshl_add_u64 v[218:219], s[52:53], 0, v[132:133]
	s_mov_b32 m0, s69
	ds_read_b128 v[200:203], v158
	ds_read_b128 v[206:209], v158 offset:1024
	ds_read_b128 v[210:213], v158 offset:2048
	ds_read_b128 v[214:217], v158 offset:3072
	global_load_lds_dwordx4 v[218:219], off
	v_lshl_add_u64 v[220:221], s[52:53], 0, v[128:129]
	s_add_i32 m0, s69, 0x2000
	s_nop 0
	global_load_lds_dwordx4 v[220:221], off
	s_barrier
	s_waitcnt lgkmcnt(0)
	s_setprio 1
	s_waitcnt lgkmcnt(0)
	v_mfma_f32_16x16x32_bf16 v[112:115], v[200:203], v[168:171], v[112:115]
	v_mfma_f32_16x16x32_bf16 v[104:107], v[210:213], v[168:171], v[104:107]
	v_mfma_f32_16x16x32_bf16 v[96:99], v[200:203], v[176:179], v[96:99]
	v_mfma_f32_16x16x32_bf16 v[88:91], v[210:213], v[176:179], v[88:91]
	v_mfma_f32_16x16x32_bf16 v[80:83], v[200:203], v[184:187], v[80:83]
	v_mfma_f32_16x16x32_bf16 v[72:75], v[210:213], v[184:187], v[72:75]
	v_mfma_f32_16x16x32_bf16 v[68:71], v[200:203], v[192:195], v[68:71]
	v_mfma_f32_16x16x32_bf16 v[64:67], v[210:213], v[192:195], v[64:67]
	v_mfma_f32_16x16x32_bf16 v[112:115], v[206:209], v[172:175], v[112:115]
	v_mfma_f32_16x16x32_bf16 v[104:107], v[214:217], v[172:175], v[104:107]
	v_mfma_f32_16x16x32_bf16 v[96:99], v[206:209], v[180:183], v[96:99]
	v_mfma_f32_16x16x32_bf16 v[88:91], v[214:217], v[180:183], v[88:91]
	v_mfma_f32_16x16x32_bf16 v[80:83], v[206:209], v[188:191], v[80:83]
	v_mfma_f32_16x16x32_bf16 v[72:75], v[214:217], v[188:191], v[72:75]
	v_mfma_f32_16x16x32_bf16 v[68:71], v[206:209], v[196:199], v[68:71]
	v_mfma_f32_16x16x32_bf16 v[64:67], v[214:217], v[196:199], v[64:67]
	s_setprio 0
	s_mov_b32 m0, s33
	v_lshl_add_u64 v[222:223], s[54:55], 0, v[134:135]
	s_barrier
	ds_read_b128 v[168:171], v157 offset:16384
	ds_read_b128 v[172:175], v157 offset:17408
	ds_read_b128 v[176:179], v157 offset:18432
	ds_read_b128 v[180:183], v157 offset:19456
	ds_read_b128 v[184:187], v157 offset:20480
	ds_read_b128 v[188:191], v157 offset:21504
	ds_read_b128 v[192:195], v157 offset:22528
	ds_read_b128 v[196:199], v157 offset:23552
	global_load_lds_dwordx4 v[222:223], off
	v_lshl_add_u64 v[224:225], s[54:55], 0, v[130:131]
	s_mov_b32 m0, s34
	s_nop 0
	global_load_lds_dwordx4 v[224:225], off
	s_barrier
	s_waitcnt lgkmcnt(0)
	s_setprio 1
	s_waitcnt lgkmcnt(0)
	v_mfma_f32_16x16x32_bf16 v[60:63], v[144:147], v[168:171], v[60:63]
	v_mfma_f32_16x16x32_bf16 v[56:59], v[160:163], v[168:171], v[56:59]
	v_mfma_f32_16x16x32_bf16 v[52:55], v[144:147], v[176:179], v[52:55]
	v_mfma_f32_16x16x32_bf16 v[44:47], v[160:163], v[176:179], v[44:47]
	v_mfma_f32_16x16x32_bf16 v[36:39], v[144:147], v[184:187], v[36:39]
	v_mfma_f32_16x16x32_bf16 v[28:31], v[160:163], v[184:187], v[28:31]
	v_mfma_f32_16x16x32_bf16 v[20:23], v[144:147], v[192:195], v[20:23]
	v_mfma_f32_16x16x32_bf16 v[12:15], v[160:163], v[192:195], v[12:15]
	v_mfma_f32_16x16x32_bf16 v[60:63], v[148:151], v[172:175], v[60:63]
	v_mfma_f32_16x16x32_bf16 v[56:59], v[164:167], v[172:175], v[56:59]
	v_mfma_f32_16x16x32_bf16 v[52:55], v[148:151], v[180:183], v[52:55]
	v_mfma_f32_16x16x32_bf16 v[44:47], v[164:167], v[180:183], v[44:47]
	v_mfma_f32_16x16x32_bf16 v[36:39], v[148:151], v[188:191], v[36:39]
	v_mfma_f32_16x16x32_bf16 v[28:31], v[164:167], v[188:191], v[28:31]
	v_mfma_f32_16x16x32_bf16 v[20:23], v[148:151], v[196:199], v[20:23]
	v_mfma_f32_16x16x32_bf16 v[12:15], v[164:167], v[196:199], v[12:15]
	s_setprio 0
	s_barrier
	s_add_u32 s70, s52, 0x40000
	s_addc_u32 s71, s53, 0
	s_add_i32 s69, s61, s1
	v_lshl_add_u64 v[144:145], s[70:71], 0, v[132:133]
	s_mov_b32 m0, s69
	s_nop 0
	global_load_lds_dwordx4 v[144:145], off
	v_lshl_add_u64 v[144:145], s[70:71], 0, v[128:129]
	s_add_i32 m0, s69, 0x2000
	s_nop 0
	global_load_lds_dwordx4 v[144:145], off
	s_waitcnt vmcnt(6)
	s_cmp_gt_u32 s68, 10
	s_cbranch_scc1 .Lds_P1_a_done
	s_cmp_lt_u32 s68, 6
	s_cbranch_scc1 .Lds_P1_a_st
	s_cmp_eq_u32 s68, 6
	s_cbranch_scc1 .Lds_P1_a_pf
	s_cmp_eq_u32 s68, 8
	s_cbranch_scc1 .Lds_P1_a_c8
	v_ffbh_u32_e32 v252, v241
	v_min_u32_e32 v252, 32, v252
	v_lshlrev_b64 v[240:241], v252, v[240:241]
	v_min_u32_e32 v240, 1, v240
	v_or_b32_e32 v241, v241, v240
	v_cvt_f32_u32_e32 v241, v241
	v_sub_u32_e32 v252, -2, v252
	v_ldexp_f32 v241, v241, v252
	v_add_f32_e32 v241, 0x358637bd, v241
	v_rsq_f32_e32 v252, v241
	v_ffbh_u32_e32 v253, v243
	v_min_u32_e32 v253, 32, v253
	v_lshlrev_b64 v[242:243], v253, v[242:243]
	v_min_u32_e32 v242, 1, v242
	v_or_b32_e32 v243, v243, v242
	v_cvt_f32_u32_e32 v243, v243
	v_sub_u32_e32 v253, -2, v253
	v_ldexp_f32 v243, v243, v253
	v_add_f32_e32 v243, 0x358637bd, v243
	v_rsq_f32_e32 v253, v243
	s_branch .Lds_P1_a_done
.Lds_P1_a_c8:
	v_ffbh_u32_e32 v248, v231
	v_min_u32_e32 v248, 32, v248
	v_lshlrev_b64 v[230:231], v248, v[230:231]
	v_min_u32_e32 v230, 1, v230
	v_or_b32_e32 v231, v231, v230
	v_cvt_f32_u32_e32 v231, v231
	v_sub_u32_e32 v248, -2, v248
	v_ldexp_f32 v231, v231, v248
	v_add_f32_e32 v231, 0x358637bd, v231
	v_rsq_f32_e32 v248, v231
	v_ffbh_u32_e32 v249, v233
	v_min_u32_e32 v249, 32, v249
	v_lshlrev_b64 v[232:233], v249, v[232:233]
	v_min_u32_e32 v232, 1, v232
	v_or_b32_e32 v233, v233, v232
	v_cvt_f32_u32_e32 v233, v233
	v_sub_u32_e32 v249, -2, v249
	v_ldexp_f32 v233, v233, v249
	v_add_f32_e32 v233, 0x358637bd, v233
	v_rsq_f32_e32 v249, v233
	s_branch .Lds_P1_a_done
.Lds_P1_a_pf:
	s_lshl_b32 s82, s6, 11
	s_add_u32 s100, s36, s82
	s_addc_u32 s101, s37, 0
	v_lshlrev_b32_e32 v252, 3, v153
	global_load_dwordx2 v[230:231], v252, s[100:101]
	global_load_dwordx2 v[232:233], v252, s[100:101] offset:128
	global_load_dwordx2 v[234:235], v252, s[100:101] offset:256
	global_load_dwordx2 v[236:237], v252, s[100:101] offset:384
	global_load_dwordx2 v[240:241], v252, s[100:101] offset:1024
	global_load_dwordx2 v[242:243], v252, s[100:101] offset:1152
	global_load_dwordx2 v[244:245], v252, s[100:101] offset:1280
	global_load_dwordx2 v[246:247], v252, s[100:101] offset:1408
	s_branch .Lds_P1_a_done
.Lds_P1_a_st:
	s_cmp_eq_u32 s32, 0
	s_cbranch_scc1 .Lds_P1_a_done
	s_cmp_eq_u32 s68, 0
	s_cbranch_scc1 .Lds_P1_a_0
	s_cmp_eq_u32 s68, 2
	s_cbranch_scc1 .Lds_P1_a_1
	s_add_u32 s100, s98, 0x134000
	s_addc_u32 s101, s99, 0
	global_store_dwordx4 v239, v[248:251], s[100:101]
	s_branch .Lds_P1_a_done

.Lds_P1_a_done:
	s_barrier
	s_setprio 1
	v_mfma_f32_16x16x32_bf16 v[48:51], v[200:203], v[168:171], v[48:51]
	v_mfma_f32_16x16x32_bf16 v[40:43], v[210:213], v[168:171], v[40:43]
	v_mfma_f32_16x16x32_bf16 v[32:35], v[200:203], v[176:179], v[32:35]
	v_mfma_f32_16x16x32_bf16 v[24:27], v[210:213], v[176:179], v[24:27]
	v_mfma_f32_16x16x32_bf16 v[16:19], v[200:203], v[184:187], v[16:19]
	v_mfma_f32_16x16x32_bf16 v[8:11], v[210:213], v[184:187], v[8:11]
	v_mfma_f32_16x16x32_bf16 v[4:7], v[200:203], v[192:195], v[4:7]
	v_mfma_f32_16x16x32_bf16 v[0:3], v[210:213], v[192:195], v[0:3]
	v_mfma_f32_16x16x32_bf16 v[48:51], v[206:209], v[172:175], v[48:51]
	v_mfma_f32_16x16x32_bf16 v[40:43], v[214:217], v[172:175], v[40:43]
	v_mfma_f32_16x16x32_bf16 v[32:35], v[206:209], v[180:183], v[32:35]
	v_mfma_f32_16x16x32_bf16 v[24:27], v[214:217], v[180:183], v[24:27]
	v_mfma_f32_16x16x32_bf16 v[16:19], v[206:209], v[188:191], v[16:19]
	v_mfma_f32_16x16x32_bf16 v[8:11], v[214:217], v[188:191], v[8:11]
	v_mfma_f32_16x16x32_bf16 v[4:7], v[206:209], v[196:199], v[4:7]
	v_mfma_f32_16x16x32_bf16 v[0:3], v[214:217], v[196:199], v[0:3]
	s_setprio 0
	s_add_i32 s69, 0, 0x18000
	v_add_u32_e32 v164, s69, v154
	s_barrier
	ds_read_b128 v[144:147], v164
	ds_read_b128 v[148:151], v164 offset:1024
	ds_read_b128 v[160:163], v164 offset:2048
	ds_read_b128 v[164:167], v164 offset:3072
	s_add_u32 s54, s54, 0x40000
	s_addc_u32 s55, s55, 0
	s_mov_b32 m0, s35
	v_lshl_add_u64 v[200:201], s[54:55], 0, v[134:135]
	ds_read_b128 v[168:171], v157 offset:32768
	ds_read_b128 v[172:175], v157 offset:33792
	ds_read_b128 v[176:179], v157 offset:34816
	ds_read_b128 v[180:183], v157 offset:35840
	ds_read_b128 v[184:187], v157 offset:36864
	ds_read_b128 v[188:191], v157 offset:37888
	ds_read_b128 v[192:195], v157 offset:38912
	ds_read_b128 v[196:199], v157 offset:39936
	global_load_lds_dwordx4 v[200:201], off
	v_lshl_add_u64 v[200:201], s[54:55], 0, v[130:131]
	s_mov_b32 m0, s46
	s_nop 0
	global_load_lds_dwordx4 v[200:201], off
	s_waitcnt lgkmcnt(8)
	s_barrier
	s_waitcnt lgkmcnt(0)
	s_setprio 1
	s_waitcnt lgkmcnt(0)
	v_mfma_f32_16x16x32_bf16 v[124:127], v[144:147], v[168:171], v[124:127]
	v_mfma_f32_16x16x32_bf16 v[120:123], v[160:163], v[168:171], v[120:123]
	v_mfma_f32_16x16x32_bf16 v[116:119], v[144:147], v[176:179], v[116:119]
	v_mfma_f32_16x16x32_bf16 v[108:111], v[160:163], v[176:179], v[108:111]
	v_mfma_f32_16x16x32_bf16 v[100:103], v[144:147], v[184:187], v[100:103]
	v_mfma_f32_16x16x32_bf16 v[92:95], v[160:163], v[184:187], v[92:95]
	v_mfma_f32_16x16x32_bf16 v[84:87], v[144:147], v[192:195], v[84:87]
	v_mfma_f32_16x16x32_bf16 v[76:79], v[160:163], v[192:195], v[76:79]
	v_mfma_f32_16x16x32_bf16 v[124:127], v[148:151], v[172:175], v[124:127]
	v_mfma_f32_16x16x32_bf16 v[120:123], v[164:167], v[172:175], v[120:123]
	v_mfma_f32_16x16x32_bf16 v[116:119], v[148:151], v[180:183], v[116:119]
	v_mfma_f32_16x16x32_bf16 v[108:111], v[164:167], v[180:183], v[108:111]
	v_mfma_f32_16x16x32_bf16 v[100:103], v[148:151], v[188:191], v[100:103]
	v_mfma_f32_16x16x32_bf16 v[92:95], v[164:167], v[188:191], v[92:95]
	v_mfma_f32_16x16x32_bf16 v[84:87], v[148:151], v[196:199], v[84:87]
	v_mfma_f32_16x16x32_bf16 v[76:79], v[164:167], v[196:199], v[76:79]
	s_setprio 0
	s_barrier
	s_add_i32 s54, 0, 0x1c000
	s_add_i32 s55, s69, s1
	v_add_u32_e32 v205, s54, v154
	v_lshl_add_u64 v[218:219], v[218:219], 0, s[40:41]
	s_mov_b32 m0, s55
	ds_read_b128 v[200:203], v205
	ds_read_b128 v[206:209], v205 offset:1024
	ds_read_b128 v[210:213], v205 offset:2048
	ds_read_b128 v[214:217], v205 offset:3072
	global_load_lds_dwordx4 v[218:219], off
	v_lshl_add_u64 v[218:219], v[220:221], 0, s[40:41]
	s_add_i32 m0, s55, 0x2000
	s_nop 0
	global_load_lds_dwordx4 v[218:219], off
	s_barrier
	s_waitcnt lgkmcnt(0)
	s_setprio 1
	s_waitcnt lgkmcnt(0)
	v_mfma_f32_16x16x32_bf16 v[112:115], v[200:203], v[168:171], v[112:115]
	v_mfma_f32_16x16x32_bf16 v[104:107], v[210:213], v[168:171], v[104:107]
	v_mfma_f32_16x16x32_bf16 v[96:99], v[200:203], v[176:179], v[96:99]
	v_mfma_f32_16x16x32_bf16 v[88:91], v[210:213], v[176:179], v[88:91]
	v_mfma_f32_16x16x32_bf16 v[80:83], v[200:203], v[184:187], v[80:83]
	v_mfma_f32_16x16x32_bf16 v[72:75], v[210:213], v[184:187], v[72:75]
	v_mfma_f32_16x16x32_bf16 v[68:71], v[200:203], v[192:195], v[68:71]
	v_mfma_f32_16x16x32_bf16 v[64:67], v[210:213], v[192:195], v[64:67]
	v_mfma_f32_16x16x32_bf16 v[112:115], v[206:209], v[172:175], v[112:115]
	v_mfma_f32_16x16x32_bf16 v[104:107], v[214:217], v[172:175], v[104:107]
	v_mfma_f32_16x16x32_bf16 v[96:99], v[206:209], v[180:183], v[96:99]
	v_mfma_f32_16x16x32_bf16 v[88:91], v[214:217], v[180:183], v[88:91]
	v_mfma_f32_16x16x32_bf16 v[80:83], v[206:209], v[188:191], v[80:83]
	v_mfma_f32_16x16x32_bf16 v[72:75], v[214:217], v[188:191], v[72:75]
	v_mfma_f32_16x16x32_bf16 v[68:71], v[206:209], v[196:199], v[68:71]
	v_mfma_f32_16x16x32_bf16 v[64:67], v[214:217], v[196:199], v[64:67]
	s_setprio 0
	s_mov_b32 m0, s56
	v_lshl_add_u64 v[218:219], v[222:223], 0, s[40:41]
	s_barrier
	ds_read_b128 v[168:171], v157 offset:49152
	ds_read_b128 v[172:175], v157 offset:50176
	ds_read_b128 v[176:179], v157 offset:51200
	ds_read_b128 v[180:183], v157 offset:52224
	ds_read_b128 v[184:187], v157 offset:53248
	ds_read_b128 v[188:191], v157 offset:54272
	ds_read_b128 v[192:195], v157 offset:55296
	ds_read_b128 v[196:199], v157 offset:56320
	global_load_lds_dwordx4 v[218:219], off
	v_lshl_add_u64 v[218:219], v[224:225], 0, s[40:41]
	s_mov_b32 m0, s57
	s_nop 0
	global_load_lds_dwordx4 v[218:219], off
	s_barrier
	s_waitcnt lgkmcnt(0)
	s_setprio 1
	s_waitcnt lgkmcnt(0)
	v_mfma_f32_16x16x32_bf16 v[60:63], v[144:147], v[168:171], v[60:63]
	v_mfma_f32_16x16x32_bf16 v[56:59], v[160:163], v[168:171], v[56:59]
	v_mfma_f32_16x16x32_bf16 v[52:55], v[144:147], v[176:179], v[52:55]
	v_mfma_f32_16x16x32_bf16 v[44:47], v[160:163], v[176:179], v[44:47]
	v_mfma_f32_16x16x32_bf16 v[36:39], v[144:147], v[184:187], v[36:39]
	v_mfma_f32_16x16x32_bf16 v[28:31], v[160:163], v[184:187], v[28:31]
	v_mfma_f32_16x16x32_bf16 v[20:23], v[144:147], v[192:195], v[20:23]
	v_mfma_f32_16x16x32_bf16 v[12:15], v[160:163], v[192:195], v[12:15]
	v_mfma_f32_16x16x32_bf16 v[60:63], v[148:151], v[172:175], v[60:63]
	v_mfma_f32_16x16x32_bf16 v[56:59], v[164:167], v[172:175], v[56:59]
	v_mfma_f32_16x16x32_bf16 v[52:55], v[148:151], v[180:183], v[52:55]
	v_mfma_f32_16x16x32_bf16 v[44:47], v[164:167], v[180:183], v[44:47]
	v_mfma_f32_16x16x32_bf16 v[36:39], v[148:151], v[188:191], v[36:39]
	v_mfma_f32_16x16x32_bf16 v[28:31], v[164:167], v[188:191], v[28:31]
	v_mfma_f32_16x16x32_bf16 v[20:23], v[148:151], v[196:199], v[20:23]
	v_mfma_f32_16x16x32_bf16 v[12:15], v[164:167], v[196:199], v[12:15]
	s_setprio 0
	s_barrier
	s_add_u32 s52, s52, 0x40080
	s_addc_u32 s53, s53, 0
	s_add_i32 s54, s54, s1
	v_lshl_add_u64 v[144:145], s[52:53], 0, v[132:133]
	s_mov_b32 m0, s54
	s_nop 0
	global_load_lds_dwordx4 v[144:145], off
	v_lshl_add_u64 v[144:145], s[52:53], 0, v[128:129]
	s_add_i32 m0, s54, 0x2000
	s_nop 0
	global_load_lds_dwordx4 v[144:145], off
	s_waitcnt vmcnt(6)
	s_cmp_gt_u32 s68, 10
	s_cbranch_scc1 .Lds_P1_b_done
	s_cmp_lt_u32 s68, 6
	s_cbranch_scc1 .Lds_P1_b_st
	s_cmp_eq_u32 s68, 6
	s_cbranch_scc1 .Lds_P1_b_done
	s_cmp_eq_u32 s68, 8
	s_cbranch_scc1 .Lds_P1_b_c8
	v_ffbh_u32_e32 v254, v245
	v_min_u32_e32 v254, 32, v254
	v_lshlrev_b64 v[244:245], v254, v[244:245]
	v_min_u32_e32 v244, 1, v244
	v_or_b32_e32 v245, v245, v244
	v_cvt_f32_u32_e32 v245, v245
	v_sub_u32_e32 v254, -2, v254
	v_ldexp_f32 v245, v245, v254
	v_add_f32_e32 v245, 0x358637bd, v245
	v_rsq_f32_e32 v254, v245
	v_ffbh_u32_e32 v255, v247
	v_min_u32_e32 v255, 32, v255
	v_lshlrev_b64 v[246:247], v255, v[246:247]
	v_min_u32_e32 v246, 1, v246
	v_or_b32_e32 v247, v247, v246
	v_cvt_f32_u32_e32 v247, v247
	v_sub_u32_e32 v255, -2, v255
	v_ldexp_f32 v247, v247, v255
	v_add_f32_e32 v247, 0x358637bd, v247
	v_rsq_f32_e32 v255, v247
	s_branch .Lds_P1_b_done
.Lds_P1_b_c8:
	v_ffbh_u32_e32 v250, v235
	v_min_u32_e32 v250, 32, v250
	v_lshlrev_b64 v[234:235], v250, v[234:235]
	v_min_u32_e32 v234, 1, v234
	v_or_b32_e32 v235, v235, v234
	v_cvt_f32_u32_e32 v235, v235
	v_sub_u32_e32 v250, -2, v250
	v_ldexp_f32 v235, v235, v250
	v_add_f32_e32 v235, 0x358637bd, v235
	v_rsq_f32_e32 v250, v235
	v_ffbh_u32_e32 v251, v237
	v_min_u32_e32 v251, 32, v251
	v_lshlrev_b64 v[236:237], v251, v[236:237]
	v_min_u32_e32 v236, 1, v236
	v_or_b32_e32 v237, v237, v236
	v_cvt_f32_u32_e32 v237, v237
	v_sub_u32_e32 v251, -2, v251
	v_ldexp_f32 v237, v237, v251
	v_add_f32_e32 v237, 0x358637bd, v237
	v_rsq_f32_e32 v251, v237
	s_branch .Lds_P1_b_done
.Lds_P1_b_st:
	s_cmp_eq_u32 s32, 0
	s_cbranch_scc1 .Lds_P1_b_done
	s_cmp_eq_u32 s68, 0
	s_cbranch_scc1 .Lds_P1_b_0
	s_cmp_eq_u32 s68, 2
	s_cbranch_scc1 .Lds_P1_b_1
	s_add_u32 s100, s98, 0x134000
	s_addc_u32 s101, s99, 0
	global_store_dwordx4 v239, v[252:255], s[100:101] offset:256
	s_branch .Lds_P1_b_done

.Lepi_P1_start:
	s_mul_i32 s82, s6, 0x1c0000
	s_lshl_b32 s84, s64, 9
	s_add_u32 s82, s82, s84
	s_add_u32 s84, s38, s82
	s_addc_u32 s85, s39, 0
	v_pk_mul_f32 v[124:125], v[124:125], v[248:249] op_sel_hi:[1,0]
	v_pk_mul_f32 v[126:127], v[126:127], v[248:249] op_sel_hi:[1,0]
	v_pk_mul_f32 v[120:121], v[120:121], v[248:249] op_sel_hi:[1,0]
	v_pk_mul_f32 v[122:123], v[122:123], v[248:249] op_sel_hi:[1,0]
	v_cvt_pk_bf16_f32 v124, v124, v125
	v_cvt_pk_bf16_f32 v125, v126, v127
	v_cvt_pk_bf16_f32 v126, v120, v121
	v_cvt_pk_bf16_f32 v127, v122, v123
	global_store_dwordx4 v239, v[124:127], s[84:85]
	v_pk_mul_f32 v[112:113], v[112:113], v[248:249] op_sel_hi:[1,0]
	v_pk_mul_f32 v[114:115], v[114:115], v[248:249] op_sel_hi:[1,0]
	v_pk_mul_f32 v[104:105], v[104:105], v[248:249] op_sel_hi:[1,0]
	v_pk_mul_f32 v[106:107], v[106:107], v[248:249] op_sel_hi:[1,0]
	v_cvt_pk_bf16_f32 v112, v112, v113
	v_cvt_pk_bf16_f32 v113, v114, v115
	v_cvt_pk_bf16_f32 v114, v104, v105
	v_cvt_pk_bf16_f32 v115, v106, v107
	global_store_dwordx4 v239, v[112:115], s[84:85] offset:256
	v_pk_mul_f32 v[116:117], v[116:117], v[248:249] op_sel:[0,1] op_sel_hi:[1,1]
	v_pk_mul_f32 v[118:119], v[118:119], v[248:249] op_sel:[0,1] op_sel_hi:[1,1]
	v_pk_mul_f32 v[108:109], v[108:109], v[248:249] op_sel:[0,1] op_sel_hi:[1,1]
	v_pk_mul_f32 v[110:111], v[110:111], v[248:249] op_sel:[0,1] op_sel_hi:[1,1]
	v_cvt_pk_bf16_f32 v116, v116, v117
	v_cvt_pk_bf16_f32 v117, v118, v119
	v_cvt_pk_bf16_f32 v118, v108, v109
	v_cvt_pk_bf16_f32 v119, v110, v111
	s_add_u32 s100, s84, 0x1c000
	s_addc_u32 s101, s85, 0
	global_store_dwordx4 v239, v[116:119], s[100:101]
	v_pk_mul_f32 v[96:97], v[96:97], v[248:249] op_sel:[0,1] op_sel_hi:[1,1]
	v_pk_mul_f32 v[98:99], v[98:99], v[248:249] op_sel:[0,1] op_sel_hi:[1,1]
	v_pk_mul_f32 v[88:89], v[88:89], v[248:249] op_sel:[0,1] op_sel_hi:[1,1]
	v_pk_mul_f32 v[90:91], v[90:91], v[248:249] op_sel:[0,1] op_sel_hi:[1,1]
	v_cvt_pk_bf16_f32 v96, v96, v97
	v_cvt_pk_bf16_f32 v97, v98, v99
	v_cvt_pk_bf16_f32 v98, v88, v89
	v_cvt_pk_bf16_f32 v99, v90, v91
	s_add_u32 s100, s84, 0x1c000
	s_addc_u32 s101, s85, 0
	global_store_dwordx4 v239, v[96:99], s[100:101] offset:256
	v_pk_mul_f32 v[100:101], v[100:101], v[250:251] op_sel_hi:[1,0]
	v_pk_mul_f32 v[102:103], v[102:103], v[250:251] op_sel_hi:[1,0]
	v_pk_mul_f32 v[92:93], v[92:93], v[250:251] op_sel_hi:[1,0]
	v_pk_mul_f32 v[94:95], v[94:95], v[250:251] op_sel_hi:[1,0]
	v_cvt_pk_bf16_f32 v100, v100, v101
	v_cvt_pk_bf16_f32 v101, v102, v103
	v_cvt_pk_bf16_f32 v102, v92, v93
	v_cvt_pk_bf16_f32 v103, v94, v95
	s_add_u32 s100, s84, 0x38000
	s_addc_u32 s101, s85, 0
	global_store_dwordx4 v239, v[100:103], s[100:101]
	v_pk_mul_f32 v[80:81], v[80:81], v[250:251] op_sel_hi:[1,0]
	v_pk_mul_f32 v[82:83], v[82:83], v[250:251] op_sel_hi:[1,0]
	v_pk_mul_f32 v[72:73], v[72:73], v[250:251] op_sel_hi:[1,0]
	v_pk_mul_f32 v[74:75], v[74:75], v[250:251] op_sel_hi:[1,0]
	v_cvt_pk_bf16_f32 v80, v80, v81
	v_cvt_pk_bf16_f32 v81, v82, v83
	v_cvt_pk_bf16_f32 v82, v72, v73
	v_cvt_pk_bf16_f32 v83, v74, v75
	s_add_u32 s100, s84, 0x38000
	s_addc_u32 s101, s85, 0
	global_store_dwordx4 v239, v[80:83], s[100:101] offset:256
	v_pk_mul_f32 v[84:85], v[84:85], v[250:251] op_sel:[0,1] op_sel_hi:[1,1]
	v_pk_mul_f32 v[86:87], v[86:87], v[250:251] op_sel:[0,1] op_sel_hi:[1,1]
	v_pk_mul_f32 v[76:77], v[76:77], v[250:251] op_sel:[0,1] op_sel_hi:[1,1]
	v_pk_mul_f32 v[78:79], v[78:79], v[250:251] op_sel:[0,1] op_sel_hi:[1,1]
	v_cvt_pk_bf16_f32 v84, v84, v85
	v_cvt_pk_bf16_f32 v85, v86, v87
	v_cvt_pk_bf16_f32 v86, v76, v77
	v_cvt_pk_bf16_f32 v87, v78, v79
	s_add_u32 s100, s84, 0x54000
	s_addc_u32 s101, s85, 0
	global_store_dwordx4 v239, v[84:87], s[100:101]
	v_pk_mul_f32 v[68:69], v[68:69], v[250:251] op_sel:[0,1] op_sel_hi:[1,1]
	v_pk_mul_f32 v[70:71], v[70:71], v[250:251] op_sel:[0,1] op_sel_hi:[1,1]
	v_pk_mul_f32 v[64:65], v[64:65], v[250:251] op_sel:[0,1] op_sel_hi:[1,1]
	v_pk_mul_f32 v[66:67], v[66:67], v[250:251] op_sel:[0,1] op_sel_hi:[1,1]
	v_cvt_pk_bf16_f32 v68, v68, v69
	v_cvt_pk_bf16_f32 v69, v70, v71
	v_cvt_pk_bf16_f32 v70, v64, v65
	v_cvt_pk_bf16_f32 v71, v66, v67
	s_add_u32 s100, s84, 0x54000
	s_addc_u32 s101, s85, 0
	global_store_dwordx4 v239, v[68:71], s[100:101] offset:256
	v_pk_mul_f32 v[60:61], v[60:61], v[252:253] op_sel_hi:[1,0]
	v_pk_mul_f32 v[62:63], v[62:63], v[252:253] op_sel_hi:[1,0]
	v_pk_mul_f32 v[56:57], v[56:57], v[252:253] op_sel_hi:[1,0]
	v_pk_mul_f32 v[58:59], v[58:59], v[252:253] op_sel_hi:[1,0]
	v_cvt_pk_bf16_f32 v60, v60, v61
	v_cvt_pk_bf16_f32 v61, v62, v63
	v_cvt_pk_bf16_f32 v62, v56, v57
	v_cvt_pk_bf16_f32 v63, v58, v59
	s_add_u32 s100, s84, 0xe0000
	s_addc_u32 s101, s85, 0
	global_store_dwordx4 v239, v[60:63], s[100:101]
	v_pk_mul_f32 v[48:49], v[48:49], v[252:253] op_sel_hi:[1,0]
	v_pk_mul_f32 v[50:51], v[50:51], v[252:253] op_sel_hi:[1,0]
	v_pk_mul_f32 v[40:41], v[40:41], v[252:253] op_sel_hi:[1,0]
	v_pk_mul_f32 v[42:43], v[42:43], v[252:253] op_sel_hi:[1,0]
	v_cvt_pk_bf16_f32 v48, v48, v49
	v_cvt_pk_bf16_f32 v49, v50, v51
	v_cvt_pk_bf16_f32 v50, v40, v41
	v_cvt_pk_bf16_f32 v51, v42, v43
	s_add_u32 s100, s84, 0xe0000
	s_addc_u32 s101, s85, 0
	global_store_dwordx4 v239, v[48:51], s[100:101] offset:256
	v_pk_mul_f32 v[52:53], v[52:53], v[252:253] op_sel:[0,1] op_sel_hi:[1,1]
	v_pk_mul_f32 v[54:55], v[54:55], v[252:253] op_sel:[0,1] op_sel_hi:[1,1]
	v_pk_mul_f32 v[44:45], v[44:45], v[252:253] op_sel:[0,1] op_sel_hi:[1,1]
	v_pk_mul_f32 v[46:47], v[46:47], v[252:253] op_sel:[0,1] op_sel_hi:[1,1]
	v_cvt_pk_bf16_f32 v230, v52, v53
	v_cvt_pk_bf16_f32 v231, v54, v55
	v_cvt_pk_bf16_f32 v232, v44, v45
	v_cvt_pk_bf16_f32 v233, v46, v47
	v_pk_mul_f32 v[32:33], v[32:33], v[252:253] op_sel:[0,1] op_sel_hi:[1,1]
	v_pk_mul_f32 v[34:35], v[34:35], v[252:253] op_sel:[0,1] op_sel_hi:[1,1]
	v_pk_mul_f32 v[24:25], v[24:25], v[252:253] op_sel:[0,1] op_sel_hi:[1,1]
	v_pk_mul_f32 v[26:27], v[26:27], v[252:253] op_sel:[0,1] op_sel_hi:[1,1]
	v_cvt_pk_bf16_f32 v234, v32, v33
	v_cvt_pk_bf16_f32 v235, v34, v35
	v_cvt_pk_bf16_f32 v236, v24, v25
	v_cvt_pk_bf16_f32 v237, v26, v27
	v_pk_mul_f32 v[36:37], v[36:37], v[254:255] op_sel_hi:[1,0]
	v_pk_mul_f32 v[38:39], v[38:39], v[254:255] op_sel_hi:[1,0]
	v_pk_mul_f32 v[28:29], v[28:29], v[254:255] op_sel_hi:[1,0]
	v_pk_mul_f32 v[30:31], v[30:31], v[254:255] op_sel_hi:[1,0]
	v_cvt_pk_bf16_f32 v240, v36, v37
	v_cvt_pk_bf16_f32 v241, v38, v39
	v_cvt_pk_bf16_f32 v242, v28, v29
	v_cvt_pk_bf16_f32 v243, v30, v31
	v_pk_mul_f32 v[16:17], v[16:17], v[254:255] op_sel_hi:[1,0]
	v_pk_mul_f32 v[18:19], v[18:19], v[254:255] op_sel_hi:[1,0]
	v_pk_mul_f32 v[8:9], v[8:9], v[254:255] op_sel_hi:[1,0]
	v_pk_mul_f32 v[10:11], v[10:11], v[254:255] op_sel_hi:[1,0]
	v_cvt_pk_bf16_f32 v244, v16, v17
	v_cvt_pk_bf16_f32 v245, v18, v19
	v_cvt_pk_bf16_f32 v246, v8, v9
	v_cvt_pk_bf16_f32 v247, v10, v11
	v_pk_mul_f32 v[20:21], v[20:21], v[254:255] op_sel:[0,1] op_sel_hi:[1,1]
	v_pk_mul_f32 v[22:23], v[22:23], v[254:255] op_sel:[0,1] op_sel_hi:[1,1]
	v_pk_mul_f32 v[12:13], v[12:13], v[254:255] op_sel:[0,1] op_sel_hi:[1,1]
	v_pk_mul_f32 v[14:15], v[14:15], v[254:255] op_sel:[0,1] op_sel_hi:[1,1]
	v_cvt_pk_bf16_f32 v248, v20, v21
	v_cvt_pk_bf16_f32 v249, v22, v23
	v_cvt_pk_bf16_f32 v250, v12, v13
	v_cvt_pk_bf16_f32 v251, v14, v15
	v_pk_mul_f32 v[4:5], v[4:5], v[254:255] op_sel:[0,1] op_sel_hi:[1,1]
	v_pk_mul_f32 v[6:7], v[6:7], v[254:255] op_sel:[0,1] op_sel_hi:[1,1]
	v_pk_mul_f32 v[0:1], v[0:1], v[254:255] op_sel:[0,1] op_sel_hi:[1,1]
	v_pk_mul_f32 v[2:3], v[2:3], v[254:255] op_sel:[0,1] op_sel_hi:[1,1]
	v_cvt_pk_bf16_f32 v252, v4, v5
	v_cvt_pk_bf16_f32 v253, v6, v7
	v_cvt_pk_bf16_f32 v254, v0, v1
	v_cvt_pk_bf16_f32 v255, v2, v3
	s_mov_b64 s[52:53], s[50:51]
	s_and_b64 vcc, exec, s[4:5]
	s_mov_b32 s64, s42
	s_mov_b32 s6, s44
	s_mov_b64 s[8:9], s[48:49]
	s_mov_b64 s[98:99], s[84:85]
	s_mov_b32 s32, 1
	s_cbranch_vccz .LBB0_156
	s_add_u32 s100, s84, 0xfc000
	s_addc_u32 s101, s85, 0
	global_store_dwordx4 v239, v[230:233], s[100:101]
	s_add_u32 s100, s84, 0xfc000
	s_addc_u32 s101, s85, 0
	global_store_dwordx4 v239, v[234:237], s[100:101] offset:256
	s_add_u32 s100, s84, 0x118000
	s_addc_u32 s101, s85, 0
	global_store_dwordx4 v239, v[240:243], s[100:101]
	s_add_u32 s100, s84, 0x118000
	s_addc_u32 s101, s85, 0
	global_store_dwordx4 v239, v[244:247], s[100:101] offset:256
	s_add_u32 s100, s84, 0x134000
	s_addc_u32 s101, s85, 0
	global_store_dwordx4 v239, v[248:251], s[100:101]
	s_add_u32 s100, s84, 0x134000
	s_addc_u32 s101, s85, 0
	global_store_dwordx4 v239, v[252:255], s[100:101] offset:256
	s_waitcnt vmcnt(0)
	s_cmpk_gt_u32 s0, 0xff
	s_cbranch_scc1 .LBB0_163
	s_barrier

.LBB0_783:
	s_or_b64 exec, exec, s[6:7]
	s_add_i32 s2, s50, s22
	s_lshl_b32 s6, s8, 2
	s_add_u32 s6, s38, s6
	s_addc_u32 s7, s39, 0
	s_waitcnt lgkmcnt(0)
	v_lshl_add_u64 v[76:77], v[74:75], 2, s[6:7]
	s_barrier
	global_load_dwordx4 v[248:251], v[76:77], off
	v_ashrrev_i32_e32 v95, 31, v94
	v_lshl_add_u32 v1, v144, 2, s96
	v_lshlrev_b64 v[96:97], 11, v[2:3]
	v_lshl_add_u32 v2, v73, 2, s96
	s_waitcnt vmcnt(4)
	v_lshlrev_b32_e32 v98, 16, v80
	v_and_b32_e32 v99, 0xffff0000, v80
	v_lshlrev_b32_e32 v100, 16, v81
	v_and_b32_e32 v101, 0xffff0000, v81
	ds_read2st64_b32 v[102:103], v1 offset1:1
	ds_read2st64_b32 v[104:105], v1 offset0:2 offset1:3
	ds_read2st64_b32 v[106:107], v1 offset0:4 offset1:5
	ds_read2st64_b32 v[108:109], v1 offset0:6 offset1:7
	v_lshlrev_b64 v[80:81], 1, v[94:95]
	ds_read2st64_b32 v[94:95], v2 offset1:1
	ds_read2st64_b32 v[110:111], v2 offset0:2 offset1:3
	ds_read2st64_b32 v[112:113], v2 offset0:4 offset1:5
	ds_read2st64_b32 v[114:115], v2 offset0:6 offset1:7
	s_waitcnt lgkmcnt(7)
	v_mov_b32_e32 v117, v102
	s_waitcnt lgkmcnt(3)
	v_mov_b32_e32 v116, v94
	v_mov_b32_e32 v102, v95
	v_pk_add_f32 v[116:117], v[116:117], 0 op_sel_hi:[1,0]
	s_waitcnt lgkmcnt(2)
	v_mov_b32_e32 v94, v110
	v_mov_b32_e32 v95, v104
	v_pk_add_f32 v[102:103], v[116:117], v[102:103]
	v_mov_b32_e32 v104, v111
	v_pk_add_f32 v[94:95], v[102:103], v[94:95]
	v_mul_f32_e32 v1, 0xbfb8aa3b, v98
	s_waitcnt lgkmcnt(1)
	v_mov_b32_e32 v110, v112
	v_mov_b32_e32 v111, v106
	v_pk_add_f32 v[94:95], v[94:95], v[104:105]
	v_exp_f32_e32 v1, v1
	v_mov_b32_e32 v106, v113
	v_pk_add_f32 v[94:95], v[94:95], v[110:111]
	s_waitcnt lgkmcnt(0)
	v_mov_b32_e32 v112, v114
	v_mov_b32_e32 v113, v108
	v_pk_add_f32 v[94:95], v[94:95], v[106:107]
	v_mov_b32_e32 v108, v115
	v_pk_add_f32 v[94:95], v[94:95], v[112:113]
	v_mov_b64_e32 v[86:87], s[82:83]
	v_pk_add_f32 v[94:95], v[94:95], v[108:109]
	v_mul_f32_e32 v61, 0xbfb8aa3b, v99
	v_mul_f32_e32 v73, 0xbfb8aa3b, v100
	v_mul_f32_e32 v83, 0xbfb8aa3b, v101
	v_add_f32_e32 v1, 1.0, v1
	v_pk_fma_f32 v[94:95], v[94:95], s[80:81], v[86:87] op_sel_hi:[1,0,0]
	v_exp_f32_e32 v2, v61
	v_exp_f32_e32 v61, v73
	v_exp_f32_e32 v73, v83
	v_rcp_f32_e32 v114, v1
	v_mul_f32_e32 v1, 0x4b800000, v95
	v_cmp_gt_f32_e32 vcc, s42, v95
	v_add_f32_e32 v2, 1.0, v2
	v_add_f32_e32 v61, 1.0, v61
	v_cndmask_b32_e32 v1, v95, v1, vcc
	v_rsq_f32_e32 v1, v1
	v_add_f32_e32 v73, 1.0, v73
	v_rcp_f32_e32 v115, v2
	v_rcp_f32_e32 v118, v61
	v_rcp_f32_e32 v119, v73
	v_mul_f32_e32 v2, 0x45800000, v1
	v_cndmask_b32_e32 v2, v1, v2, vcc
	v_lshl_add_u64 v[96:97], s[16:17], 0, v[96:97]
	v_pk_mul_f32 v[68:69], v[68:69], v[2:3] op_sel_hi:[1,0]
	v_pk_mul_f32 v[70:71], v[70:71], v[2:3] op_sel_hi:[1,0]
	v_lshl_add_u64 v[96:97], v[96:97], 0, s[62:63]
	v_pk_mul_f32 v[98:99], v[114:115], v[98:99]
	v_pk_mul_f32 v[100:101], v[118:119], v[100:101]
	v_lshlrev_b32_e32 v74, 1, v150
	v_mov_b32_e32 v75, v0
	v_lshl_add_u64 v[96:97], v[96:97], 0, v[80:81]
	v_lshl_add_u64 v[96:97], v[96:97], 0, v[74:75]
	v_cmp_gt_f32_e32 vcc, s42, v94
	v_mov_b32_e32 v83, v3
	v_lshlrev_b64 v[82:83], 11, v[82:83]
	v_lshl_add_u64 v[82:83], s[16:17], 0, v[82:83]
	v_lshl_add_u64 v[82:83], v[82:83], 0, s[62:63]
	v_lshl_add_u64 v[82:83], v[82:83], 0, v[80:81]
	v_lshl_add_u64 v[82:83], v[82:83], 0, v[74:75]
	s_add_i32 s73, s73, s88
	s_add_i32 s61, s61, s91
	s_cmpk_gt_i32 s2, 0x7ff
	s_cselect_b64 s[6:7], -1, 0
	s_waitcnt vmcnt(0)
	v_pk_mul_f32 v[68:69], v[248:249], v[68:69]
	v_pk_mul_f32 v[70:71], v[250:251], v[70:71]
	v_pk_mul_f32 v[68:69], v[98:99], v[68:69]
	v_pk_mul_f32 v[70:71], v[100:101], v[70:71]
	v_cvt_pk_bf16_f32 v68, v68, v69
	v_cvt_pk_bf16_f32 v69, v70, v71
	global_store_dwordx2 v[96:97], v[68:69], off offset:1024
	s_nop 0
	v_lshlrev_b32_e32 v90, 16, v84
	v_mul_f32_e32 v1, 0xbfb8aa3b, v90
	v_exp_f32_e32 v1, v1
	v_and_b32_e32 v91, 0xffff0000, v84
	v_lshlrev_b32_e32 v84, 16, v85
	v_and_b32_e32 v85, 0xffff0000, v85
	v_mul_f32_e32 v2, 0xbfb8aa3b, v91
	v_mul_f32_e32 v61, 0xbfb8aa3b, v84
	v_mul_f32_e32 v73, 0xbfb8aa3b, v85
	v_add_f32_e32 v1, 1.0, v1
	v_exp_f32_e32 v2, v2
	v_exp_f32_e32 v61, v61
	v_exp_f32_e32 v73, v73
	v_rcp_f32_e32 v92, v1
	v_mul_f32_e32 v1, 0x4b800000, v94
	v_cndmask_b32_e32 v1, v94, v1, vcc
	v_rsq_f32_e32 v1, v1
	v_add_f32_e32 v2, 1.0, v2
	v_add_f32_e32 v61, 1.0, v61
	v_add_f32_e32 v73, 1.0, v73
	v_rcp_f32_e32 v93, v2
	v_rcp_f32_e32 v96, v61
	v_rcp_f32_e32 v97, v73
	v_mul_f32_e32 v2, 0x45800000, v1
	v_cndmask_b32_e32 v2, v1, v2, vcc
	v_pk_mul_f32 v[64:65], v[64:65], v[2:3] op_sel_hi:[1,0]
	v_pk_mul_f32 v[66:67], v[66:67], v[2:3] op_sel_hi:[1,0]
	v_pk_mul_f32 v[90:91], v[92:93], v[90:91]
	v_pk_mul_f32 v[84:85], v[96:97], v[84:85]
	v_lshl_add_u32 v1, v89, 2, s96
	v_lshl_add_u32 v2, v88, 2, s96
	v_mov_b32_e32 v73, v3
	v_lshlrev_b64 v[72:73], 11, v[72:73]
	v_lshl_add_u64 v[72:73], s[16:17], 0, v[72:73]
	v_lshl_add_u64 v[72:73], v[72:73], 0, s[62:63]
	v_lshl_add_u64 v[72:73], v[72:73], 0, v[80:81]
	v_lshl_add_u64 v[72:73], v[72:73], 0, v[74:75]
	s_nop 0
	v_pk_mul_f32 v[64:65], v[248:249], v[64:65]
	v_pk_mul_f32 v[66:67], v[250:251], v[66:67]
	v_pk_mul_f32 v[64:65], v[90:91], v[64:65]
	v_pk_mul_f32 v[66:67], v[84:85], v[66:67]
	v_cvt_pk_bf16_f32 v64, v64, v65
	v_cvt_pk_bf16_f32 v65, v66, v67
	global_store_dwordx2 v[82:83], v[64:65], off offset:1024
	s_nop 0
	v_and_b32_e32 v69, 0xffff0000, v78
	v_lshlrev_b32_e32 v70, 16, v79
	v_and_b32_e32 v71, 0xffff0000, v79
	v_mul_f32_e32 v61, 0xbfb8aa3b, v69
	v_mul_f32_e32 v98, 0xbfb8aa3b, v70
	v_mul_f32_e32 v99, 0xbfb8aa3b, v71
	v_lshlrev_b32_e32 v68, 16, v78
	ds_read2st64_b32 v[78:79], v1 offset1:1
	ds_read2st64_b32 v[82:83], v1 offset0:2 offset1:3
	ds_read2st64_b32 v[84:85], v1 offset0:4 offset1:5
	ds_read2st64_b32 v[88:89], v1 offset0:6 offset1:7
	ds_read2st64_b32 v[90:91], v2 offset1:1
	ds_read2st64_b32 v[92:93], v2 offset0:2 offset1:3
	ds_read2st64_b32 v[94:95], v2 offset0:4 offset1:5
	ds_read2st64_b32 v[96:97], v2 offset0:6 offset1:7
	v_exp_f32_e32 v2, v61
	v_exp_f32_e32 v61, v98
	v_exp_f32_e32 v98, v99
	s_waitcnt lgkmcnt(7)
	v_mov_b32_e32 v99, v78
	s_waitcnt lgkmcnt(3)
	v_mov_b32_e32 v78, v91
	v_mov_b32_e32 v91, v82
	v_add_f32_e32 v101, 1.0, v98
	v_mov_b32_e32 v98, v90
	v_pk_add_f32 v[98:99], v[98:99], 0 op_sel_hi:[1,0]
	s_waitcnt lgkmcnt(2)
	v_mov_b32_e32 v90, v92
	v_pk_add_f32 v[78:79], v[98:99], v[78:79]
	v_mov_b32_e32 v82, v93
	v_pk_add_f32 v[78:79], v[78:79], v[90:91]
	v_mul_f32_e32 v1, 0xbfb8aa3b, v68
	s_waitcnt lgkmcnt(1)
	v_mov_b32_e32 v92, v94
	v_mov_b32_e32 v93, v84
	v_pk_add_f32 v[78:79], v[78:79], v[82:83]
	v_exp_f32_e32 v1, v1
	v_mov_b32_e32 v84, v95
	v_pk_add_f32 v[78:79], v[78:79], v[92:93]
	s_waitcnt lgkmcnt(0)
	v_mov_b32_e32 v94, v96
	v_mov_b32_e32 v95, v88
	v_pk_add_f32 v[78:79], v[78:79], v[84:85]
	v_mov_b32_e32 v88, v97
	v_pk_add_f32 v[78:79], v[78:79], v[94:95]
	v_add_f32_e32 v1, 1.0, v1
	v_pk_add_f32 v[78:79], v[78:79], v[88:89]
	v_rcp_f32_e32 v96, v1
	v_pk_fma_f32 v[78:79], v[78:79], s[80:81], v[86:87] op_sel_hi:[1,0,0]
	v_add_f32_e32 v2, 1.0, v2
	v_mul_f32_e32 v1, 0x4b800000, v79
	v_cmp_gt_f32_e32 vcc, s42, v79
	v_add_f32_e32 v61, 1.0, v61
	v_rcp_f32_e32 v97, v2
	v_cndmask_b32_e32 v1, v79, v1, vcc
	v_rsq_f32_e32 v1, v1
	v_rcp_f32_e32 v100, v61
	v_rcp_f32_e32 v101, v101
	v_pk_mul_f32 v[68:69], v[96:97], v[68:69]
	v_mul_f32_e32 v2, 0x45800000, v1
	v_cndmask_b32_e32 v2, v1, v2, vcc
	v_pk_mul_f32 v[56:57], v[56:57], v[2:3] op_sel_hi:[1,0]
	v_pk_mul_f32 v[58:59], v[58:59], v[2:3] op_sel_hi:[1,0]
	v_pk_mul_f32 v[70:71], v[100:101], v[70:71]
	v_lshlrev_b32_e32 v2, 16, v62
	v_mov_b32_e32 v61, v3
	v_and_b32_e32 v3, 0xffff0000, v62
	v_mul_f32_e32 v1, 0xbfb8aa3b, v2
	v_exp_f32_e32 v1, v1
	v_lshlrev_b32_e32 v62, 16, v63
	v_and_b32_e32 v63, 0xffff0000, v63
	v_cmp_gt_f32_e32 vcc, s42, v78
	v_add_f32_e32 v1, 1.0, v1
	v_lshlrev_b64 v[60:61], 11, v[60:61]
	v_lshl_add_u64 v[60:61], s[16:17], 0, v[60:61]
	v_lshl_add_u64 v[60:61], v[60:61], 0, s[62:63]
	v_lshl_add_u64 v[60:61], v[60:61], 0, v[80:81]
	v_lshl_add_u64 v[60:61], v[60:61], 0, v[74:75]
	s_nop 0
	v_pk_mul_f32 v[56:57], v[248:249], v[56:57]
	v_pk_mul_f32 v[58:59], v[250:251], v[58:59]
	v_pk_mul_f32 v[56:57], v[68:69], v[56:57]
	v_pk_mul_f32 v[58:59], v[70:71], v[58:59]
	v_cvt_pk_bf16_f32 v56, v56, v57
	v_cvt_pk_bf16_f32 v57, v58, v59
	global_store_dwordx2 v[72:73], v[56:57], off offset:1024
	s_nop 0
	v_mul_f32_e32 v64, 0xbfb8aa3b, v3
	v_exp_f32_e32 v64, v64
	v_mul_f32_e32 v65, 0xbfb8aa3b, v62
	v_exp_f32_e32 v65, v65
	v_mul_f32_e32 v66, 0xbfb8aa3b, v63
	v_exp_f32_e32 v66, v66
	v_add_f32_e32 v67, 1.0, v64
	v_rcp_f32_e32 v64, v1
	v_mul_f32_e32 v1, 0x4b800000, v78
	v_cndmask_b32_e32 v1, v78, v1, vcc
	v_add_f32_e32 v68, 1.0, v65
	v_rcp_f32_e32 v65, v67
	v_rsq_f32_e32 v1, v1
	v_add_f32_e32 v69, 1.0, v66
	v_rcp_f32_e32 v66, v68
	v_rcp_f32_e32 v67, v69
	v_pk_mul_f32 v[2:3], v[64:65], v[2:3]
	v_mul_f32_e32 v64, 0x45800000, v1
	v_cndmask_b32_e32 v64, v1, v64, vcc
	v_pk_mul_f32 v[52:53], v[52:53], v[64:65] op_sel_hi:[1,0]
	v_pk_mul_f32 v[54:55], v[54:55], v[64:65] op_sel_hi:[1,0]
	v_pk_mul_f32 v[62:63], v[66:67], v[62:63]
	s_nop 0
	v_pk_mul_f32 v[52:53], v[248:249], v[52:53]
	v_pk_mul_f32 v[54:55], v[250:251], v[54:55]
	v_pk_mul_f32 v[2:3], v[2:3], v[52:53]
	v_pk_mul_f32 v[52:53], v[62:63], v[54:55]
	v_cvt_pk_bf16_f32 v2, v2, v3
	v_cvt_pk_bf16_f32 v3, v52, v53
	global_store_dwordx2 v[60:61], v[2:3], off offset:1024
	s_barrier

.LBB0_805:
	s_or_b64 exec, exec, s[6:7]
	s_lshl_b32 s6, s8, 2
	s_add_u32 s6, s38, s6
	s_addc_u32 s7, s39, 0
	v_lshl_add_u64 v[78:79], v[78:79], 2, s[6:7]
	s_waitcnt lgkmcnt(0)
	s_barrier
	global_load_dwordx4 v[248:251], v[78:79], off
	v_ashrrev_i32_e32 v93, 31, v92
	v_lshl_add_u32 v61, v144, 2, s96
	v_lshlrev_b64 v[84:85], 11, v[2:3]
	v_lshl_add_u32 v2, v73, 2, s96
	s_waitcnt vmcnt(4)
	v_lshlrev_b32_e32 v90, 16, v76
	v_and_b32_e32 v91, 0xffff0000, v76
	v_lshlrev_b32_e32 v98, 16, v77
	v_and_b32_e32 v99, 0xffff0000, v77
	ds_read2st64_b32 v[100:101], v61 offset1:1
	ds_read2st64_b32 v[102:103], v61 offset0:2 offset1:3
	ds_read2st64_b32 v[104:105], v61 offset0:4 offset1:5
	ds_read2st64_b32 v[106:107], v61 offset0:6 offset1:7
	v_lshl_add_u64 v[108:109], s[16:17], 0, v[84:85]
	v_lshlrev_b64 v[84:85], 1, v[92:93]
	ds_read2st64_b32 v[92:93], v2 offset1:1
	ds_read2st64_b32 v[110:111], v2 offset0:2 offset1:3
	ds_read2st64_b32 v[112:113], v2 offset0:4 offset1:5
	ds_read2st64_b32 v[114:115], v2 offset0:6 offset1:7
	v_mul_f32_e32 v61, 0xbfb8aa3b, v90
	v_mul_f32_e32 v73, 0xbfb8aa3b, v91
	v_mul_f32_e32 v81, 0xbfb8aa3b, v98
	v_mul_f32_e32 v116, 0xbfb8aa3b, v99
	v_exp_f32_e32 v2, v61
	v_exp_f32_e32 v61, v73
	v_exp_f32_e32 v73, v81
	v_exp_f32_e32 v81, v116
	s_waitcnt lgkmcnt(3)
	v_mov_b32_e32 v116, v92
	v_mov_b32_e32 v117, v100
	v_mov_b32_e32 v100, v93
	v_pk_add_f32 v[116:117], v[116:117], 0 op_sel_hi:[1,0]
	s_waitcnt lgkmcnt(2)
	v_mov_b32_e32 v92, v110
	v_mov_b32_e32 v93, v102
	v_pk_add_f32 v[100:101], v[116:117], v[100:101]
	v_mov_b32_e32 v102, v111
	v_pk_add_f32 v[92:93], v[100:101], v[92:93]
	s_waitcnt lgkmcnt(1)
	v_mov_b32_e32 v110, v112
	v_mov_b32_e32 v111, v104
	v_pk_add_f32 v[92:93], v[92:93], v[102:103]
	v_mov_b32_e32 v104, v113
	v_pk_add_f32 v[92:93], v[92:93], v[110:111]
	s_waitcnt lgkmcnt(0)
	v_mov_b32_e32 v112, v114
	v_mov_b32_e32 v113, v106
	v_pk_add_f32 v[92:93], v[92:93], v[104:105]
	v_mov_b32_e32 v106, v115
	v_pk_add_f32 v[92:93], v[92:93], v[112:113]
	v_mov_b64_e32 v[86:87], s[82:83]
	v_pk_add_f32 v[92:93], v[92:93], v[106:107]
	v_add_f32_e32 v2, 1.0, v2
	v_pk_fma_f32 v[92:93], v[92:93], s[80:81], v[86:87] op_sel_hi:[1,0,0]
	v_rcp_f32_e32 v114, v2
	v_mul_f32_e32 v2, 0x4b800000, v93
	v_cmp_gt_f32_e32 vcc, s42, v93
	v_add_f32_e32 v61, 1.0, v61
	v_add_f32_e32 v73, 1.0, v73
	v_cndmask_b32_e32 v2, v93, v2, vcc
	v_rsq_f32_e32 v2, v2
	v_add_f32_e32 v81, 1.0, v81
	v_rcp_f32_e32 v115, v61
	v_rcp_f32_e32 v118, v73
	v_rcp_f32_e32 v119, v81
	v_mul_f32_e32 v61, 0x45800000, v2
	v_cndmask_b32_e32 v2, v2, v61, vcc
	v_pk_mul_f32 v[68:69], v[68:69], v[2:3] op_sel_hi:[1,0]
	v_pk_mul_f32 v[70:71], v[70:71], v[2:3] op_sel_hi:[1,0]
	v_lshl_add_u64 v[108:109], v[108:109], 0, s[62:63]
	v_pk_mul_f32 v[90:91], v[114:115], v[90:91]
	v_pk_mul_f32 v[98:99], v[118:119], v[98:99]
	v_lshlrev_b32_e32 v76, 1, v145
	v_mov_b32_e32 v77, v0
	v_lshl_add_u64 v[108:109], v[108:109], 0, v[84:85]
	v_lshl_add_u64 v[100:101], v[108:109], 0, v[76:77]
	v_cmp_gt_f32_e32 vcc, s42, v92
	v_mov_b32_e32 v81, v3
	v_lshlrev_b64 v[80:81], 11, v[80:81]
	v_lshl_add_u64 v[80:81], s[16:17], 0, v[80:81]
	v_lshl_add_u64 v[80:81], v[80:81], 0, s[62:63]
	v_lshl_add_u64 v[80:81], v[80:81], 0, v[84:85]
	v_lshl_add_u64 v[80:81], v[80:81], 0, v[76:77]
	s_cmpk_gt_i32 s50, 0x7ff
	s_mov_b64 s[6:7], -1
	s_waitcnt vmcnt(0)
	v_pk_mul_f32 v[68:69], v[248:249], v[68:69]
	v_pk_mul_f32 v[70:71], v[250:251], v[70:71]
	v_pk_mul_f32 v[68:69], v[90:91], v[68:69]
	v_pk_mul_f32 v[70:71], v[98:99], v[70:71]
	v_cvt_pk_bf16_f32 v68, v68, v69
	v_cvt_pk_bf16_f32 v69, v70, v71
	global_store_dwordx2 v[100:101], v[68:69], off offset:1024
	s_nop 0
	v_lshlrev_b32_e32 v90, 16, v82
	v_mul_f32_e32 v2, 0xbfb8aa3b, v90
	v_exp_f32_e32 v2, v2
	v_and_b32_e32 v91, 0xffff0000, v82
	v_lshlrev_b32_e32 v82, 16, v83
	v_and_b32_e32 v83, 0xffff0000, v83
	v_mul_f32_e32 v61, 0xbfb8aa3b, v91
	v_mul_f32_e32 v73, 0xbfb8aa3b, v82
	v_mul_f32_e32 v93, 0xbfb8aa3b, v83
	v_add_f32_e32 v2, 1.0, v2
	v_exp_f32_e32 v61, v61
	v_exp_f32_e32 v73, v73
	v_exp_f32_e32 v93, v93
	v_rcp_f32_e32 v94, v2
	v_mul_f32_e32 v2, 0x4b800000, v92
	v_cndmask_b32_e32 v2, v92, v2, vcc
	v_rsq_f32_e32 v2, v2
	v_add_f32_e32 v61, 1.0, v61
	v_add_f32_e32 v73, 1.0, v73
	v_add_f32_e32 v93, 1.0, v93
	v_rcp_f32_e32 v95, v61
	v_rcp_f32_e32 v96, v73
	v_rcp_f32_e32 v97, v93
	v_mul_f32_e32 v61, 0x45800000, v2
	v_cndmask_b32_e32 v2, v2, v61, vcc
	v_pk_mul_f32 v[64:65], v[64:65], v[2:3] op_sel_hi:[1,0]
	v_pk_mul_f32 v[66:67], v[66:67], v[2:3] op_sel_hi:[1,0]
	v_pk_mul_f32 v[90:91], v[94:95], v[90:91]
	v_pk_mul_f32 v[82:83], v[96:97], v[82:83]
	v_lshl_add_u32 v2, v89, 2, s96
	v_lshl_add_u32 v61, v88, 2, s96
	v_mov_b32_e32 v73, v3
	v_lshlrev_b64 v[72:73], 11, v[72:73]
	v_lshl_add_u64 v[72:73], s[16:17], 0, v[72:73]
	v_lshl_add_u64 v[72:73], v[72:73], 0, s[62:63]
	v_lshl_add_u64 v[72:73], v[72:73], 0, v[84:85]
	v_lshl_add_u64 v[72:73], v[72:73], 0, v[76:77]
	s_nop 0
	v_pk_mul_f32 v[64:65], v[248:249], v[64:65]
	v_pk_mul_f32 v[66:67], v[250:251], v[66:67]
	v_pk_mul_f32 v[64:65], v[90:91], v[64:65]
	v_pk_mul_f32 v[66:67], v[82:83], v[66:67]
	v_cvt_pk_bf16_f32 v64, v64, v65
	v_cvt_pk_bf16_f32 v65, v66, v67
	global_store_dwordx2 v[80:81], v[64:65], off offset:1024
	s_nop 0
	v_and_b32_e32 v69, 0xffff0000, v74
	v_lshlrev_b32_e32 v70, 16, v75
	v_and_b32_e32 v71, 0xffff0000, v75
	v_mul_f32_e32 v98, 0xbfb8aa3b, v69
	v_mul_f32_e32 v99, 0xbfb8aa3b, v70
	v_mul_f32_e32 v100, 0xbfb8aa3b, v71
	v_lshlrev_b32_e32 v68, 16, v74
	ds_read2st64_b32 v[74:75], v2 offset1:1
	ds_read2st64_b32 v[80:81], v2 offset0:2 offset1:3
	ds_read2st64_b32 v[82:83], v2 offset0:4 offset1:5
	ds_read2st64_b32 v[88:89], v2 offset0:6 offset1:7
	ds_read2st64_b32 v[90:91], v61 offset1:1
	ds_read2st64_b32 v[92:93], v61 offset0:2 offset1:3
	ds_read2st64_b32 v[94:95], v61 offset0:4 offset1:5
	ds_read2st64_b32 v[96:97], v61 offset0:6 offset1:7
	v_exp_f32_e32 v61, v98
	v_exp_f32_e32 v98, v99
	v_exp_f32_e32 v99, v100
	v_mul_f32_e32 v2, 0xbfb8aa3b, v68
	v_exp_f32_e32 v2, v2
	v_add_f32_e32 v100, 1.0, v98
	v_add_f32_e32 v101, 1.0, v99
	s_waitcnt lgkmcnt(3)
	v_mov_b32_e32 v98, v90
	v_mov_b32_e32 v99, v74
	v_mov_b32_e32 v74, v91
	v_pk_add_f32 v[98:99], v[98:99], 0 op_sel_hi:[1,0]
	s_waitcnt lgkmcnt(2)
	v_mov_b32_e32 v90, v92
	v_mov_b32_e32 v91, v80
	v_pk_add_f32 v[74:75], v[98:99], v[74:75]
	v_mov_b32_e32 v80, v93
	v_pk_add_f32 v[74:75], v[74:75], v[90:91]
	s_waitcnt lgkmcnt(1)
	v_mov_b32_e32 v92, v94
	v_mov_b32_e32 v93, v82
	v_pk_add_f32 v[74:75], v[74:75], v[80:81]
	v_mov_b32_e32 v82, v95
	v_pk_add_f32 v[74:75], v[74:75], v[92:93]
	s_waitcnt lgkmcnt(0)
	v_mov_b32_e32 v94, v96
	v_mov_b32_e32 v95, v88
	v_pk_add_f32 v[74:75], v[74:75], v[82:83]
	v_mov_b32_e32 v88, v97
	v_pk_add_f32 v[74:75], v[74:75], v[94:95]
	v_add_f32_e32 v2, 1.0, v2
	v_pk_add_f32 v[74:75], v[74:75], v[88:89]
	v_rcp_f32_e32 v96, v2
	v_pk_fma_f32 v[74:75], v[74:75], s[80:81], v[86:87] op_sel_hi:[1,0,0]
	v_add_f32_e32 v61, 1.0, v61
	v_mul_f32_e32 v2, 0x4b800000, v75
	v_cmp_gt_f32_e32 vcc, s42, v75
	v_rcp_f32_e32 v97, v61
	v_rcp_f32_e32 v100, v100
	v_cndmask_b32_e32 v2, v75, v2, vcc
	v_rsq_f32_e32 v2, v2
	v_rcp_f32_e32 v101, v101
	v_pk_mul_f32 v[68:69], v[96:97], v[68:69]
	v_mul_f32_e32 v61, 0x45800000, v2
	v_cndmask_b32_e32 v2, v2, v61, vcc
	v_pk_mul_f32 v[56:57], v[56:57], v[2:3] op_sel_hi:[1,0]
	v_pk_mul_f32 v[58:59], v[58:59], v[2:3] op_sel_hi:[1,0]
	v_pk_mul_f32 v[70:71], v[100:101], v[70:71]
	v_mov_b32_e32 v61, v3
	v_lshlrev_b32_e32 v2, 16, v62
	v_and_b32_e32 v3, 0xffff0000, v62
	v_lshlrev_b32_e32 v62, 16, v63
	v_and_b32_e32 v63, 0xffff0000, v63
	v_cmp_gt_f32_e32 vcc, s42, v74
	v_lshlrev_b64 v[60:61], 11, v[60:61]
	v_lshl_add_u64 v[60:61], s[16:17], 0, v[60:61]
	v_lshl_add_u64 v[60:61], v[60:61], 0, s[62:63]
	v_lshl_add_u64 v[60:61], v[60:61], 0, v[84:85]
	v_lshl_add_u64 v[60:61], v[60:61], 0, v[76:77]
	s_nop 0
	v_pk_mul_f32 v[56:57], v[248:249], v[56:57]
	v_pk_mul_f32 v[58:59], v[250:251], v[58:59]
	v_pk_mul_f32 v[56:57], v[68:69], v[56:57]
	v_pk_mul_f32 v[58:59], v[70:71], v[58:59]
	v_cvt_pk_bf16_f32 v56, v56, v57
	v_cvt_pk_bf16_f32 v57, v58, v59
	global_store_dwordx2 v[72:73], v[56:57], off offset:1024
	s_nop 0
	v_mul_f32_e32 v64, 0xbfb8aa3b, v2
	v_mul_f32_e32 v65, 0xbfb8aa3b, v3
	v_exp_f32_e32 v64, v64
	v_exp_f32_e32 v65, v65
	v_mul_f32_e32 v66, 0xbfb8aa3b, v62
	v_mul_f32_e32 v67, 0xbfb8aa3b, v63
	v_exp_f32_e32 v66, v66
	v_exp_f32_e32 v67, v67
	v_mul_f32_e32 v68, 0x4b800000, v74
	v_add_f32_e32 v64, 1.0, v64
	v_add_f32_e32 v65, 1.0, v65
	v_cndmask_b32_e32 v68, v74, v68, vcc
	v_rcp_f32_e32 v64, v64
	v_rcp_f32_e32 v65, v65
	v_rsq_f32_e32 v68, v68
	v_add_f32_e32 v66, 1.0, v66
	v_add_f32_e32 v67, 1.0, v67
	v_rcp_f32_e32 v66, v66
	v_rcp_f32_e32 v67, v67
	v_pk_mul_f32 v[2:3], v[64:65], v[2:3]
	v_mul_f32_e32 v64, 0x45800000, v68
	v_cndmask_b32_e32 v64, v68, v64, vcc
	v_pk_mul_f32 v[52:53], v[52:53], v[64:65] op_sel_hi:[1,0]
	v_pk_mul_f32 v[54:55], v[54:55], v[64:65] op_sel_hi:[1,0]
	v_pk_mul_f32 v[62:63], v[66:67], v[62:63]
	s_nop 0
	v_pk_mul_f32 v[52:53], v[248:249], v[52:53]
	v_pk_mul_f32 v[54:55], v[250:251], v[54:55]
	v_pk_mul_f32 v[2:3], v[2:3], v[52:53]
	v_pk_mul_f32 v[52:53], v[62:63], v[54:55]
	v_cvt_pk_bf16_f32 v2, v2, v3
	v_cvt_pk_bf16_f32 v3, v52, v53
	global_store_dwordx2 v[60:61], v[2:3], off offset:1024
	s_barrier
	s_cbranch_scc1 .LBB0_784
	s_add_i32 s2, s89, s2
	s_cmpk_gt_i32 s2, 0x7ff
	s_cbranch_scc1 .LBB0_808
	v_mov_b32_e32 v12, v204
	s_ashr_i32 s6, s2, 8
	v_ashrrev_i32_e32 v2, 31, v12
	v_lshrrev_b32_e32 v2, 28, v2
	v_add_u32_e32 v3, v12, v2
	s_ashr_i32 s7, s6, 31
	s_add_i32 s2, s88, s73
	v_ashrrev_i32_e32 v2, 4, v3
	v_and_b32_e32 v3, 0x1ffffff0, v3
	s_lshl_b64 s[6:7], s[6:7], 12
	s_and_b32 s2, s2, 0xfc0
	v_sub_u32_e32 v3, v12, v3
	s_or_b32 s6, s6, s2
	v_lshlrev_b32_e32 v4, 3, v3
	v_ashrrev_i32_e32 v3, 31, v2
	s_add_i32 s2, s91, s61
	v_lshl_add_u64 v[2:3], s[6:7], 0, v[2:3]
	v_mov_b64_e32 v[6:7], s[66:67]
	s_and_b32 s2, s2, 0x180
	v_mad_u64_u32 v[8:9], s[8:9], v2, s0, v[6:7]
	v_mad_i32_i24 v9, v3, s0, v9
	s_lshl_b32 s62, s2, 1
	v_lshl_add_u64 v[2:3], v[8:9], 0, s[62:63]
	v_ashrrev_i32_e32 v5, 31, v4
	v_lshl_add_u64 v[2:3], v[4:5], 1, v[2:3]
	v_add_u32_e32 v5, 0x200, v12
	v_ashrrev_i32_e32 v4, 31, v5
	v_lshrrev_b32_e32 v4, 28, v4
	v_add_u32_e32 v8, v5, v4
	v_ashrrev_i32_e32 v4, 4, v8
	v_and_b32_e32 v8, 0x1ffffff0, v8
	v_sub_u32_e32 v5, v5, v8
	v_lshlrev_b32_e32 v8, 3, v5
	v_ashrrev_i32_e32 v5, 31, v4
	v_lshl_add_u64 v[4:5], s[6:7], 0, v[4:5]
	v_mad_u64_u32 v[6:7], s[8:9], v4, s0, v[6:7]
	v_mad_i32_i24 v7, v5, s0, v7
	v_add_co_u32_e32 v2, vcc, s48, v2
	v_lshl_add_u64 v[4:5], v[6:7], 0, s[62:63]
	v_ashrrev_i32_e32 v9, 31, v8
	v_addc_co_u32_e32 v3, vcc, 0, v3, vcc
	v_lshl_add_u64 v[4:5], v[8:9], 1, v[4:5]
	v_add_co_u32_e32 v8, vcc, s48, v4
	s_add_u32 s8, s66, s62
	s_nop 0
	v_addc_co_u32_e32 v9, vcc, 0, v5, vcc
	global_load_dwordx4 v[4:7], v[2:3], off offset:1024
	s_nop 0
	global_load_dwordx4 v[8:11], v[8:9], off offset:1024
	v_ashrrev_i32_e32 v2, 4, v12
	v_lshlrev_b32_e32 v3, 4, v12
	s_addc_u32 s9, s67, 0
	v_and_b32_e32 v12, 0xf0, v3
	v_mov_b32_e32 v13, v0
	v_ashrrev_i32_e32 v3, 31, v2
	v_lshl_add_u64 v[12:13], s[8:9], 0, v[12:13]
	v_lshl_add_u64 v[14:15], s[6:7], 0, v[2:3]
	v_add_u32_e32 v2, 32, v2
	v_mad_u64_u32 v[20:21], s[8:9], v14, s0, v[12:13]
	v_ashrrev_i32_e32 v3, 31, v2
	v_mad_i32_i24 v21, v15, s0, v21
	v_add_co_u32_e32 v28, vcc, s48, v20
	v_lshl_add_u64 v[2:3], s[6:7], 0, v[2:3]
	s_nop 0
	v_addc_co_u32_e32 v29, vcc, 0, v21, vcc
	v_mad_u64_u32 v[30:31], s[6:7], v2, s0, v[12:13]
	v_mad_i32_i24 v31, v3, s0, v31
	v_add_co_u32_e32 v2, vcc, 0x1000, v30
	global_load_dwordx4 v[12:15], v[20:21], off offset:3072
	s_nop 0
	global_load_dwordx4 v[20:23], v[30:31], off offset:3072
	v_addc_co_u32_e32 v3, vcc, 0, v31, vcc
	global_load_dwordx4 v[28:31], v[28:29], off
	s_nop 0
	global_load_dwordx4 v[32:35], v[2:3], off

.LBB0_987:
	ds_read_b128 v[164:167], v155
	ds_read_b128 v[168:171], v155 offset:1024
	ds_read_b128 v[172:175], v155 offset:2048
	ds_read_b128 v[176:179], v155 offset:3072
	s_add_u32 s56, s12, 0xfffc0080
	s_addc_u32 s57, s13, -1
	s_cmp_eq_u32 s71, 12
	s_cselect_b32 s59, s11, s57
	s_cselect_b32 s58, s51, s56
	s_cselect_b32 s57, s39, s70
	s_cselect_b32 s56, s68, s69
	v_lshl_add_u64 v[146:147], s[12:13], 0, v[136:137]
	s_add_i32 m0, s35, 0xc000
	ds_read_b128 v[180:183], v159
	ds_read_b128 v[184:187], v159 offset:1024
	ds_read_b128 v[188:191], v159 offset:2048
	ds_read_b128 v[192:195], v159 offset:3072
	ds_read_b128 v[196:199], v159 offset:4096
	ds_read_b128 v[200:203], v159 offset:5120
	ds_read_b128 v[206:209], v159 offset:6144
	ds_read_b128 v[210:213], v159 offset:7168
	global_load_lds_dwordx4 v[146:147], off
	v_lshl_add_u64 v[146:147], s[12:13], 0, v[138:139]
	s_add_i32 m0, s35, 0xe000
	s_nop 0
	global_load_lds_dwordx4 v[146:147], off
	s_waitcnt lgkmcnt(8)
	s_barrier
	s_waitcnt lgkmcnt(0)
	s_setprio 1
	s_waitcnt lgkmcnt(0)
	v_mfma_f32_16x16x32_bf16 v[124:127], v[164:167], v[180:183], v[124:127]
	v_mfma_f32_16x16x32_bf16 v[120:123], v[172:175], v[180:183], v[120:123]
	v_mfma_f32_16x16x32_bf16 v[108:111], v[164:167], v[188:191], v[108:111]
	v_mfma_f32_16x16x32_bf16 v[104:107], v[172:175], v[188:191], v[104:107]
	v_mfma_f32_16x16x32_bf16 v[92:95], v[164:167], v[196:199], v[92:95]
	v_mfma_f32_16x16x32_bf16 v[88:91], v[172:175], v[196:199], v[88:91]
	v_mfma_f32_16x16x32_bf16 v[76:79], v[164:167], v[206:209], v[76:79]
	v_mfma_f32_16x16x32_bf16 v[72:75], v[172:175], v[206:209], v[72:75]
	v_mfma_f32_16x16x32_bf16 v[124:127], v[168:171], v[184:187], v[124:127]
	v_mfma_f32_16x16x32_bf16 v[120:123], v[176:179], v[184:187], v[120:123]
	v_mfma_f32_16x16x32_bf16 v[108:111], v[168:171], v[192:195], v[108:111]
	v_mfma_f32_16x16x32_bf16 v[104:107], v[176:179], v[192:195], v[104:107]
	v_mfma_f32_16x16x32_bf16 v[92:95], v[168:171], v[200:203], v[92:95]
	v_mfma_f32_16x16x32_bf16 v[88:91], v[176:179], v[200:203], v[88:91]
	v_mfma_f32_16x16x32_bf16 v[76:79], v[168:171], v[210:213], v[76:79]
	v_mfma_f32_16x16x32_bf16 v[72:75], v[176:179], v[210:213], v[72:75]
	s_setprio 0
	s_barrier
	s_add_i32 s72, s60, s34
	v_lshl_add_u64 v[146:147], s[56:57], 0, v[130:131]
	s_mov_b32 m0, s72
	ds_read_b128 v[214:217], v162
	ds_read_b128 v[218:221], v162 offset:1024
	ds_read_b128 v[222:225], v162 offset:2048
	ds_read_b128 v[226:229], v162 offset:3072
	global_load_lds_dwordx4 v[146:147], off
	v_lshl_add_u64 v[152:153], s[56:57], 0, v[134:135]
	s_add_i32 m0, s72, 0x2000
	s_nop 0
	global_load_lds_dwordx4 v[152:153], off
	s_barrier
	s_waitcnt lgkmcnt(0)
	s_setprio 1
	s_waitcnt lgkmcnt(0)
	v_mfma_f32_16x16x32_bf16 v[116:119], v[214:217], v[180:183], v[116:119]
	v_mfma_f32_16x16x32_bf16 v[112:115], v[222:225], v[180:183], v[112:115]
	v_mfma_f32_16x16x32_bf16 v[100:103], v[214:217], v[188:191], v[100:103]
	v_mfma_f32_16x16x32_bf16 v[96:99], v[222:225], v[188:191], v[96:99]
	v_mfma_f32_16x16x32_bf16 v[84:87], v[214:217], v[196:199], v[84:87]
	v_mfma_f32_16x16x32_bf16 v[80:83], v[222:225], v[196:199], v[80:83]
	v_mfma_f32_16x16x32_bf16 v[68:71], v[214:217], v[206:209], v[68:71]
	v_mfma_f32_16x16x32_bf16 v[64:67], v[222:225], v[206:209], v[64:67]
	v_mfma_f32_16x16x32_bf16 v[116:119], v[218:221], v[184:187], v[116:119]
	v_mfma_f32_16x16x32_bf16 v[112:115], v[226:229], v[184:187], v[112:115]
	v_mfma_f32_16x16x32_bf16 v[100:103], v[218:221], v[192:195], v[100:103]
	v_mfma_f32_16x16x32_bf16 v[96:99], v[226:229], v[192:195], v[96:99]
	v_mfma_f32_16x16x32_bf16 v[84:87], v[218:221], v[200:203], v[84:87]
	v_mfma_f32_16x16x32_bf16 v[80:83], v[226:229], v[200:203], v[80:83]
	v_mfma_f32_16x16x32_bf16 v[68:71], v[218:221], v[210:213], v[68:71]
	v_mfma_f32_16x16x32_bf16 v[64:67], v[226:229], v[210:213], v[64:67]
	s_setprio 0
	s_mov_b32 m0, s35
	v_lshl_add_u64 v[156:157], s[58:59], 0, v[128:129]
	s_barrier
	ds_read_b128 v[180:183], v159 offset:16384
	ds_read_b128 v[184:187], v159 offset:17408
	ds_read_b128 v[188:191], v159 offset:18432
	ds_read_b128 v[192:195], v159 offset:19456
	ds_read_b128 v[196:199], v159 offset:20480
	ds_read_b128 v[200:203], v159 offset:21504
	ds_read_b128 v[206:209], v159 offset:22528
	ds_read_b128 v[210:213], v159 offset:23552
	global_load_lds_dwordx4 v[156:157], off
	v_lshl_add_u64 v[160:161], s[58:59], 0, v[132:133]
	s_mov_b32 m0, s42
	s_nop 0
	global_load_lds_dwordx4 v[160:161], off
	s_barrier
	s_waitcnt lgkmcnt(0)
	s_setprio 1
	s_waitcnt lgkmcnt(0)
	v_mfma_f32_16x16x32_bf16 v[60:63], v[164:167], v[180:183], v[60:63]
	v_mfma_f32_16x16x32_bf16 v[56:59], v[172:175], v[180:183], v[56:59]
	v_mfma_f32_16x16x32_bf16 v[44:47], v[164:167], v[188:191], v[44:47]
	v_mfma_f32_16x16x32_bf16 v[40:43], v[172:175], v[188:191], v[40:43]
	v_mfma_f32_16x16x32_bf16 v[28:31], v[164:167], v[196:199], v[28:31]
	v_mfma_f32_16x16x32_bf16 v[24:27], v[172:175], v[196:199], v[24:27]
	v_mfma_f32_16x16x32_bf16 v[12:15], v[164:167], v[206:209], v[12:15]
	v_mfma_f32_16x16x32_bf16 v[8:11], v[172:175], v[206:209], v[8:11]
	v_mfma_f32_16x16x32_bf16 v[60:63], v[168:171], v[184:187], v[60:63]
	v_mfma_f32_16x16x32_bf16 v[56:59], v[176:179], v[184:187], v[56:59]
	v_mfma_f32_16x16x32_bf16 v[44:47], v[168:171], v[192:195], v[44:47]
	v_mfma_f32_16x16x32_bf16 v[40:43], v[176:179], v[192:195], v[40:43]
	v_mfma_f32_16x16x32_bf16 v[28:31], v[168:171], v[200:203], v[28:31]
	v_mfma_f32_16x16x32_bf16 v[24:27], v[176:179], v[200:203], v[24:27]
	v_mfma_f32_16x16x32_bf16 v[12:15], v[168:171], v[210:213], v[12:15]
	v_mfma_f32_16x16x32_bf16 v[8:11], v[176:179], v[210:213], v[8:11]
	s_setprio 0
	s_barrier
	s_add_u32 s72, s56, 0x40000
	s_addc_u32 s73, s57, 0
	s_add_i32 s74, s61, s34
	v_lshl_add_u64 v[164:165], s[72:73], 0, v[130:131]
	s_mov_b32 m0, s74
	s_nop 0
	global_load_lds_dwordx4 v[164:165], off
	v_lshl_add_u64 v[164:165], s[72:73], 0, v[134:135]
	s_add_i32 m0, s74, 0x2000
	s_nop 0
	global_load_lds_dwordx4 v[164:165], off
	s_waitcnt vmcnt(6)
	s_cmp_gt_u32 s71, 10
	s_cbranch_scc1 .Lds_P6_a_done
	s_cmp_lt_u32 s71, 6
	s_cbranch_scc1 .Lds_P6_a_st
	s_cmp_eq_u32 s71, 6
	s_cbranch_scc1 .Lds_P6_a_pf
	s_cmp_eq_u32 s71, 8
	s_cbranch_scc1 .Lds_P6_a_c8
	v_ffbh_u32_e32 v252, v241
	v_min_u32_e32 v252, 32, v252
	v_lshlrev_b64 v[240:241], v252, v[240:241]
	v_min_u32_e32 v240, 1, v240
	v_or_b32_e32 v241, v241, v240
	v_cvt_f32_u32_e32 v241, v241
	v_sub_u32_e32 v252, -2, v252
	v_ldexp_f32 v241, v241, v252
	v_add_f32_e32 v241, 0x358637bd, v241
	v_rsq_f32_e32 v252, v241
	v_ffbh_u32_e32 v253, v243
	v_min_u32_e32 v253, 32, v253
	v_lshlrev_b64 v[242:243], v253, v[242:243]
	v_min_u32_e32 v242, 1, v242
	v_or_b32_e32 v243, v243, v242
	v_cvt_f32_u32_e32 v243, v243
	v_sub_u32_e32 v253, -2, v253
	v_ldexp_f32 v243, v243, v253
	v_add_f32_e32 v243, 0x358637bd, v243
	v_rsq_f32_e32 v253, v243
	s_branch .Lds_P6_a_done

.Lds_P6_a_pf:
	s_lshl_b32 s82, s10, 11
	s_add_u32 s100, s18, s82
	s_addc_u32 s101, s19, 0
	v_lshlrev_b32_e32 v252, 3, v145
	global_load_dwordx2 v[230:231], v252, s[100:101]
	global_load_dwordx2 v[232:233], v252, s[100:101] offset:128
	global_load_dwordx2 v[234:235], v252, s[100:101] offset:256
	global_load_dwordx2 v[236:237], v252, s[100:101] offset:384
	global_load_dwordx2 v[240:241], v252, s[100:101] offset:1024
	global_load_dwordx2 v[242:243], v252, s[100:101] offset:1152
	global_load_dwordx2 v[244:245], v252, s[100:101] offset:1280
	global_load_dwordx2 v[246:247], v252, s[100:101] offset:1408
	s_branch .Lds_P6_a_done
.Lds_P6_a_st:
	s_cmp_eq_u32 s32, 0
	s_cbranch_scc1 .Lds_P6_a_done
	s_cmp_eq_u32 s71, 0
	s_cbranch_scc1 .Lds_P6_a_0
	s_cmp_eq_u32 s71, 2
	s_cbranch_scc1 .Lds_P6_a_1
	s_add_u32 s100, s98, 0x160000
	s_addc_u32 s101, s99, 0
	global_store_dwordx4 v239, v[248:251], s[100:101]
	s_branch .Lds_P6_a_done

.Lds_P6_a_done:
	s_barrier
	s_setprio 1
	v_mfma_f32_16x16x32_bf16 v[52:55], v[214:217], v[180:183], v[52:55]
	v_mfma_f32_16x16x32_bf16 v[48:51], v[222:225], v[180:183], v[48:51]
	v_mfma_f32_16x16x32_bf16 v[36:39], v[214:217], v[188:191], v[36:39]
	v_mfma_f32_16x16x32_bf16 v[32:35], v[222:225], v[188:191], v[32:35]
	v_mfma_f32_16x16x32_bf16 v[20:23], v[214:217], v[196:199], v[20:23]
	v_mfma_f32_16x16x32_bf16 v[16:19], v[222:225], v[196:199], v[16:19]
	v_mfma_f32_16x16x32_bf16 v[4:7], v[214:217], v[206:209], v[4:7]
	v_mfma_f32_16x16x32_bf16 v[0:3], v[222:225], v[206:209], v[0:3]
	v_mfma_f32_16x16x32_bf16 v[52:55], v[218:221], v[184:187], v[52:55]
	v_mfma_f32_16x16x32_bf16 v[48:51], v[226:229], v[184:187], v[48:51]
	v_mfma_f32_16x16x32_bf16 v[36:39], v[218:221], v[192:195], v[36:39]
	v_mfma_f32_16x16x32_bf16 v[32:35], v[226:229], v[192:195], v[32:35]
	v_mfma_f32_16x16x32_bf16 v[20:23], v[218:221], v[200:203], v[20:23]
	v_mfma_f32_16x16x32_bf16 v[16:19], v[226:229], v[200:203], v[16:19]
	v_mfma_f32_16x16x32_bf16 v[4:7], v[218:221], v[210:213], v[4:7]
	v_mfma_f32_16x16x32_bf16 v[0:3], v[226:229], v[210:213], v[0:3]
	s_setprio 0
	s_add_i32 s72, 0, 0x18000
	v_add_u32_e32 v144, s72, v149
	s_barrier
	ds_read_b128 v[164:167], v144
	ds_read_b128 v[168:171], v144 offset:1024
	ds_read_b128 v[172:175], v144 offset:2048
	ds_read_b128 v[176:179], v144 offset:3072
	s_add_u32 s58, s58, 0x40000
	s_addc_u32 s59, s59, 0
	s_mov_b32 m0, s43
	v_lshl_add_u64 v[214:215], s[58:59], 0, v[128:129]
	ds_read_b128 v[180:183], v159 offset:32768
	ds_read_b128 v[184:187], v159 offset:33792
	ds_read_b128 v[188:191], v159 offset:34816
	ds_read_b128 v[192:195], v159 offset:35840
	ds_read_b128 v[196:199], v159 offset:36864
	ds_read_b128 v[200:203], v159 offset:37888
	ds_read_b128 v[206:209], v159 offset:38912
	ds_read_b128 v[210:213], v159 offset:39936
	global_load_lds_dwordx4 v[214:215], off
	v_lshl_add_u64 v[214:215], s[58:59], 0, v[132:133]
	s_mov_b32 m0, s44
	s_nop 0
	global_load_lds_dwordx4 v[214:215], off
	s_waitcnt lgkmcnt(8)
	s_barrier
	s_waitcnt lgkmcnt(0)
	s_setprio 1
	s_waitcnt lgkmcnt(0)
	v_mfma_f32_16x16x32_bf16 v[124:127], v[164:167], v[180:183], v[124:127]
	v_mfma_f32_16x16x32_bf16 v[120:123], v[172:175], v[180:183], v[120:123]
	v_mfma_f32_16x16x32_bf16 v[108:111], v[164:167], v[188:191], v[108:111]
	v_mfma_f32_16x16x32_bf16 v[104:107], v[172:175], v[188:191], v[104:107]
	v_mfma_f32_16x16x32_bf16 v[92:95], v[164:167], v[196:199], v[92:95]
	v_mfma_f32_16x16x32_bf16 v[88:91], v[172:175], v[196:199], v[88:91]
	v_mfma_f32_16x16x32_bf16 v[76:79], v[164:167], v[206:209], v[76:79]
	v_mfma_f32_16x16x32_bf16 v[72:75], v[172:175], v[206:209], v[72:75]
	v_mfma_f32_16x16x32_bf16 v[124:127], v[168:171], v[184:187], v[124:127]
	v_mfma_f32_16x16x32_bf16 v[120:123], v[176:179], v[184:187], v[120:123]
	v_mfma_f32_16x16x32_bf16 v[108:111], v[168:171], v[192:195], v[108:111]
	v_mfma_f32_16x16x32_bf16 v[104:107], v[176:179], v[192:195], v[104:107]
	v_mfma_f32_16x16x32_bf16 v[92:95], v[168:171], v[200:203], v[92:95]
	v_mfma_f32_16x16x32_bf16 v[88:91], v[176:179], v[200:203], v[88:91]
	v_mfma_f32_16x16x32_bf16 v[76:79], v[168:171], v[210:213], v[76:79]
	v_mfma_f32_16x16x32_bf16 v[72:75], v[176:179], v[210:213], v[72:75]
	s_setprio 0
	s_barrier
	s_add_i32 s58, 0, 0x1c000
	s_add_i32 s59, s72, s34
	v_add_u32_e32 v144, s58, v149
	v_lshl_add_u64 v[146:147], v[146:147], 0, s[24:25]
	s_mov_b32 m0, s59
	ds_read_b128 v[214:217], v144
	ds_read_b128 v[218:221], v144 offset:1024
	ds_read_b128 v[222:225], v144 offset:2048
	ds_read_b128 v[226:229], v144 offset:3072
	global_load_lds_dwordx4 v[146:147], off
	v_lshl_add_u64 v[146:147], v[152:153], 0, s[24:25]
	s_add_i32 m0, s59, 0x2000
	s_nop 0
	global_load_lds_dwordx4 v[146:147], off
	s_barrier
	s_waitcnt lgkmcnt(0)
	s_setprio 1
	s_waitcnt lgkmcnt(0)
	v_mfma_f32_16x16x32_bf16 v[116:119], v[214:217], v[180:183], v[116:119]
	v_mfma_f32_16x16x32_bf16 v[112:115], v[222:225], v[180:183], v[112:115]
	v_mfma_f32_16x16x32_bf16 v[100:103], v[214:217], v[188:191], v[100:103]
	v_mfma_f32_16x16x32_bf16 v[96:99], v[222:225], v[188:191], v[96:99]
	v_mfma_f32_16x16x32_bf16 v[84:87], v[214:217], v[196:199], v[84:87]
	v_mfma_f32_16x16x32_bf16 v[80:83], v[222:225], v[196:199], v[80:83]
	v_mfma_f32_16x16x32_bf16 v[68:71], v[214:217], v[206:209], v[68:71]
	v_mfma_f32_16x16x32_bf16 v[64:67], v[222:225], v[206:209], v[64:67]
	v_mfma_f32_16x16x32_bf16 v[116:119], v[218:221], v[184:187], v[116:119]
	v_mfma_f32_16x16x32_bf16 v[112:115], v[226:229], v[184:187], v[112:115]
	v_mfma_f32_16x16x32_bf16 v[100:103], v[218:221], v[192:195], v[100:103]
	v_mfma_f32_16x16x32_bf16 v[96:99], v[226:229], v[192:195], v[96:99]
	v_mfma_f32_16x16x32_bf16 v[84:87], v[218:221], v[200:203], v[84:87]
	v_mfma_f32_16x16x32_bf16 v[80:83], v[226:229], v[200:203], v[80:83]
	v_mfma_f32_16x16x32_bf16 v[68:71], v[218:221], v[210:213], v[68:71]
	v_mfma_f32_16x16x32_bf16 v[64:67], v[226:229], v[210:213], v[64:67]
	s_setprio 0
	s_mov_b32 m0, s46
	v_lshl_add_u64 v[146:147], v[156:157], 0, s[24:25]
	s_barrier
	ds_read_b128 v[180:183], v159 offset:49152
	ds_read_b128 v[184:187], v159 offset:50176
	ds_read_b128 v[188:191], v159 offset:51200
	ds_read_b128 v[192:195], v159 offset:52224
	ds_read_b128 v[196:199], v159 offset:53248
	ds_read_b128 v[200:203], v159 offset:54272
	ds_read_b128 v[206:209], v159 offset:55296
	ds_read_b128 v[210:213], v159 offset:56320
	global_load_lds_dwordx4 v[146:147], off
	v_lshl_add_u64 v[146:147], v[160:161], 0, s[24:25]
	s_mov_b32 m0, s47
	s_nop 0
	global_load_lds_dwordx4 v[146:147], off
	s_barrier
	s_waitcnt lgkmcnt(0)
	s_setprio 1
	s_waitcnt lgkmcnt(0)
	v_mfma_f32_16x16x32_bf16 v[60:63], v[164:167], v[180:183], v[60:63]
	v_mfma_f32_16x16x32_bf16 v[56:59], v[172:175], v[180:183], v[56:59]
	v_mfma_f32_16x16x32_bf16 v[44:47], v[164:167], v[188:191], v[44:47]
	v_mfma_f32_16x16x32_bf16 v[40:43], v[172:175], v[188:191], v[40:43]
	v_mfma_f32_16x16x32_bf16 v[28:31], v[164:167], v[196:199], v[28:31]
	v_mfma_f32_16x16x32_bf16 v[24:27], v[172:175], v[196:199], v[24:27]
	v_mfma_f32_16x16x32_bf16 v[12:15], v[164:167], v[206:209], v[12:15]
	v_mfma_f32_16x16x32_bf16 v[8:11], v[172:175], v[206:209], v[8:11]
	v_mfma_f32_16x16x32_bf16 v[60:63], v[168:171], v[184:187], v[60:63]
	v_mfma_f32_16x16x32_bf16 v[56:59], v[176:179], v[184:187], v[56:59]
	v_mfma_f32_16x16x32_bf16 v[44:47], v[168:171], v[192:195], v[44:47]
	v_mfma_f32_16x16x32_bf16 v[40:43], v[176:179], v[192:195], v[40:43]
	v_mfma_f32_16x16x32_bf16 v[28:31], v[168:171], v[200:203], v[28:31]
	v_mfma_f32_16x16x32_bf16 v[24:27], v[176:179], v[200:203], v[24:27]
	v_mfma_f32_16x16x32_bf16 v[12:15], v[168:171], v[210:213], v[12:15]
	v_mfma_f32_16x16x32_bf16 v[8:11], v[176:179], v[210:213], v[8:11]
	s_setprio 0
	s_barrier
	s_add_u32 s56, s56, 0x40080
	s_addc_u32 s57, s57, 0
	s_add_i32 s58, s58, s34
	v_lshl_add_u64 v[146:147], s[56:57], 0, v[130:131]
	s_mov_b32 m0, s58
	s_nop 0
	global_load_lds_dwordx4 v[146:147], off
	v_lshl_add_u64 v[146:147], s[56:57], 0, v[134:135]
	s_add_i32 m0, s58, 0x2000
	s_nop 0
	global_load_lds_dwordx4 v[146:147], off
	s_waitcnt vmcnt(6)
	s_cmp_gt_u32 s71, 10
	s_cbranch_scc1 .Lds_P6_b_done
	s_cmp_lt_u32 s71, 6
	s_cbranch_scc1 .Lds_P6_b_st
	s_cmp_eq_u32 s71, 6
	s_cbranch_scc1 .Lds_P6_b_done
	s_cmp_eq_u32 s71, 8
	s_cbranch_scc1 .Lds_P6_b_c8
	v_ffbh_u32_e32 v254, v245
	v_min_u32_e32 v254, 32, v254
	v_lshlrev_b64 v[244:245], v254, v[244:245]
	v_min_u32_e32 v244, 1, v244
	v_or_b32_e32 v245, v245, v244
	v_cvt_f32_u32_e32 v245, v245
	v_sub_u32_e32 v254, -2, v254
	v_ldexp_f32 v245, v245, v254
	v_add_f32_e32 v245, 0x358637bd, v245
	v_rsq_f32_e32 v254, v245
	v_ffbh_u32_e32 v255, v247
	v_min_u32_e32 v255, 32, v255
	v_lshlrev_b64 v[246:247], v255, v[246:247]
	v_min_u32_e32 v246, 1, v246
	v_or_b32_e32 v247, v247, v246
	v_cvt_f32_u32_e32 v247, v247
	v_sub_u32_e32 v255, -2, v255
	v_ldexp_f32 v247, v247, v255
	v_add_f32_e32 v247, 0x358637bd, v247
	v_rsq_f32_e32 v255, v247
	s_branch .Lds_P6_b_done

.Lds_P6_b_st:
	s_cmp_eq_u32 s32, 0
	s_cbranch_scc1 .Lds_P6_b_done
	s_cmp_eq_u32 s71, 0
	s_cbranch_scc1 .Lds_P6_b_0
	s_cmp_eq_u32 s71, 2
	s_cbranch_scc1 .Lds_P6_b_1
	s_add_u32 s100, s98, 0x160000
	s_addc_u32 s101, s99, 0
	global_store_dwordx4 v239, v[252:255], s[100:101] offset:256
	s_branch .Lds_P6_b_done

.Lepi_P6_start:
	s_mul_i32 s82, s10, 0x200000
	s_lshl_b32 s84, s67, 9
	s_add_u32 s82, s82, s84
	s_add_u32 s84, s16, s82
	s_addc_u32 s85, s17, 0
	v_pk_mul_f32 v[124:125], v[124:125], v[248:249] op_sel_hi:[1,0]
	v_pk_mul_f32 v[126:127], v[126:127], v[248:249] op_sel_hi:[1,0]
	v_pk_mul_f32 v[120:121], v[120:121], v[248:249] op_sel_hi:[1,0]
	v_pk_mul_f32 v[122:123], v[122:123], v[248:249] op_sel_hi:[1,0]
	v_max_f32_e32 v124, 0, v124
	v_max_f32_e32 v125, 0, v125
	v_max_f32_e32 v126, 0, v126
	v_max_f32_e32 v127, 0, v127
	v_max_f32_e32 v120, 0, v120
	v_max_f32_e32 v121, 0, v121
	v_max_f32_e32 v122, 0, v122
	v_max_f32_e32 v123, 0, v123
	v_pk_mul_f32 v[124:125], v[124:125], v[124:125]
	v_pk_mul_f32 v[126:127], v[126:127], v[126:127]
	v_pk_mul_f32 v[120:121], v[120:121], v[120:121]
	v_pk_mul_f32 v[122:123], v[122:123], v[122:123]
	v_cvt_pk_bf16_f32 v124, v124, v125
	v_cvt_pk_bf16_f32 v125, v126, v127
	v_cvt_pk_bf16_f32 v126, v120, v121
	v_cvt_pk_bf16_f32 v127, v122, v123
	global_store_dwordx4 v239, v[124:127], s[84:85]
	v_pk_mul_f32 v[116:117], v[116:117], v[248:249] op_sel_hi:[1,0]
	v_pk_mul_f32 v[118:119], v[118:119], v[248:249] op_sel_hi:[1,0]
	v_pk_mul_f32 v[112:113], v[112:113], v[248:249] op_sel_hi:[1,0]
	v_pk_mul_f32 v[114:115], v[114:115], v[248:249] op_sel_hi:[1,0]
	v_max_f32_e32 v116, 0, v116
	v_max_f32_e32 v117, 0, v117
	v_max_f32_e32 v118, 0, v118
	v_max_f32_e32 v119, 0, v119
	v_max_f32_e32 v112, 0, v112
	v_max_f32_e32 v113, 0, v113
	v_max_f32_e32 v114, 0, v114
	v_max_f32_e32 v115, 0, v115
	v_pk_mul_f32 v[116:117], v[116:117], v[116:117]
	v_pk_mul_f32 v[118:119], v[118:119], v[118:119]
	v_pk_mul_f32 v[112:113], v[112:113], v[112:113]
	v_pk_mul_f32 v[114:115], v[114:115], v[114:115]
	v_cvt_pk_bf16_f32 v116, v116, v117
	v_cvt_pk_bf16_f32 v117, v118, v119
	v_cvt_pk_bf16_f32 v118, v112, v113
	v_cvt_pk_bf16_f32 v119, v114, v115
	global_store_dwordx4 v239, v[116:119], s[84:85] offset:256
	v_pk_mul_f32 v[108:109], v[108:109], v[248:249] op_sel:[0,1] op_sel_hi:[1,1]
	v_pk_mul_f32 v[110:111], v[110:111], v[248:249] op_sel:[0,1] op_sel_hi:[1,1]
	v_pk_mul_f32 v[104:105], v[104:105], v[248:249] op_sel:[0,1] op_sel_hi:[1,1]
	v_pk_mul_f32 v[106:107], v[106:107], v[248:249] op_sel:[0,1] op_sel_hi:[1,1]
	v_max_f32_e32 v108, 0, v108
	v_max_f32_e32 v109, 0, v109
	v_max_f32_e32 v110, 0, v110
	v_max_f32_e32 v111, 0, v111
	v_max_f32_e32 v104, 0, v104
	v_max_f32_e32 v105, 0, v105
	v_max_f32_e32 v106, 0, v106
	v_max_f32_e32 v107, 0, v107
	v_pk_mul_f32 v[108:109], v[108:109], v[108:109]
	v_pk_mul_f32 v[110:111], v[110:111], v[110:111]
	v_pk_mul_f32 v[104:105], v[104:105], v[104:105]
	v_pk_mul_f32 v[106:107], v[106:107], v[106:107]
	v_cvt_pk_bf16_f32 v108, v108, v109
	v_cvt_pk_bf16_f32 v109, v110, v111
	v_cvt_pk_bf16_f32 v110, v104, v105
	v_cvt_pk_bf16_f32 v111, v106, v107
	s_add_u32 s100, s84, 0x20000
	s_addc_u32 s101, s85, 0
	global_store_dwordx4 v239, v[108:111], s[100:101]
	v_pk_mul_f32 v[100:101], v[100:101], v[248:249] op_sel:[0,1] op_sel_hi:[1,1]
	v_pk_mul_f32 v[102:103], v[102:103], v[248:249] op_sel:[0,1] op_sel_hi:[1,1]
	v_pk_mul_f32 v[96:97], v[96:97], v[248:249] op_sel:[0,1] op_sel_hi:[1,1]
	v_pk_mul_f32 v[98:99], v[98:99], v[248:249] op_sel:[0,1] op_sel_hi:[1,1]
	v_max_f32_e32 v100, 0, v100
	v_max_f32_e32 v101, 0, v101
	v_max_f32_e32 v102, 0, v102
	v_max_f32_e32 v103, 0, v103
	v_max_f32_e32 v96, 0, v96
	v_max_f32_e32 v97, 0, v97
	v_max_f32_e32 v98, 0, v98
	v_max_f32_e32 v99, 0, v99
	v_pk_mul_f32 v[100:101], v[100:101], v[100:101]
	v_pk_mul_f32 v[102:103], v[102:103], v[102:103]
	v_pk_mul_f32 v[96:97], v[96:97], v[96:97]
	v_pk_mul_f32 v[98:99], v[98:99], v[98:99]
	v_cvt_pk_bf16_f32 v100, v100, v101
	v_cvt_pk_bf16_f32 v101, v102, v103
	v_cvt_pk_bf16_f32 v102, v96, v97
	v_cvt_pk_bf16_f32 v103, v98, v99
	s_add_u32 s100, s84, 0x20000
	s_addc_u32 s101, s85, 0
	global_store_dwordx4 v239, v[100:103], s[100:101] offset:256
	v_pk_mul_f32 v[92:93], v[92:93], v[250:251] op_sel_hi:[1,0]
	v_pk_mul_f32 v[94:95], v[94:95], v[250:251] op_sel_hi:[1,0]
	v_pk_mul_f32 v[88:89], v[88:89], v[250:251] op_sel_hi:[1,0]
	v_pk_mul_f32 v[90:91], v[90:91], v[250:251] op_sel_hi:[1,0]
	v_max_f32_e32 v92, 0, v92
	v_max_f32_e32 v93, 0, v93
	v_max_f32_e32 v94, 0, v94
	v_max_f32_e32 v95, 0, v95
	v_max_f32_e32 v88, 0, v88
	v_max_f32_e32 v89, 0, v89
	v_max_f32_e32 v90, 0, v90
	v_max_f32_e32 v91, 0, v91
	v_pk_mul_f32 v[92:93], v[92:93], v[92:93]
	v_pk_mul_f32 v[94:95], v[94:95], v[94:95]
	v_pk_mul_f32 v[88:89], v[88:89], v[88:89]
	v_pk_mul_f32 v[90:91], v[90:91], v[90:91]
	v_cvt_pk_bf16_f32 v92, v92, v93
	v_cvt_pk_bf16_f32 v93, v94, v95
	v_cvt_pk_bf16_f32 v94, v88, v89
	v_cvt_pk_bf16_f32 v95, v90, v91
	s_add_u32 s100, s84, 0x40000
	s_addc_u32 s101, s85, 0
	global_store_dwordx4 v239, v[92:95], s[100:101]
	v_pk_mul_f32 v[84:85], v[84:85], v[250:251] op_sel_hi:[1,0]
	v_pk_mul_f32 v[86:87], v[86:87], v[250:251] op_sel_hi:[1,0]
	v_pk_mul_f32 v[80:81], v[80:81], v[250:251] op_sel_hi:[1,0]
	v_pk_mul_f32 v[82:83], v[82:83], v[250:251] op_sel_hi:[1,0]
	v_max_f32_e32 v84, 0, v84
	v_max_f32_e32 v85, 0, v85
	v_max_f32_e32 v86, 0, v86
	v_max_f32_e32 v87, 0, v87
	v_max_f32_e32 v80, 0, v80
	v_max_f32_e32 v81, 0, v81
	v_max_f32_e32 v82, 0, v82
	v_max_f32_e32 v83, 0, v83
	v_pk_mul_f32 v[84:85], v[84:85], v[84:85]
	v_pk_mul_f32 v[86:87], v[86:87], v[86:87]
	v_pk_mul_f32 v[80:81], v[80:81], v[80:81]
	v_pk_mul_f32 v[82:83], v[82:83], v[82:83]
	v_cvt_pk_bf16_f32 v84, v84, v85
	v_cvt_pk_bf16_f32 v85, v86, v87
	v_cvt_pk_bf16_f32 v86, v80, v81
	v_cvt_pk_bf16_f32 v87, v82, v83
	s_add_u32 s100, s84, 0x40000
	s_addc_u32 s101, s85, 0
	global_store_dwordx4 v239, v[84:87], s[100:101] offset:256
	v_pk_mul_f32 v[76:77], v[76:77], v[250:251] op_sel:[0,1] op_sel_hi:[1,1]
	v_pk_mul_f32 v[78:79], v[78:79], v[250:251] op_sel:[0,1] op_sel_hi:[1,1]
	v_pk_mul_f32 v[72:73], v[72:73], v[250:251] op_sel:[0,1] op_sel_hi:[1,1]
	v_pk_mul_f32 v[74:75], v[74:75], v[250:251] op_sel:[0,1] op_sel_hi:[1,1]
	v_max_f32_e32 v76, 0, v76
	v_max_f32_e32 v77, 0, v77
	v_max_f32_e32 v78, 0, v78
	v_max_f32_e32 v79, 0, v79
	v_max_f32_e32 v72, 0, v72
	v_max_f32_e32 v73, 0, v73
	v_max_f32_e32 v74, 0, v74
	v_max_f32_e32 v75, 0, v75
	v_pk_mul_f32 v[76:77], v[76:77], v[76:77]
	v_pk_mul_f32 v[78:79], v[78:79], v[78:79]
	v_pk_mul_f32 v[72:73], v[72:73], v[72:73]
	v_pk_mul_f32 v[74:75], v[74:75], v[74:75]
	v_cvt_pk_bf16_f32 v76, v76, v77
	v_cvt_pk_bf16_f32 v77, v78, v79
	v_cvt_pk_bf16_f32 v78, v72, v73
	v_cvt_pk_bf16_f32 v79, v74, v75
	s_add_u32 s100, s84, 0x60000
	s_addc_u32 s101, s85, 0
	global_store_dwordx4 v239, v[76:79], s[100:101]
	v_pk_mul_f32 v[68:69], v[68:69], v[250:251] op_sel:[0,1] op_sel_hi:[1,1]
	v_pk_mul_f32 v[70:71], v[70:71], v[250:251] op_sel:[0,1] op_sel_hi:[1,1]
	v_pk_mul_f32 v[64:65], v[64:65], v[250:251] op_sel:[0,1] op_sel_hi:[1,1]
	v_pk_mul_f32 v[66:67], v[66:67], v[250:251] op_sel:[0,1] op_sel_hi:[1,1]
	v_max_f32_e32 v68, 0, v68
	v_max_f32_e32 v69, 0, v69
	v_max_f32_e32 v70, 0, v70
	v_max_f32_e32 v71, 0, v71
	v_max_f32_e32 v64, 0, v64
	v_max_f32_e32 v65, 0, v65
	v_max_f32_e32 v66, 0, v66
	v_max_f32_e32 v67, 0, v67
	v_pk_mul_f32 v[68:69], v[68:69], v[68:69]
	v_pk_mul_f32 v[70:71], v[70:71], v[70:71]
	v_pk_mul_f32 v[64:65], v[64:65], v[64:65]
	v_pk_mul_f32 v[66:67], v[66:67], v[66:67]
	v_cvt_pk_bf16_f32 v68, v68, v69
	v_cvt_pk_bf16_f32 v69, v70, v71
	v_cvt_pk_bf16_f32 v70, v64, v65
	v_cvt_pk_bf16_f32 v71, v66, v67
	s_add_u32 s100, s84, 0x60000
	s_addc_u32 s101, s85, 0
	global_store_dwordx4 v239, v[68:71], s[100:101] offset:256
	v_pk_mul_f32 v[60:61], v[60:61], v[252:253] op_sel_hi:[1,0]
	v_pk_mul_f32 v[62:63], v[62:63], v[252:253] op_sel_hi:[1,0]
	v_pk_mul_f32 v[56:57], v[56:57], v[252:253] op_sel_hi:[1,0]
	v_pk_mul_f32 v[58:59], v[58:59], v[252:253] op_sel_hi:[1,0]
	v_max_f32_e32 v60, 0, v60
	v_max_f32_e32 v61, 0, v61
	v_max_f32_e32 v62, 0, v62
	v_max_f32_e32 v63, 0, v63
	v_max_f32_e32 v56, 0, v56
	v_max_f32_e32 v57, 0, v57
	v_max_f32_e32 v58, 0, v58
	v_max_f32_e32 v59, 0, v59
	v_pk_mul_f32 v[60:61], v[60:61], v[60:61]
	v_pk_mul_f32 v[62:63], v[62:63], v[62:63]
	v_pk_mul_f32 v[56:57], v[56:57], v[56:57]
	v_pk_mul_f32 v[58:59], v[58:59], v[58:59]
	v_cvt_pk_bf16_f32 v60, v60, v61
	v_cvt_pk_bf16_f32 v61, v62, v63
	v_cvt_pk_bf16_f32 v62, v56, v57
	v_cvt_pk_bf16_f32 v63, v58, v59
	s_add_u32 s100, s84, 0x100000
	s_addc_u32 s101, s85, 0
	global_store_dwordx4 v239, v[60:63], s[100:101]
	v_pk_mul_f32 v[52:53], v[52:53], v[252:253] op_sel_hi:[1,0]
	v_pk_mul_f32 v[54:55], v[54:55], v[252:253] op_sel_hi:[1,0]
	v_pk_mul_f32 v[48:49], v[48:49], v[252:253] op_sel_hi:[1,0]
	v_pk_mul_f32 v[50:51], v[50:51], v[252:253] op_sel_hi:[1,0]
	v_max_f32_e32 v52, 0, v52
	v_max_f32_e32 v53, 0, v53
	v_max_f32_e32 v54, 0, v54
	v_max_f32_e32 v55, 0, v55
	v_max_f32_e32 v48, 0, v48
	v_max_f32_e32 v49, 0, v49
	v_max_f32_e32 v50, 0, v50
	v_max_f32_e32 v51, 0, v51
	v_pk_mul_f32 v[52:53], v[52:53], v[52:53]
	v_pk_mul_f32 v[54:55], v[54:55], v[54:55]
	v_pk_mul_f32 v[48:49], v[48:49], v[48:49]
	v_pk_mul_f32 v[50:51], v[50:51], v[50:51]
	v_cvt_pk_bf16_f32 v52, v52, v53
	v_cvt_pk_bf16_f32 v53, v54, v55
	v_cvt_pk_bf16_f32 v54, v48, v49
	v_cvt_pk_bf16_f32 v55, v50, v51
	s_add_u32 s100, s84, 0x100000
	s_addc_u32 s101, s85, 0
	global_store_dwordx4 v239, v[52:55], s[100:101] offset:256
	v_pk_mul_f32 v[44:45], v[44:45], v[252:253] op_sel:[0,1] op_sel_hi:[1,1]
	v_pk_mul_f32 v[46:47], v[46:47], v[252:253] op_sel:[0,1] op_sel_hi:[1,1]
	v_pk_mul_f32 v[40:41], v[40:41], v[252:253] op_sel:[0,1] op_sel_hi:[1,1]
	v_pk_mul_f32 v[42:43], v[42:43], v[252:253] op_sel:[0,1] op_sel_hi:[1,1]
	v_max_f32_e32 v44, 0, v44
	v_max_f32_e32 v45, 0, v45
	v_max_f32_e32 v46, 0, v46
	v_max_f32_e32 v47, 0, v47
	v_max_f32_e32 v40, 0, v40
	v_max_f32_e32 v41, 0, v41
	v_max_f32_e32 v42, 0, v42
	v_max_f32_e32 v43, 0, v43
	v_pk_mul_f32 v[44:45], v[44:45], v[44:45]
	v_pk_mul_f32 v[46:47], v[46:47], v[46:47]
	v_pk_mul_f32 v[40:41], v[40:41], v[40:41]
	v_pk_mul_f32 v[42:43], v[42:43], v[42:43]
	v_cvt_pk_bf16_f32 v230, v44, v45
	v_cvt_pk_bf16_f32 v231, v46, v47
	v_cvt_pk_bf16_f32 v232, v40, v41
	v_cvt_pk_bf16_f32 v233, v42, v43
	v_pk_mul_f32 v[36:37], v[36:37], v[252:253] op_sel:[0,1] op_sel_hi:[1,1]
	v_pk_mul_f32 v[38:39], v[38:39], v[252:253] op_sel:[0,1] op_sel_hi:[1,1]
	v_pk_mul_f32 v[32:33], v[32:33], v[252:253] op_sel:[0,1] op_sel_hi:[1,1]
	v_pk_mul_f32 v[34:35], v[34:35], v[252:253] op_sel:[0,1] op_sel_hi:[1,1]
	v_max_f32_e32 v36, 0, v36
	v_max_f32_e32 v37, 0, v37
	v_max_f32_e32 v38, 0, v38
	v_max_f32_e32 v39, 0, v39
	v_max_f32_e32 v32, 0, v32
	v_max_f32_e32 v33, 0, v33
	v_max_f32_e32 v34, 0, v34
	v_max_f32_e32 v35, 0, v35
	v_pk_mul_f32 v[36:37], v[36:37], v[36:37]
	v_pk_mul_f32 v[38:39], v[38:39], v[38:39]
	v_pk_mul_f32 v[32:33], v[32:33], v[32:33]
	v_pk_mul_f32 v[34:35], v[34:35], v[34:35]
	v_cvt_pk_bf16_f32 v234, v36, v37
	v_cvt_pk_bf16_f32 v235, v38, v39
	v_cvt_pk_bf16_f32 v236, v32, v33
	v_cvt_pk_bf16_f32 v237, v34, v35
	v_pk_mul_f32 v[28:29], v[28:29], v[254:255] op_sel_hi:[1,0]
	v_pk_mul_f32 v[30:31], v[30:31], v[254:255] op_sel_hi:[1,0]
	v_pk_mul_f32 v[24:25], v[24:25], v[254:255] op_sel_hi:[1,0]
	v_pk_mul_f32 v[26:27], v[26:27], v[254:255] op_sel_hi:[1,0]
	v_max_f32_e32 v28, 0, v28
	v_max_f32_e32 v29, 0, v29
	v_max_f32_e32 v30, 0, v30
	v_max_f32_e32 v31, 0, v31
	v_max_f32_e32 v24, 0, v24
	v_max_f32_e32 v25, 0, v25
	v_max_f32_e32 v26, 0, v26
	v_max_f32_e32 v27, 0, v27
	v_pk_mul_f32 v[28:29], v[28:29], v[28:29]
	v_pk_mul_f32 v[30:31], v[30:31], v[30:31]
	v_pk_mul_f32 v[24:25], v[24:25], v[24:25]
	v_pk_mul_f32 v[26:27], v[26:27], v[26:27]
	v_cvt_pk_bf16_f32 v240, v28, v29
	v_cvt_pk_bf16_f32 v241, v30, v31
	v_cvt_pk_bf16_f32 v242, v24, v25
	v_cvt_pk_bf16_f32 v243, v26, v27
	v_pk_mul_f32 v[20:21], v[20:21], v[254:255] op_sel_hi:[1,0]
	v_pk_mul_f32 v[22:23], v[22:23], v[254:255] op_sel_hi:[1,0]
	v_pk_mul_f32 v[16:17], v[16:17], v[254:255] op_sel_hi:[1,0]
	v_pk_mul_f32 v[18:19], v[18:19], v[254:255] op_sel_hi:[1,0]
	v_max_f32_e32 v20, 0, v20
	v_max_f32_e32 v21, 0, v21
	v_max_f32_e32 v22, 0, v22
	v_max_f32_e32 v23, 0, v23
	v_max_f32_e32 v16, 0, v16
	v_max_f32_e32 v17, 0, v17
	v_max_f32_e32 v18, 0, v18
	v_max_f32_e32 v19, 0, v19
	v_pk_mul_f32 v[20:21], v[20:21], v[20:21]
	v_pk_mul_f32 v[22:23], v[22:23], v[22:23]
	v_pk_mul_f32 v[16:17], v[16:17], v[16:17]
	v_pk_mul_f32 v[18:19], v[18:19], v[18:19]
	v_cvt_pk_bf16_f32 v244, v20, v21
	v_cvt_pk_bf16_f32 v245, v22, v23
	v_cvt_pk_bf16_f32 v246, v16, v17
	v_cvt_pk_bf16_f32 v247, v18, v19
	v_pk_mul_f32 v[12:13], v[12:13], v[254:255] op_sel:[0,1] op_sel_hi:[1,1]
	v_pk_mul_f32 v[14:15], v[14:15], v[254:255] op_sel:[0,1] op_sel_hi:[1,1]
	v_pk_mul_f32 v[8:9], v[8:9], v[254:255] op_sel:[0,1] op_sel_hi:[1,1]
	v_pk_mul_f32 v[10:11], v[10:11], v[254:255] op_sel:[0,1] op_sel_hi:[1,1]
	v_max_f32_e32 v12, 0, v12
	v_max_f32_e32 v13, 0, v13
	v_max_f32_e32 v14, 0, v14
	v_max_f32_e32 v15, 0, v15
	v_max_f32_e32 v8, 0, v8
	v_max_f32_e32 v9, 0, v9
	v_max_f32_e32 v10, 0, v10
	v_max_f32_e32 v11, 0, v11
	v_pk_mul_f32 v[12:13], v[12:13], v[12:13]
	v_pk_mul_f32 v[14:15], v[14:15], v[14:15]
	v_pk_mul_f32 v[8:9], v[8:9], v[8:9]
	v_pk_mul_f32 v[10:11], v[10:11], v[10:11]
	v_cvt_pk_bf16_f32 v248, v12, v13
	v_cvt_pk_bf16_f32 v249, v14, v15
	v_cvt_pk_bf16_f32 v250, v8, v9
	v_cvt_pk_bf16_f32 v251, v10, v11
	v_pk_mul_f32 v[4:5], v[4:5], v[254:255] op_sel:[0,1] op_sel_hi:[1,1]
	v_pk_mul_f32 v[6:7], v[6:7], v[254:255] op_sel:[0,1] op_sel_hi:[1,1]
	v_pk_mul_f32 v[0:1], v[0:1], v[254:255] op_sel:[0,1] op_sel_hi:[1,1]
	v_pk_mul_f32 v[2:3], v[2:3], v[254:255] op_sel:[0,1] op_sel_hi:[1,1]
	v_max_f32_e32 v4, 0, v4
	v_max_f32_e32 v5, 0, v5
	v_max_f32_e32 v6, 0, v6
	v_max_f32_e32 v7, 0, v7
	v_max_f32_e32 v0, 0, v0
	v_max_f32_e32 v1, 0, v1
	v_max_f32_e32 v2, 0, v2
	v_max_f32_e32 v3, 0, v3
	v_pk_mul_f32 v[4:5], v[4:5], v[4:5]
	v_pk_mul_f32 v[6:7], v[6:7], v[6:7]
	v_pk_mul_f32 v[0:1], v[0:1], v[0:1]
	v_pk_mul_f32 v[2:3], v[2:3], v[2:3]
	v_cvt_pk_bf16_f32 v252, v4, v5
	v_cvt_pk_bf16_f32 v253, v6, v7
	v_cvt_pk_bf16_f32 v254, v0, v1
	v_cvt_pk_bf16_f32 v255, v2, v3
	s_mov_b64 s[56:57], s[54:55]
	s_and_b64 vcc, exec, s[8:9]
	s_mov_b32 s67, s38
	s_mov_b32 s10, s50
	s_mov_b64 s[12:13], s[52:53]
	s_mov_b64 s[98:99], s[84:85]
	s_mov_b32 s32, 1
	s_cbranch_vccz .LBB0_980
	s_add_u32 s100, s84, 0x120000
	s_addc_u32 s101, s85, 0
	global_store_dwordx4 v239, v[230:233], s[100:101]
	s_add_u32 s100, s84, 0x120000
	s_addc_u32 s101, s85, 0
	global_store_dwordx4 v239, v[234:237], s[100:101] offset:256
	s_add_u32 s100, s84, 0x140000
	s_addc_u32 s101, s85, 0
	global_store_dwordx4 v239, v[240:243], s[100:101]
	s_add_u32 s100, s84, 0x140000
	s_addc_u32 s101, s85, 0
	global_store_dwordx4 v239, v[244:247], s[100:101] offset:256
	s_add_u32 s100, s84, 0x160000
	s_addc_u32 s101, s85, 0
	global_store_dwordx4 v239, v[248:251], s[100:101]
	s_add_u32 s100, s84, 0x160000
	s_addc_u32 s101, s85, 0
	global_store_dwordx4 v239, v[252:255], s[100:101] offset:256
	s_waitcnt vmcnt(0)
	s_cmpk_gt_u32 s0, 0xff
	s_cbranch_scc1 .LBB0_991
	s_barrier

.LBB0_1141:
	ds_read_b128 v[144:147], v159
	ds_read_b128 v[150:153], v159 offset:1024
	ds_read_b128 v[164:167], v159 offset:2048
	ds_read_b128 v[168:171], v159 offset:3072
	s_add_u32 s66, s12, 0xfffc0080
	s_addc_u32 s67, s13, -1
	s_cmp_eq_u32 s77, 12
	s_cselect_b32 s69, s11, s67
	s_cselect_b32 s68, s61, s66
	s_cselect_b32 s67, s59, s76
	s_cselect_b32 s66, s74, s75
	v_lshl_add_u64 v[154:155], s[12:13], 0, v[136:137]
	s_add_i32 m0, s34, 0xc000
	ds_read_b128 v[172:175], v160
	ds_read_b128 v[176:179], v160 offset:1024
	ds_read_b128 v[180:183], v160 offset:2048
	ds_read_b128 v[184:187], v160 offset:3072
	ds_read_b128 v[188:191], v160 offset:4096
	ds_read_b128 v[192:195], v160 offset:5120
	ds_read_b128 v[196:199], v160 offset:6144
	ds_read_b128 v[200:203], v160 offset:7168
	global_load_lds_dwordx4 v[154:155], off
	v_lshl_add_u64 v[154:155], s[12:13], 0, v[138:139]
	s_add_i32 m0, s34, 0xe000
	s_nop 0
	global_load_lds_dwordx4 v[154:155], off
	s_waitcnt lgkmcnt(8)
	s_barrier
	s_waitcnt lgkmcnt(0)
	s_setprio 1
	s_waitcnt lgkmcnt(0)
	v_mfma_f32_16x16x32_bf16 v[124:127], v[144:147], v[172:175], v[124:127]
	v_mfma_f32_16x16x32_bf16 v[120:123], v[164:167], v[172:175], v[120:123]
	v_mfma_f32_16x16x32_bf16 v[116:119], v[144:147], v[180:183], v[116:119]
	v_mfma_f32_16x16x32_bf16 v[108:111], v[164:167], v[180:183], v[108:111]
	v_mfma_f32_16x16x32_bf16 v[100:103], v[144:147], v[188:191], v[100:103]
	v_mfma_f32_16x16x32_bf16 v[92:95], v[164:167], v[188:191], v[92:95]
	v_mfma_f32_16x16x32_bf16 v[84:87], v[144:147], v[196:199], v[84:87]
	v_mfma_f32_16x16x32_bf16 v[76:79], v[164:167], v[196:199], v[76:79]
	v_mfma_f32_16x16x32_bf16 v[124:127], v[150:153], v[176:179], v[124:127]
	v_mfma_f32_16x16x32_bf16 v[120:123], v[168:171], v[176:179], v[120:123]
	v_mfma_f32_16x16x32_bf16 v[116:119], v[150:153], v[184:187], v[116:119]
	v_mfma_f32_16x16x32_bf16 v[108:111], v[168:171], v[184:187], v[108:111]
	v_mfma_f32_16x16x32_bf16 v[100:103], v[150:153], v[192:195], v[100:103]
	v_mfma_f32_16x16x32_bf16 v[92:95], v[168:171], v[192:195], v[92:95]
	v_mfma_f32_16x16x32_bf16 v[84:87], v[150:153], v[200:203], v[84:87]
	v_mfma_f32_16x16x32_bf16 v[76:79], v[168:171], v[200:203], v[76:79]
	s_setprio 0
	s_barrier
	s_add_i32 s78, s49, s20
	v_lshl_add_u64 v[154:155], s[66:67], 0, v[132:133]
	s_mov_b32 m0, s78
	ds_read_b128 v[206:209], v161
	ds_read_b128 v[210:213], v161 offset:1024
	ds_read_b128 v[214:217], v161 offset:2048
	ds_read_b128 v[218:221], v161 offset:3072
	global_load_lds_dwordx4 v[154:155], off
	v_lshl_add_u64 v[222:223], s[66:67], 0, v[128:129]
	s_add_i32 m0, s78, 0x2000
	s_nop 0
	global_load_lds_dwordx4 v[222:223], off
	s_barrier
	s_waitcnt lgkmcnt(0)
	s_setprio 1
	s_waitcnt lgkmcnt(0)
	v_mfma_f32_16x16x32_bf16 v[112:115], v[206:209], v[172:175], v[112:115]
	v_mfma_f32_16x16x32_bf16 v[104:107], v[214:217], v[172:175], v[104:107]
	v_mfma_f32_16x16x32_bf16 v[96:99], v[206:209], v[180:183], v[96:99]
	v_mfma_f32_16x16x32_bf16 v[88:91], v[214:217], v[180:183], v[88:91]
	v_mfma_f32_16x16x32_bf16 v[80:83], v[206:209], v[188:191], v[80:83]
	v_mfma_f32_16x16x32_bf16 v[72:75], v[214:217], v[188:191], v[72:75]
	v_mfma_f32_16x16x32_bf16 v[68:71], v[206:209], v[196:199], v[68:71]
	v_mfma_f32_16x16x32_bf16 v[64:67], v[214:217], v[196:199], v[64:67]
	v_mfma_f32_16x16x32_bf16 v[112:115], v[210:213], v[176:179], v[112:115]
	v_mfma_f32_16x16x32_bf16 v[104:107], v[218:221], v[176:179], v[104:107]
	v_mfma_f32_16x16x32_bf16 v[96:99], v[210:213], v[184:187], v[96:99]
	v_mfma_f32_16x16x32_bf16 v[88:91], v[218:221], v[184:187], v[88:91]
	v_mfma_f32_16x16x32_bf16 v[80:83], v[210:213], v[192:195], v[80:83]
	v_mfma_f32_16x16x32_bf16 v[72:75], v[218:221], v[192:195], v[72:75]
	v_mfma_f32_16x16x32_bf16 v[68:71], v[210:213], v[200:203], v[68:71]
	v_mfma_f32_16x16x32_bf16 v[64:67], v[218:221], v[200:203], v[64:67]
	s_setprio 0
	s_mov_b32 m0, s34
	v_lshl_add_u64 v[224:225], s[68:69], 0, v[134:135]
	s_barrier
	ds_read_b128 v[172:175], v160 offset:16384
	ds_read_b128 v[176:179], v160 offset:17408
	ds_read_b128 v[180:183], v160 offset:18432
	ds_read_b128 v[184:187], v160 offset:19456
	ds_read_b128 v[188:191], v160 offset:20480
	ds_read_b128 v[192:195], v160 offset:21504
	ds_read_b128 v[196:199], v160 offset:22528
	ds_read_b128 v[200:203], v160 offset:23552
	global_load_lds_dwordx4 v[224:225], off
	v_lshl_add_u64 v[226:227], s[68:69], 0, v[130:131]
	s_mov_b32 m0, s35
	s_nop 0
	global_load_lds_dwordx4 v[226:227], off
	s_barrier
	s_waitcnt lgkmcnt(0)
	s_setprio 1
	s_waitcnt lgkmcnt(0)
	v_mfma_f32_16x16x32_bf16 v[60:63], v[144:147], v[172:175], v[60:63]
	v_mfma_f32_16x16x32_bf16 v[56:59], v[164:167], v[172:175], v[56:59]
	v_mfma_f32_16x16x32_bf16 v[52:55], v[144:147], v[180:183], v[52:55]
	v_mfma_f32_16x16x32_bf16 v[44:47], v[164:167], v[180:183], v[44:47]
	v_mfma_f32_16x16x32_bf16 v[36:39], v[144:147], v[188:191], v[36:39]
	v_mfma_f32_16x16x32_bf16 v[28:31], v[164:167], v[188:191], v[28:31]
	v_mfma_f32_16x16x32_bf16 v[20:23], v[144:147], v[196:199], v[20:23]
	v_mfma_f32_16x16x32_bf16 v[12:15], v[164:167], v[196:199], v[12:15]
	v_mfma_f32_16x16x32_bf16 v[60:63], v[150:153], v[176:179], v[60:63]
	v_mfma_f32_16x16x32_bf16 v[56:59], v[168:171], v[176:179], v[56:59]
	v_mfma_f32_16x16x32_bf16 v[52:55], v[150:153], v[184:187], v[52:55]
	v_mfma_f32_16x16x32_bf16 v[44:47], v[168:171], v[184:187], v[44:47]
	v_mfma_f32_16x16x32_bf16 v[36:39], v[150:153], v[192:195], v[36:39]
	v_mfma_f32_16x16x32_bf16 v[28:31], v[168:171], v[192:195], v[28:31]
	v_mfma_f32_16x16x32_bf16 v[20:23], v[150:153], v[200:203], v[20:23]
	v_mfma_f32_16x16x32_bf16 v[12:15], v[168:171], v[200:203], v[12:15]
	s_setprio 0
	s_barrier
	s_add_u32 s78, s66, 0x40000
	s_addc_u32 s79, s67, 0
	s_add_i32 s80, s70, s20
	v_lshl_add_u64 v[144:145], s[78:79], 0, v[132:133]
	s_mov_b32 m0, s80
	s_nop 0
	global_load_lds_dwordx4 v[144:145], off
	v_lshl_add_u64 v[144:145], s[78:79], 0, v[128:129]
	s_add_i32 m0, s80, 0x2000
	s_nop 0
	global_load_lds_dwordx4 v[144:145], off
	s_waitcnt vmcnt(6)
	s_cmp_gt_u32 s77, 10
	s_cbranch_scc1 .Lds_P8_a_done
	s_cmp_lt_u32 s77, 6
	s_cbranch_scc1 .Lds_P8_a_st
	s_cmp_eq_u32 s77, 6
	s_cbranch_scc1 .Lds_P8_a_pf
	s_cmp_eq_u32 s77, 8
	s_cbranch_scc1 .Lds_P8_a_c8
	v_ffbh_u32_e32 v252, v241
	v_min_u32_e32 v252, 32, v252
	v_lshlrev_b64 v[240:241], v252, v[240:241]
	v_min_u32_e32 v240, 1, v240
	v_or_b32_e32 v241, v241, v240
	v_cvt_f32_u32_e32 v241, v241
	v_sub_u32_e32 v252, -2, v252
	v_ldexp_f32 v241, v241, v252
	v_add_f32_e32 v241, 0x358637bd, v241
	v_rsq_f32_e32 v252, v241
	v_ffbh_u32_e32 v253, v243
	v_min_u32_e32 v253, 32, v253
	v_lshlrev_b64 v[242:243], v253, v[242:243]
	v_min_u32_e32 v242, 1, v242
	v_or_b32_e32 v243, v243, v242
	v_cvt_f32_u32_e32 v243, v243
	v_sub_u32_e32 v253, -2, v253
	v_ldexp_f32 v243, v243, v253
	v_add_f32_e32 v243, 0x358637bd, v243
	v_rsq_f32_e32 v253, v243
	s_branch .Lds_P8_a_done

.Lds_P8_a_pf:
	s_lshl_b32 s82, s10, 11
	s_add_u32 s100, s54, s82
	s_addc_u32 s101, s55, 0
	v_lshlrev_b32_e32 v252, 3, v149
	global_load_dwordx2 v[230:231], v252, s[100:101]
	global_load_dwordx2 v[232:233], v252, s[100:101] offset:128
	global_load_dwordx2 v[234:235], v252, s[100:101] offset:256
	global_load_dwordx2 v[236:237], v252, s[100:101] offset:384
	global_load_dwordx2 v[240:241], v252, s[100:101] offset:1024
	global_load_dwordx2 v[242:243], v252, s[100:101] offset:1152
	global_load_dwordx2 v[244:245], v252, s[100:101] offset:1280
	global_load_dwordx2 v[246:247], v252, s[100:101] offset:1408
	s_branch .Lds_P8_a_done
.Lds_P8_a_st:
	s_cmp_eq_u32 s32, 0
	s_cbranch_scc1 .Lds_P8_a_done
	s_cmp_eq_u32 s77, 0
	s_cbranch_scc1 .Lds_P8_a_0
	s_cmp_eq_u32 s77, 2
	s_cbranch_scc1 .Lds_P8_a_1
	s_add_u32 s100, s98, 0x11e000
	s_addc_u32 s101, s99, 0
	global_store_dwordx4 v239, v[248:251], s[100:101]
	s_branch .Lds_P8_a_done

.Lds_P8_a_done:
	s_barrier
	s_setprio 1
	v_mfma_f32_16x16x32_bf16 v[48:51], v[206:209], v[172:175], v[48:51]
	v_mfma_f32_16x16x32_bf16 v[40:43], v[214:217], v[172:175], v[40:43]
	v_mfma_f32_16x16x32_bf16 v[32:35], v[206:209], v[180:183], v[32:35]
	v_mfma_f32_16x16x32_bf16 v[24:27], v[214:217], v[180:183], v[24:27]
	v_mfma_f32_16x16x32_bf16 v[16:19], v[206:209], v[188:191], v[16:19]
	v_mfma_f32_16x16x32_bf16 v[8:11], v[214:217], v[188:191], v[8:11]
	v_mfma_f32_16x16x32_bf16 v[4:7], v[206:209], v[196:199], v[4:7]
	v_mfma_f32_16x16x32_bf16 v[0:3], v[214:217], v[196:199], v[0:3]
	v_mfma_f32_16x16x32_bf16 v[48:51], v[210:213], v[176:179], v[48:51]
	v_mfma_f32_16x16x32_bf16 v[40:43], v[218:221], v[176:179], v[40:43]
	v_mfma_f32_16x16x32_bf16 v[32:35], v[210:213], v[184:187], v[32:35]
	v_mfma_f32_16x16x32_bf16 v[24:27], v[218:221], v[184:187], v[24:27]
	v_mfma_f32_16x16x32_bf16 v[16:19], v[210:213], v[192:195], v[16:19]
	v_mfma_f32_16x16x32_bf16 v[8:11], v[218:221], v[192:195], v[8:11]
	v_mfma_f32_16x16x32_bf16 v[4:7], v[210:213], v[200:203], v[4:7]
	v_mfma_f32_16x16x32_bf16 v[0:3], v[218:221], v[200:203], v[0:3]
	s_setprio 0
	s_add_i32 s78, 0, 0x18000
	v_add_u32_e32 v148, s78, v157
	s_barrier
	ds_read_b128 v[144:147], v148
	ds_read_b128 v[150:153], v148 offset:1024
	ds_read_b128 v[164:167], v148 offset:2048
	ds_read_b128 v[168:171], v148 offset:3072
	s_add_u32 s68, s68, 0x40000
	s_addc_u32 s69, s69, 0
	s_mov_b32 m0, s42
	v_lshl_add_u64 v[206:207], s[68:69], 0, v[134:135]
	ds_read_b128 v[172:175], v160 offset:32768
	ds_read_b128 v[176:179], v160 offset:33792
	ds_read_b128 v[180:183], v160 offset:34816
	ds_read_b128 v[184:187], v160 offset:35840
	ds_read_b128 v[188:191], v160 offset:36864
	ds_read_b128 v[192:195], v160 offset:37888
	ds_read_b128 v[196:199], v160 offset:38912
	ds_read_b128 v[200:203], v160 offset:39936
	global_load_lds_dwordx4 v[206:207], off
	v_lshl_add_u64 v[206:207], s[68:69], 0, v[130:131]
	s_mov_b32 m0, s43
	s_nop 0
	global_load_lds_dwordx4 v[206:207], off
	s_waitcnt lgkmcnt(8)
	s_barrier
	s_waitcnt lgkmcnt(0)
	s_setprio 1
	s_waitcnt lgkmcnt(0)
	v_mfma_f32_16x16x32_bf16 v[124:127], v[144:147], v[172:175], v[124:127]
	v_mfma_f32_16x16x32_bf16 v[120:123], v[164:167], v[172:175], v[120:123]
	v_mfma_f32_16x16x32_bf16 v[116:119], v[144:147], v[180:183], v[116:119]
	v_mfma_f32_16x16x32_bf16 v[108:111], v[164:167], v[180:183], v[108:111]
	v_mfma_f32_16x16x32_bf16 v[100:103], v[144:147], v[188:191], v[100:103]
	v_mfma_f32_16x16x32_bf16 v[92:95], v[164:167], v[188:191], v[92:95]
	v_mfma_f32_16x16x32_bf16 v[84:87], v[144:147], v[196:199], v[84:87]
	v_mfma_f32_16x16x32_bf16 v[76:79], v[164:167], v[196:199], v[76:79]
	v_mfma_f32_16x16x32_bf16 v[124:127], v[150:153], v[176:179], v[124:127]
	v_mfma_f32_16x16x32_bf16 v[120:123], v[168:171], v[176:179], v[120:123]
	v_mfma_f32_16x16x32_bf16 v[116:119], v[150:153], v[184:187], v[116:119]
	v_mfma_f32_16x16x32_bf16 v[108:111], v[168:171], v[184:187], v[108:111]
	v_mfma_f32_16x16x32_bf16 v[100:103], v[150:153], v[192:195], v[100:103]
	v_mfma_f32_16x16x32_bf16 v[92:95], v[168:171], v[192:195], v[92:95]
	v_mfma_f32_16x16x32_bf16 v[84:87], v[150:153], v[200:203], v[84:87]
	v_mfma_f32_16x16x32_bf16 v[76:79], v[168:171], v[200:203], v[76:79]
	s_setprio 0
	s_barrier
	s_add_i32 s68, 0, 0x1c000
	s_add_i32 s69, s78, s20
	v_add_u32_e32 v148, s68, v157
	v_lshl_add_u64 v[154:155], v[154:155], 0, s[56:57]
	s_mov_b32 m0, s69
	ds_read_b128 v[206:209], v148
	ds_read_b128 v[210:213], v148 offset:1024
	ds_read_b128 v[214:217], v148 offset:2048
	ds_read_b128 v[218:221], v148 offset:3072
	global_load_lds_dwordx4 v[154:155], off
	v_lshl_add_u64 v[154:155], v[222:223], 0, s[56:57]
	s_add_i32 m0, s69, 0x2000
	s_nop 0
	global_load_lds_dwordx4 v[154:155], off
	s_barrier
	s_waitcnt lgkmcnt(0)
	s_setprio 1
	s_waitcnt lgkmcnt(0)
	v_mfma_f32_16x16x32_bf16 v[112:115], v[206:209], v[172:175], v[112:115]
	v_mfma_f32_16x16x32_bf16 v[104:107], v[214:217], v[172:175], v[104:107]
	v_mfma_f32_16x16x32_bf16 v[96:99], v[206:209], v[180:183], v[96:99]
	v_mfma_f32_16x16x32_bf16 v[88:91], v[214:217], v[180:183], v[88:91]
	v_mfma_f32_16x16x32_bf16 v[80:83], v[206:209], v[188:191], v[80:83]
	v_mfma_f32_16x16x32_bf16 v[72:75], v[214:217], v[188:191], v[72:75]
	v_mfma_f32_16x16x32_bf16 v[68:71], v[206:209], v[196:199], v[68:71]
	v_mfma_f32_16x16x32_bf16 v[64:67], v[214:217], v[196:199], v[64:67]
	v_mfma_f32_16x16x32_bf16 v[112:115], v[210:213], v[176:179], v[112:115]
	v_mfma_f32_16x16x32_bf16 v[104:107], v[218:221], v[176:179], v[104:107]
	v_mfma_f32_16x16x32_bf16 v[96:99], v[210:213], v[184:187], v[96:99]
	v_mfma_f32_16x16x32_bf16 v[88:91], v[218:221], v[184:187], v[88:91]
	v_mfma_f32_16x16x32_bf16 v[80:83], v[210:213], v[192:195], v[80:83]
	v_mfma_f32_16x16x32_bf16 v[72:75], v[218:221], v[192:195], v[72:75]
	v_mfma_f32_16x16x32_bf16 v[68:71], v[210:213], v[200:203], v[68:71]
	v_mfma_f32_16x16x32_bf16 v[64:67], v[218:221], v[200:203], v[64:67]
	s_setprio 0
	s_mov_b32 m0, s45
	v_lshl_add_u64 v[154:155], v[224:225], 0, s[56:57]
	s_barrier
	ds_read_b128 v[172:175], v160 offset:49152
	ds_read_b128 v[176:179], v160 offset:50176
	ds_read_b128 v[180:183], v160 offset:51200
	ds_read_b128 v[184:187], v160 offset:52224
	ds_read_b128 v[188:191], v160 offset:53248
	ds_read_b128 v[192:195], v160 offset:54272
	ds_read_b128 v[196:199], v160 offset:55296
	ds_read_b128 v[200:203], v160 offset:56320
	global_load_lds_dwordx4 v[154:155], off
	v_lshl_add_u64 v[154:155], v[226:227], 0, s[56:57]
	s_mov_b32 m0, s46
	s_nop 0
	global_load_lds_dwordx4 v[154:155], off
	s_barrier
	s_waitcnt lgkmcnt(0)
	s_setprio 1
	s_waitcnt lgkmcnt(0)
	v_mfma_f32_16x16x32_bf16 v[60:63], v[144:147], v[172:175], v[60:63]
	v_mfma_f32_16x16x32_bf16 v[56:59], v[164:167], v[172:175], v[56:59]
	v_mfma_f32_16x16x32_bf16 v[52:55], v[144:147], v[180:183], v[52:55]
	v_mfma_f32_16x16x32_bf16 v[44:47], v[164:167], v[180:183], v[44:47]
	v_mfma_f32_16x16x32_bf16 v[36:39], v[144:147], v[188:191], v[36:39]
	v_mfma_f32_16x16x32_bf16 v[28:31], v[164:167], v[188:191], v[28:31]
	v_mfma_f32_16x16x32_bf16 v[20:23], v[144:147], v[196:199], v[20:23]
	v_mfma_f32_16x16x32_bf16 v[12:15], v[164:167], v[196:199], v[12:15]
	v_mfma_f32_16x16x32_bf16 v[60:63], v[150:153], v[176:179], v[60:63]
	v_mfma_f32_16x16x32_bf16 v[56:59], v[168:171], v[176:179], v[56:59]
	v_mfma_f32_16x16x32_bf16 v[52:55], v[150:153], v[184:187], v[52:55]
	v_mfma_f32_16x16x32_bf16 v[44:47], v[168:171], v[184:187], v[44:47]
	v_mfma_f32_16x16x32_bf16 v[36:39], v[150:153], v[192:195], v[36:39]
	v_mfma_f32_16x16x32_bf16 v[28:31], v[168:171], v[192:195], v[28:31]
	v_mfma_f32_16x16x32_bf16 v[20:23], v[150:153], v[200:203], v[20:23]
	v_mfma_f32_16x16x32_bf16 v[12:15], v[168:171], v[200:203], v[12:15]
	s_setprio 0
	s_barrier
	s_add_u32 s66, s66, 0x40080
	s_addc_u32 s67, s67, 0
	s_add_i32 s68, s68, s20
	v_lshl_add_u64 v[144:145], s[66:67], 0, v[132:133]
	s_mov_b32 m0, s68
	s_nop 0
	global_load_lds_dwordx4 v[144:145], off
	v_lshl_add_u64 v[144:145], s[66:67], 0, v[128:129]
	s_add_i32 m0, s68, 0x2000
	s_nop 0
	global_load_lds_dwordx4 v[144:145], off
	s_waitcnt vmcnt(6)
	s_cmp_gt_u32 s77, 10
	s_cbranch_scc1 .Lds_P8_b_done
	s_cmp_lt_u32 s77, 6
	s_cbranch_scc1 .Lds_P8_b_st
	s_cmp_eq_u32 s77, 6
	s_cbranch_scc1 .Lds_P8_b_done
	s_cmp_eq_u32 s77, 8
	s_cbranch_scc1 .Lds_P8_b_c8
	v_ffbh_u32_e32 v254, v245
	v_min_u32_e32 v254, 32, v254
	v_lshlrev_b64 v[244:245], v254, v[244:245]
	v_min_u32_e32 v244, 1, v244
	v_or_b32_e32 v245, v245, v244
	v_cvt_f32_u32_e32 v245, v245
	v_sub_u32_e32 v254, -2, v254
	v_ldexp_f32 v245, v245, v254
	v_add_f32_e32 v245, 0x358637bd, v245
	v_rsq_f32_e32 v254, v245
	v_ffbh_u32_e32 v255, v247
	v_min_u32_e32 v255, 32, v255
	v_lshlrev_b64 v[246:247], v255, v[246:247]
	v_min_u32_e32 v246, 1, v246
	v_or_b32_e32 v247, v247, v246
	v_cvt_f32_u32_e32 v247, v247
	v_sub_u32_e32 v255, -2, v255
	v_ldexp_f32 v247, v247, v255
	v_add_f32_e32 v247, 0x358637bd, v247
	v_rsq_f32_e32 v255, v247
	s_branch .Lds_P8_b_done

.Lds_P8_b_st:
	s_cmp_eq_u32 s32, 0
	s_cbranch_scc1 .Lds_P8_b_done
	s_cmp_eq_u32 s77, 0
	s_cbranch_scc1 .Lds_P8_b_0
	s_cmp_eq_u32 s77, 2
	s_cbranch_scc1 .Lds_P8_b_1
	s_add_u32 s100, s98, 0x11e000
	s_addc_u32 s101, s99, 0
	global_store_dwordx4 v239, v[252:255], s[100:101] offset:256
	s_branch .Lds_P8_b_done

.Lepi_P8_start:
	s_mul_i32 s82, s10, 0x1a0000
	s_lshl_b32 s84, s73, 9
	s_add_u32 s82, s82, s84
	s_add_u32 s84, s52, s82
	s_addc_u32 s85, s53, 0
	v_pk_mul_f32 v[124:125], v[124:125], v[248:249] op_sel_hi:[1,0]
	v_pk_mul_f32 v[126:127], v[126:127], v[248:249] op_sel_hi:[1,0]
	v_pk_mul_f32 v[120:121], v[120:121], v[248:249] op_sel_hi:[1,0]
	v_pk_mul_f32 v[122:123], v[122:123], v[248:249] op_sel_hi:[1,0]
	v_cvt_pk_bf16_f32 v124, v124, v125
	v_cvt_pk_bf16_f32 v125, v126, v127
	v_cvt_pk_bf16_f32 v126, v120, v121
	v_cvt_pk_bf16_f32 v127, v122, v123
	global_store_dwordx4 v239, v[124:127], s[84:85]
	v_pk_mul_f32 v[112:113], v[112:113], v[248:249] op_sel_hi:[1,0]
	v_pk_mul_f32 v[114:115], v[114:115], v[248:249] op_sel_hi:[1,0]
	v_pk_mul_f32 v[104:105], v[104:105], v[248:249] op_sel_hi:[1,0]
	v_pk_mul_f32 v[106:107], v[106:107], v[248:249] op_sel_hi:[1,0]
	v_cvt_pk_bf16_f32 v112, v112, v113
	v_cvt_pk_bf16_f32 v113, v114, v115
	v_cvt_pk_bf16_f32 v114, v104, v105
	v_cvt_pk_bf16_f32 v115, v106, v107
	global_store_dwordx4 v239, v[112:115], s[84:85] offset:256
	v_pk_mul_f32 v[116:117], v[116:117], v[248:249] op_sel:[0,1] op_sel_hi:[1,1]
	v_pk_mul_f32 v[118:119], v[118:119], v[248:249] op_sel:[0,1] op_sel_hi:[1,1]
	v_pk_mul_f32 v[108:109], v[108:109], v[248:249] op_sel:[0,1] op_sel_hi:[1,1]
	v_pk_mul_f32 v[110:111], v[110:111], v[248:249] op_sel:[0,1] op_sel_hi:[1,1]
	v_cvt_pk_bf16_f32 v116, v116, v117
	v_cvt_pk_bf16_f32 v117, v118, v119
	v_cvt_pk_bf16_f32 v118, v108, v109
	v_cvt_pk_bf16_f32 v119, v110, v111
	s_add_u32 s100, s84, 0x1a000
	s_addc_u32 s101, s85, 0
	global_store_dwordx4 v239, v[116:119], s[100:101]
	v_pk_mul_f32 v[96:97], v[96:97], v[248:249] op_sel:[0,1] op_sel_hi:[1,1]
	v_pk_mul_f32 v[98:99], v[98:99], v[248:249] op_sel:[0,1] op_sel_hi:[1,1]
	v_pk_mul_f32 v[88:89], v[88:89], v[248:249] op_sel:[0,1] op_sel_hi:[1,1]
	v_pk_mul_f32 v[90:91], v[90:91], v[248:249] op_sel:[0,1] op_sel_hi:[1,1]
	v_cvt_pk_bf16_f32 v96, v96, v97
	v_cvt_pk_bf16_f32 v97, v98, v99
	v_cvt_pk_bf16_f32 v98, v88, v89
	v_cvt_pk_bf16_f32 v99, v90, v91
	s_add_u32 s100, s84, 0x1a000
	s_addc_u32 s101, s85, 0
	global_store_dwordx4 v239, v[96:99], s[100:101] offset:256
	v_pk_mul_f32 v[100:101], v[100:101], v[250:251] op_sel_hi:[1,0]
	v_pk_mul_f32 v[102:103], v[102:103], v[250:251] op_sel_hi:[1,0]
	v_pk_mul_f32 v[92:93], v[92:93], v[250:251] op_sel_hi:[1,0]
	v_pk_mul_f32 v[94:95], v[94:95], v[250:251] op_sel_hi:[1,0]
	v_cvt_pk_bf16_f32 v100, v100, v101
	v_cvt_pk_bf16_f32 v101, v102, v103
	v_cvt_pk_bf16_f32 v102, v92, v93
	v_cvt_pk_bf16_f32 v103, v94, v95
	s_add_u32 s100, s84, 0x34000
	s_addc_u32 s101, s85, 0
	global_store_dwordx4 v239, v[100:103], s[100:101]
	v_pk_mul_f32 v[80:81], v[80:81], v[250:251] op_sel_hi:[1,0]
	v_pk_mul_f32 v[82:83], v[82:83], v[250:251] op_sel_hi:[1,0]
	v_pk_mul_f32 v[72:73], v[72:73], v[250:251] op_sel_hi:[1,0]
	v_pk_mul_f32 v[74:75], v[74:75], v[250:251] op_sel_hi:[1,0]
	v_cvt_pk_bf16_f32 v80, v80, v81
	v_cvt_pk_bf16_f32 v81, v82, v83
	v_cvt_pk_bf16_f32 v82, v72, v73
	v_cvt_pk_bf16_f32 v83, v74, v75
	s_add_u32 s100, s84, 0x34000
	s_addc_u32 s101, s85, 0
	global_store_dwordx4 v239, v[80:83], s[100:101] offset:256
	v_pk_mul_f32 v[84:85], v[84:85], v[250:251] op_sel:[0,1] op_sel_hi:[1,1]
	v_pk_mul_f32 v[86:87], v[86:87], v[250:251] op_sel:[0,1] op_sel_hi:[1,1]
	v_pk_mul_f32 v[76:77], v[76:77], v[250:251] op_sel:[0,1] op_sel_hi:[1,1]
	v_pk_mul_f32 v[78:79], v[78:79], v[250:251] op_sel:[0,1] op_sel_hi:[1,1]
	v_cvt_pk_bf16_f32 v84, v84, v85
	v_cvt_pk_bf16_f32 v85, v86, v87
	v_cvt_pk_bf16_f32 v86, v76, v77
	v_cvt_pk_bf16_f32 v87, v78, v79
	s_add_u32 s100, s84, 0x4e000
	s_addc_u32 s101, s85, 0
	global_store_dwordx4 v239, v[84:87], s[100:101]
	v_pk_mul_f32 v[68:69], v[68:69], v[250:251] op_sel:[0,1] op_sel_hi:[1,1]
	v_pk_mul_f32 v[70:71], v[70:71], v[250:251] op_sel:[0,1] op_sel_hi:[1,1]
	v_pk_mul_f32 v[64:65], v[64:65], v[250:251] op_sel:[0,1] op_sel_hi:[1,1]
	v_pk_mul_f32 v[66:67], v[66:67], v[250:251] op_sel:[0,1] op_sel_hi:[1,1]
	v_cvt_pk_bf16_f32 v68, v68, v69
	v_cvt_pk_bf16_f32 v69, v70, v71
	v_cvt_pk_bf16_f32 v70, v64, v65
	v_cvt_pk_bf16_f32 v71, v66, v67
	s_add_u32 s100, s84, 0x4e000
	s_addc_u32 s101, s85, 0
	global_store_dwordx4 v239, v[68:71], s[100:101] offset:256
	v_pk_mul_f32 v[60:61], v[60:61], v[252:253] op_sel_hi:[1,0]
	v_pk_mul_f32 v[62:63], v[62:63], v[252:253] op_sel_hi:[1,0]
	v_pk_mul_f32 v[56:57], v[56:57], v[252:253] op_sel_hi:[1,0]
	v_pk_mul_f32 v[58:59], v[58:59], v[252:253] op_sel_hi:[1,0]
	v_cvt_pk_bf16_f32 v60, v60, v61
	v_cvt_pk_bf16_f32 v61, v62, v63
	v_cvt_pk_bf16_f32 v62, v56, v57
	v_cvt_pk_bf16_f32 v63, v58, v59
	s_add_u32 s100, s84, 0xd0000
	s_addc_u32 s101, s85, 0
	global_store_dwordx4 v239, v[60:63], s[100:101]
	v_pk_mul_f32 v[48:49], v[48:49], v[252:253] op_sel_hi:[1,0]
	v_pk_mul_f32 v[50:51], v[50:51], v[252:253] op_sel_hi:[1,0]
	v_pk_mul_f32 v[40:41], v[40:41], v[252:253] op_sel_hi:[1,0]
	v_pk_mul_f32 v[42:43], v[42:43], v[252:253] op_sel_hi:[1,0]
	v_cvt_pk_bf16_f32 v48, v48, v49
	v_cvt_pk_bf16_f32 v49, v50, v51
	v_cvt_pk_bf16_f32 v50, v40, v41
	v_cvt_pk_bf16_f32 v51, v42, v43
	s_add_u32 s100, s84, 0xd0000
	s_addc_u32 s101, s85, 0
	global_store_dwordx4 v239, v[48:51], s[100:101] offset:256
	v_pk_mul_f32 v[52:53], v[52:53], v[252:253] op_sel:[0,1] op_sel_hi:[1,1]
	v_pk_mul_f32 v[54:55], v[54:55], v[252:253] op_sel:[0,1] op_sel_hi:[1,1]
	v_pk_mul_f32 v[44:45], v[44:45], v[252:253] op_sel:[0,1] op_sel_hi:[1,1]
	v_pk_mul_f32 v[46:47], v[46:47], v[252:253] op_sel:[0,1] op_sel_hi:[1,1]
	v_cvt_pk_bf16_f32 v230, v52, v53
	v_cvt_pk_bf16_f32 v231, v54, v55
	v_cvt_pk_bf16_f32 v232, v44, v45
	v_cvt_pk_bf16_f32 v233, v46, v47
	v_pk_mul_f32 v[32:33], v[32:33], v[252:253] op_sel:[0,1] op_sel_hi:[1,1]
	v_pk_mul_f32 v[34:35], v[34:35], v[252:253] op_sel:[0,1] op_sel_hi:[1,1]
	v_pk_mul_f32 v[24:25], v[24:25], v[252:253] op_sel:[0,1] op_sel_hi:[1,1]
	v_pk_mul_f32 v[26:27], v[26:27], v[252:253] op_sel:[0,1] op_sel_hi:[1,1]
	v_cvt_pk_bf16_f32 v234, v32, v33
	v_cvt_pk_bf16_f32 v235, v34, v35
	v_cvt_pk_bf16_f32 v236, v24, v25
	v_cvt_pk_bf16_f32 v237, v26, v27
	v_pk_mul_f32 v[36:37], v[36:37], v[254:255] op_sel_hi:[1,0]
	v_pk_mul_f32 v[38:39], v[38:39], v[254:255] op_sel_hi:[1,0]
	v_pk_mul_f32 v[28:29], v[28:29], v[254:255] op_sel_hi:[1,0]
	v_pk_mul_f32 v[30:31], v[30:31], v[254:255] op_sel_hi:[1,0]
	v_cvt_pk_bf16_f32 v240, v36, v37
	v_cvt_pk_bf16_f32 v241, v38, v39
	v_cvt_pk_bf16_f32 v242, v28, v29
	v_cvt_pk_bf16_f32 v243, v30, v31
	v_pk_mul_f32 v[16:17], v[16:17], v[254:255] op_sel_hi:[1,0]
	v_pk_mul_f32 v[18:19], v[18:19], v[254:255] op_sel_hi:[1,0]
	v_pk_mul_f32 v[8:9], v[8:9], v[254:255] op_sel_hi:[1,0]
	v_pk_mul_f32 v[10:11], v[10:11], v[254:255] op_sel_hi:[1,0]
	v_cvt_pk_bf16_f32 v244, v16, v17
	v_cvt_pk_bf16_f32 v245, v18, v19
	v_cvt_pk_bf16_f32 v246, v8, v9
	v_cvt_pk_bf16_f32 v247, v10, v11
	v_pk_mul_f32 v[20:21], v[20:21], v[254:255] op_sel:[0,1] op_sel_hi:[1,1]
	v_pk_mul_f32 v[22:23], v[22:23], v[254:255] op_sel:[0,1] op_sel_hi:[1,1]
	v_pk_mul_f32 v[12:13], v[12:13], v[254:255] op_sel:[0,1] op_sel_hi:[1,1]
	v_pk_mul_f32 v[14:15], v[14:15], v[254:255] op_sel:[0,1] op_sel_hi:[1,1]
	v_cvt_pk_bf16_f32 v248, v20, v21
	v_cvt_pk_bf16_f32 v249, v22, v23
	v_cvt_pk_bf16_f32 v250, v12, v13
	v_cvt_pk_bf16_f32 v251, v14, v15
	v_pk_mul_f32 v[4:5], v[4:5], v[254:255] op_sel:[0,1] op_sel_hi:[1,1]
	v_pk_mul_f32 v[6:7], v[6:7], v[254:255] op_sel:[0,1] op_sel_hi:[1,1]
	v_pk_mul_f32 v[0:1], v[0:1], v[254:255] op_sel:[0,1] op_sel_hi:[1,1]
	v_pk_mul_f32 v[2:3], v[2:3], v[254:255] op_sel:[0,1] op_sel_hi:[1,1]
	v_cvt_pk_bf16_f32 v252, v4, v5
	v_cvt_pk_bf16_f32 v253, v6, v7
	v_cvt_pk_bf16_f32 v254, v0, v1
	v_cvt_pk_bf16_f32 v255, v2, v3
	s_mov_b64 s[66:67], s[64:65]
	s_and_b64 vcc, exec, s[8:9]
	s_mov_b32 s73, s58
	s_mov_b64 s[12:13], s[62:63]
	s_mov_b32 s10, s60
	s_mov_b64 s[98:99], s[84:85]
	s_mov_b32 s32, 1
	s_cbranch_vccz .LBB0_1138
	s_add_u32 s100, s84, 0xea000
	s_addc_u32 s101, s85, 0
	global_store_dwordx4 v239, v[230:233], s[100:101]
	s_add_u32 s100, s84, 0xea000
	s_addc_u32 s101, s85, 0
	global_store_dwordx4 v239, v[234:237], s[100:101] offset:256
	s_add_u32 s100, s84, 0x104000
	s_addc_u32 s101, s85, 0
	global_store_dwordx4 v239, v[240:243], s[100:101]
	s_add_u32 s100, s84, 0x104000
	s_addc_u32 s101, s85, 0
	global_store_dwordx4 v239, v[244:247], s[100:101] offset:256
	s_add_u32 s100, s84, 0x11e000
	s_addc_u32 s101, s85, 0
	global_store_dwordx4 v239, v[248:251], s[100:101]
	s_add_u32 s100, s84, 0x11e000
	s_addc_u32 s101, s85, 0
	global_store_dwordx4 v239, v[252:255], s[100:101] offset:256
	s_waitcnt vmcnt(0)
	s_cmpk_gt_u32 s0, 0xff
	s_cbranch_scc1 .LBB0_1145
	s_barrier

.LBB0_1594:
	s_or_b64 exec, exec, s[12:13]
	s_add_i32 s82, s81, s61
	s_lshl_b32 s12, s2, 2
	s_add_u32 s12, s26, s12
	s_addc_u32 s13, s27, 0
	v_lshl_add_u32 v0, v131, 2, s96
	v_lshl_add_u64 v[84:85], v[84:85], 2, s[12:13]
	s_waitcnt lgkmcnt(0)
	s_barrier
	ds_read2st64_b32 v[94:95], v0 offset1:1
	ds_read2st64_b32 v[96:97], v0 offset0:2 offset1:3
	ds_read2st64_b32 v[98:99], v0 offset0:4 offset1:5
	ds_read2st64_b32 v[100:101], v0 offset0:6 offset1:7
	global_load_dwordx4 v[252:255], v[84:85], off offset:16
	global_load_dwordx4 v[248:251], v[84:85], off
	s_waitcnt vmcnt(5)
	v_lshlrev_b32_e32 v104, 16, v72
	v_and_b32_e32 v105, 0xffff0000, v72
	v_mul_f32_e32 v0, 0xbfb8aa3b, v104
	v_lshlrev_b64 v[102:103], 11, v[2:3]
	v_exp_f32_e32 v0, v0
	v_mul_f32_e32 v2, 0xbfb8aa3b, v105
	v_exp_f32_e32 v2, v2
	v_lshlrev_b32_e32 v106, 16, v73
	v_add_f32_e32 v0, 1.0, v0
	v_rcp_f32_e32 v72, v0
	v_add_f32_e32 v0, 1.0, v2
	v_mul_f32_e32 v2, 0xbfb8aa3b, v106
	v_exp_f32_e32 v2, v2
	v_and_b32_e32 v107, 0xffff0000, v73
	v_mul_f32_e32 v73, 0xbfb8aa3b, v107
	v_lshlrev_b32_e32 v110, 16, v74
	v_exp_f32_e32 v109, v73
	v_rcp_f32_e32 v73, v0
	v_add_f32_e32 v0, 1.0, v2
	v_and_b32_e32 v111, 0xffff0000, v74
	v_mul_f32_e32 v2, 0xbfb8aa3b, v110
	v_exp_f32_e32 v2, v2
	v_mul_f32_e32 v74, 0xbfb8aa3b, v111
	v_exp_f32_e32 v112, v74
	v_rcp_f32_e32 v108, v0
	v_add_f32_e32 v0, 1.0, v109
	v_rcp_f32_e32 v109, v0
	v_add_f32_e32 v0, 1.0, v2
	v_rcp_f32_e32 v74, v0
	v_add_f32_e32 v0, 1.0, v112
	v_lshlrev_b32_e32 v112, 16, v75
	v_and_b32_e32 v113, 0xffff0000, v75
	v_mul_f32_e32 v2, 0xbfb8aa3b, v112
	v_exp_f32_e32 v2, v2
	v_mul_f32_e32 v75, 0xbfb8aa3b, v113
	v_exp_f32_e32 v115, v75
	v_rcp_f32_e32 v75, v0
	v_add_f32_e32 v0, 1.0, v2
	v_rcp_f32_e32 v114, v0
	v_add_f32_e32 v0, 1.0, v115
	v_rcp_f32_e32 v115, v0
	v_lshl_add_u32 v0, v129, 2, s96
	v_pk_mul_f32 v[106:107], v[108:109], v[106:107]
	v_pk_mul_f32 v[108:109], v[74:75], v[110:111]
	ds_read2st64_b32 v[74:75], v0 offset1:1
	v_pk_mul_f32 v[110:111], v[114:115], v[112:113]
	ds_read2st64_b32 v[112:113], v0 offset0:2 offset1:3
	ds_read2st64_b32 v[114:115], v0 offset0:4 offset1:5
	ds_read2st64_b32 v[116:117], v0 offset0:6 offset1:7
	s_waitcnt lgkmcnt(7)
	v_mov_b32_e32 v119, v94
	v_ashrrev_i32_e32 v133, 31, v132
	s_waitcnt lgkmcnt(3)
	v_mov_b32_e32 v118, v74
	v_pk_add_f32 v[118:119], v[118:119], 0 op_sel_hi:[1,0]
	v_mov_b32_e32 v94, v75
	v_pk_add_f32 v[74:75], v[118:119], v[94:95]
	s_waitcnt lgkmcnt(2)
	v_mov_b32_e32 v94, v112
	v_mov_b32_e32 v95, v96
	v_pk_add_f32 v[74:75], v[74:75], v[94:95]
	v_mov_b32_e32 v96, v113
	v_pk_add_f32 v[74:75], v[74:75], v[96:97]
	s_waitcnt lgkmcnt(1)
	v_mov_b32_e32 v94, v114
	v_mov_b32_e32 v95, v98
	v_pk_add_f32 v[74:75], v[74:75], v[94:95]
	v_mov_b32_e32 v98, v115
	v_pk_add_f32 v[74:75], v[74:75], v[98:99]
	s_waitcnt lgkmcnt(0)
	v_mov_b32_e32 v94, v116
	v_mov_b32_e32 v95, v100
	v_pk_add_f32 v[74:75], v[74:75], v[94:95]
	v_mov_b32_e32 v100, v117
	v_pk_add_f32 v[94:95], v[74:75], v[100:101]
	v_mov_b64_e32 v[74:75], s[60:61]
	v_pk_fma_f32 v[94:95], v[94:95], s[58:59], v[74:75] op_sel_hi:[1,0,0]
	v_lshl_add_u64 v[102:103], s[28:29], 0, v[102:103]
	v_mul_f32_e32 v0, 0x4b800000, v95
	v_cmp_gt_f32_e32 vcc, s59, v95
	s_lshl_b32 s38, s2, 1
	v_pk_mul_f32 v[104:105], v[72:73], v[104:105]
	v_cndmask_b32_e32 v0, v95, v0, vcc
	v_rsq_f32_e32 v0, v0
	v_lshl_add_u64 v[102:103], v[102:103], 0, s[38:39]
	v_lshlrev_b64 v[72:73], 1, v[132:133]
	v_lshl_add_u64 v[96:97], v[102:103], 0, v[72:73]
	v_mul_f32_e32 v2, 0x45800000, v0
	v_cndmask_b32_e32 v0, v0, v2, vcc
	v_pk_mul_f32 v[80:81], v[80:81], v[0:1] op_sel_hi:[1,0]
	v_pk_mul_f32 v[82:83], v[82:83], v[0:1] op_sel_hi:[1,0]
	v_pk_mul_f32 v[76:77], v[76:77], v[0:1] op_sel_hi:[1,0]
	v_pk_mul_f32 v[78:79], v[78:79], v[0:1] op_sel_hi:[1,0]
	s_waitcnt vmcnt(0)
	v_pk_mul_f32 v[80:81], v[248:249], v[80:81]
	v_pk_mul_f32 v[82:83], v[250:251], v[82:83]
	v_pk_mul_f32 v[76:77], v[252:253], v[76:77]
	v_pk_mul_f32 v[78:79], v[254:255], v[78:79]
	v_mov_b32_e32 v127, v1
	v_pk_mul_f32 v[80:81], v[104:105], v[80:81]
	v_pk_mul_f32 v[82:83], v[106:107], v[82:83]
	v_pk_mul_f32 v[76:77], v[108:109], v[76:77]
	v_pk_mul_f32 v[78:79], v[110:111], v[78:79]
	v_lshl_add_u64 v[96:97], v[96:97], 0, v[126:127]
	v_cvt_pk_bf16_f32 v80, v80, v81
	v_cvt_pk_bf16_f32 v81, v82, v83
	v_cvt_pk_bf16_f32 v82, v76, v77
	v_cvt_pk_bf16_f32 v83, v78, v79
	global_store_dwordx4 v[96:97], v[80:83], off
	s_nop 1
	s_nop 0
	s_nop 0
	s_nop 0
	v_lshlrev_b32_e32 v86, 16, v68
	v_and_b32_e32 v87, 0xffff0000, v68
	v_lshlrev_b32_e32 v68, 16, v69
	v_and_b32_e32 v69, 0xffff0000, v69
	v_mul_f32_e32 v0, 0xbfb8aa3b, v86
	v_mul_f32_e32 v92, 0xbfb8aa3b, v69
	v_exp_f32_e32 v0, v0
	v_exp_f32_e32 v92, v92
	v_lshlrev_b32_e32 v88, 16, v70
	v_and_b32_e32 v89, 0xffff0000, v70
	v_mul_f32_e32 v2, 0xbfb8aa3b, v87
	v_mul_f32_e32 v70, 0xbfb8aa3b, v68
	v_add_f32_e32 v0, 1.0, v0
	v_mul_f32_e32 v93, 0xbfb8aa3b, v88
	v_exp_f32_e32 v2, v2
	v_exp_f32_e32 v70, v70
	v_add_f32_e32 v97, 1.0, v92
	v_rcp_f32_e32 v92, v0
	v_mul_f32_e32 v0, 0x4b800000, v94
	v_cmp_gt_f32_e32 vcc, s59, v94
	v_exp_f32_e32 v93, v93
	v_add_f32_e32 v2, 1.0, v2
	v_cndmask_b32_e32 v0, v94, v0, vcc
	v_rsq_f32_e32 v0, v0
	v_add_f32_e32 v70, 1.0, v70
	v_add_f32_e32 v98, 1.0, v93
	v_rcp_f32_e32 v93, v2
	v_rcp_f32_e32 v96, v70
	v_rcp_f32_e32 v97, v97
	v_mul_f32_e32 v2, 0x45800000, v0
	v_cndmask_b32_e32 v0, v0, v2, vcc
	v_pk_mul_f32 v[64:65], v[64:65], v[0:1] op_sel_hi:[1,0]
	v_pk_mul_f32 v[66:67], v[66:67], v[0:1] op_sel_hi:[1,0]
	v_pk_mul_f32 v[86:87], v[92:93], v[86:87]
	v_pk_mul_f32 v[68:69], v[96:97], v[68:69]
	v_pk_mul_f32 v[60:61], v[60:61], v[0:1] op_sel_hi:[1,0]
	v_mul_f32_e32 v95, 0xbfb8aa3b, v89
	v_exp_f32_e32 v95, v95
	v_rcp_f32_e32 v94, v98
	v_mov_b32_e32 v131, v3
	v_pk_mul_f32 v[62:63], v[62:63], v[0:1] op_sel_hi:[1,0]
	v_add_f32_e32 v95, 1.0, v95
	v_rcp_f32_e32 v95, v95
	v_lshlrev_b64 v[90:91], 11, v[130:131]
	v_lshl_add_u64 v[90:91], s[28:29], 0, v[90:91]
	v_lshl_add_u32 v0, v177, 2, s96
	v_mov_b32_e32 v129, v3
	s_add_i32 s80, s80, s75
	s_add_i32 s79, s79, s76
	s_cmpk_gt_i32 s82, 0x3ff
	s_cselect_b64 s[12:13], -1, 0
	s_nop 0
	v_pk_mul_f32 v[64:65], v[248:249], v[64:65]
	v_pk_mul_f32 v[66:67], v[250:251], v[66:67]
	s_nop 0
	v_pk_mul_f32 v[76:77], v[252:253], v[60:61]
	v_pk_mul_f32 v[60:61], v[86:87], v[64:65]
	v_pk_mul_f32 v[64:65], v[68:69], v[66:67]
	v_cvt_pk_bf16_f32 v60, v60, v61
	v_cvt_pk_bf16_f32 v61, v64, v65
	v_lshlrev_b32_e32 v64, 16, v71
	v_and_b32_e32 v65, 0xffff0000, v71
	v_mul_f32_e32 v2, 0xbfb8aa3b, v64
	v_exp_f32_e32 v2, v2
	v_mul_f32_e32 v66, 0xbfb8aa3b, v65
	v_exp_f32_e32 v69, v66
	v_pk_mul_f32 v[62:63], v[254:255], v[62:63]
	v_add_f32_e32 v2, 1.0, v2
	v_rcp_f32_e32 v68, v2
	v_add_f32_e32 v2, 1.0, v69
	v_rcp_f32_e32 v69, v2
	v_pk_mul_f32 v[66:67], v[94:95], v[88:89]
	v_lshlrev_b32_e32 v82, 16, v56
	v_pk_mul_f32 v[66:67], v[66:67], v[76:77]
	v_pk_mul_f32 v[64:65], v[68:69], v[64:65]
	v_and_b32_e32 v83, 0xffff0000, v56
	v_pk_mul_f32 v[64:65], v[64:65], v[62:63]
	v_cvt_pk_bf16_f32 v62, v66, v67
	v_cvt_pk_bf16_f32 v63, v64, v65
	v_lshl_add_u64 v[64:65], v[90:91], 0, s[38:39]
	v_lshl_add_u64 v[64:65], v[64:65], 0, v[72:73]
	v_lshl_add_u64 v[64:65], v[64:65], 0, v[126:127]
	global_store_dwordx4 v[64:65], v[60:63], off
	s_nop 1
	ds_read2st64_b32 v[68:69], v0 offset1:1
	ds_read2st64_b32 v[70:71], v0 offset0:2 offset1:3
	ds_read2st64_b32 v[76:77], v0 offset0:4 offset1:5
	ds_read2st64_b32 v[78:79], v0 offset0:6 offset1:7
	s_nop 0
	s_nop 0
	v_mul_f32_e32 v0, 0xbfb8aa3b, v82
	v_exp_f32_e32 v0, v0
	v_mul_f32_e32 v2, 0xbfb8aa3b, v83
	v_exp_f32_e32 v2, v2
	v_lshlrev_b32_e32 v56, 16, v57
	v_add_f32_e32 v0, 1.0, v0
	v_rcp_f32_e32 v86, v0
	v_add_f32_e32 v0, 1.0, v2
	v_rcp_f32_e32 v87, v0
	v_and_b32_e32 v57, 0xffff0000, v57
	v_mul_f32_e32 v0, 0xbfb8aa3b, v56
	v_exp_f32_e32 v0, v0
	v_mul_f32_e32 v2, 0xbfb8aa3b, v57
	v_exp_f32_e32 v2, v2
	v_pk_mul_f32 v[82:83], v[86:87], v[82:83]
	v_add_f32_e32 v0, 1.0, v0
	v_rcp_f32_e32 v86, v0
	v_add_f32_e32 v0, 1.0, v2
	v_lshlrev_b32_e32 v88, 16, v58
	v_rcp_f32_e32 v87, v0
	v_and_b32_e32 v89, 0xffff0000, v58
	v_mul_f32_e32 v0, 0xbfb8aa3b, v88
	v_exp_f32_e32 v0, v0
	v_mul_f32_e32 v2, 0xbfb8aa3b, v89
	v_exp_f32_e32 v2, v2
	v_pk_mul_f32 v[56:57], v[86:87], v[56:57]
	v_add_f32_e32 v0, 1.0, v0
	v_lshlrev_b32_e32 v86, 16, v59
	v_rcp_f32_e32 v58, v0
	v_add_f32_e32 v0, 1.0, v2
	v_and_b32_e32 v87, 0xffff0000, v59
	v_mul_f32_e32 v2, 0xbfb8aa3b, v86
	v_exp_f32_e32 v2, v2
	v_mul_f32_e32 v59, 0xbfb8aa3b, v87
	v_exp_f32_e32 v91, v59
	v_rcp_f32_e32 v59, v0
	v_add_f32_e32 v0, 1.0, v2
	v_rcp_f32_e32 v90, v0
	v_add_f32_e32 v0, 1.0, v91
	v_rcp_f32_e32 v91, v0
	v_lshl_add_u32 v0, v125, 2, s96
	v_pk_mul_f32 v[58:59], v[58:59], v[88:89]
	ds_read2st64_b32 v[88:89], v0 offset1:1
	v_pk_mul_f32 v[86:87], v[90:91], v[86:87]
	ds_read2st64_b32 v[90:91], v0 offset0:2 offset1:3
	ds_read2st64_b32 v[92:93], v0 offset0:4 offset1:5
	ds_read2st64_b32 v[94:95], v0 offset0:6 offset1:7
	s_waitcnt lgkmcnt(7)
	v_mov_b32_e32 v97, v68
	v_lshlrev_b64 v[80:81], 11, v[128:129]
	s_waitcnt lgkmcnt(3)
	v_mov_b32_e32 v96, v88
	v_pk_add_f32 v[96:97], v[96:97], 0 op_sel_hi:[1,0]
	v_mov_b32_e32 v68, v89
	v_pk_add_f32 v[68:69], v[96:97], v[68:69]
	s_waitcnt lgkmcnt(2)
	v_mov_b32_e32 v88, v90
	v_mov_b32_e32 v89, v70
	v_pk_add_f32 v[68:69], v[68:69], v[88:89]
	v_mov_b32_e32 v70, v91
	v_pk_add_f32 v[68:69], v[68:69], v[70:71]
	s_waitcnt lgkmcnt(1)
	v_mov_b32_e32 v70, v92
	v_mov_b32_e32 v71, v76
	v_pk_add_f32 v[68:69], v[68:69], v[70:71]
	v_mov_b32_e32 v76, v93
	v_pk_add_f32 v[68:69], v[68:69], v[76:77]
	s_waitcnt lgkmcnt(0)
	v_mov_b32_e32 v70, v94
	v_mov_b32_e32 v71, v78
	v_pk_add_f32 v[68:69], v[68:69], v[70:71]
	v_mov_b32_e32 v78, v95
	v_pk_add_f32 v[68:69], v[68:69], v[78:79]
	v_lshl_add_u64 v[80:81], s[28:29], 0, v[80:81]
	v_pk_fma_f32 v[68:69], v[68:69], s[58:59], v[74:75] op_sel_hi:[1,0,0]
	v_lshl_add_u64 v[70:71], v[80:81], 0, s[38:39]
	v_mul_f32_e32 v0, 0x4b800000, v69
	v_cmp_gt_f32_e32 vcc, s59, v69
	v_lshl_add_u64 v[70:71], v[70:71], 0, v[72:73]
	v_lshl_add_u64 v[70:71], v[70:71], 0, v[126:127]
	v_cndmask_b32_e32 v0, v69, v0, vcc
	v_rsq_f32_e32 v0, v0
	v_mov_b32_e32 v125, v3
	v_and_b32_e32 v3, 0xffff0000, v44
	v_mul_f32_e32 v2, 0x45800000, v0
	v_cndmask_b32_e32 v0, v0, v2, vcc
	v_pk_mul_f32 v[52:53], v[52:53], v[0:1] op_sel_hi:[1,0]
	v_pk_mul_f32 v[54:55], v[54:55], v[0:1] op_sel_hi:[1,0]
	v_pk_mul_f32 v[48:49], v[48:49], v[0:1] op_sel_hi:[1,0]
	v_pk_mul_f32 v[50:51], v[50:51], v[0:1] op_sel_hi:[1,0]
	s_nop 0
	v_pk_mul_f32 v[52:53], v[248:249], v[52:53]
	v_pk_mul_f32 v[54:55], v[250:251], v[54:55]
	v_pk_mul_f32 v[48:49], v[252:253], v[48:49]
	v_pk_mul_f32 v[50:51], v[254:255], v[50:51]
	v_pk_mul_f32 v[52:53], v[82:83], v[52:53]
	v_pk_mul_f32 v[54:55], v[56:57], v[54:55]
	v_pk_mul_f32 v[48:49], v[58:59], v[48:49]
	v_pk_mul_f32 v[50:51], v[86:87], v[50:51]
	v_cvt_pk_bf16_f32 v52, v52, v53
	v_cvt_pk_bf16_f32 v53, v54, v55
	v_cvt_pk_bf16_f32 v54, v48, v49
	v_cvt_pk_bf16_f32 v55, v50, v51
	global_store_dwordx4 v[70:71], v[52:55], off
	s_nop 1
	s_nop 0
	s_nop 0
	s_nop 0
	v_lshlrev_b32_e32 v2, 16, v44
	v_mul_f32_e32 v0, 0xbfb8aa3b, v2
	v_mul_f32_e32 v58, 0xbfb8aa3b, v3
	v_exp_f32_e32 v0, v0
	v_lshlrev_b32_e32 v44, 16, v45
	v_exp_f32_e32 v58, v58
	v_mul_f32_e32 v59, 0xbfb8aa3b, v44
	v_and_b32_e32 v45, 0xffff0000, v45
	v_exp_f32_e32 v59, v59
	v_mul_f32_e32 v60, 0xbfb8aa3b, v45
	v_add_f32_e32 v0, 1.0, v0
	v_exp_f32_e32 v60, v60
	v_add_f32_e32 v61, 1.0, v58
	v_rcp_f32_e32 v58, v0
	v_mul_f32_e32 v0, 0x4b800000, v68
	v_cmp_gt_f32_e32 vcc, s59, v68
	v_add_f32_e32 v62, 1.0, v59
	v_rcp_f32_e32 v59, v61
	v_cndmask_b32_e32 v0, v68, v0, vcc
	v_rsq_f32_e32 v0, v0
	v_add_f32_e32 v63, 1.0, v60
	v_rcp_f32_e32 v60, v62
	v_rcp_f32_e32 v61, v63
	v_pk_mul_f32 v[2:3], v[58:59], v[2:3]
	v_mul_f32_e32 v58, 0x45800000, v0
	v_cndmask_b32_e32 v0, v0, v58, vcc
	v_pk_mul_f32 v[42:43], v[42:43], v[0:1] op_sel_hi:[1,0]
	v_pk_mul_f32 v[44:45], v[60:61], v[44:45]
	v_pk_mul_f32 v[40:41], v[40:41], v[0:1] op_sel_hi:[1,0]
	v_pk_mul_f32 v[36:37], v[36:37], v[0:1] op_sel_hi:[1,0]
	v_lshlrev_b64 v[56:57], 11, v[124:125]
	v_lshl_add_u64 v[56:57], s[28:29], 0, v[56:57]
	s_nop 0
	v_pk_mul_f32 v[42:43], v[250:251], v[42:43]
	v_pk_mul_f32 v[40:41], v[248:249], v[40:41]
	v_pk_mul_f32 v[42:43], v[44:45], v[42:43]
	v_lshlrev_b32_e32 v44, 16, v46
	v_pk_mul_f32 v[2:3], v[2:3], v[40:41]
	v_mul_f32_e32 v40, 0xbfb8aa3b, v44
	v_and_b32_e32 v45, 0xffff0000, v46
	v_exp_f32_e32 v48, v40
	v_cvt_pk_bf16_f32 v40, v2, v3
	v_mul_f32_e32 v3, 0xbfb8aa3b, v45
	v_exp_f32_e32 v3, v3
	v_cvt_pk_bf16_f32 v41, v42, v43
	v_lshlrev_b32_e32 v42, 16, v47
	v_and_b32_e32 v43, 0xffff0000, v47
	v_add_f32_e32 v2, 1.0, v48
	v_add_f32_e32 v3, 1.0, v3
	v_mul_f32_e32 v46, 0xbfb8aa3b, v42
	v_mul_f32_e32 v47, 0xbfb8aa3b, v43
	v_rcp_f32_e32 v2, v2
	v_rcp_f32_e32 v3, v3
	v_exp_f32_e32 v46, v46
	v_exp_f32_e32 v47, v47
	s_nop 0
	v_pk_mul_f32 v[36:37], v[252:253], v[36:37]
	v_pk_mul_f32 v[2:3], v[2:3], v[44:45]
	v_add_f32_e32 v44, 1.0, v46
	v_add_f32_e32 v45, 1.0, v47
	v_rcp_f32_e32 v44, v44
	v_rcp_f32_e32 v45, v45
	v_pk_mul_f32 v[2:3], v[2:3], v[36:37]
	v_pk_mul_f32 v[36:37], v[38:39], v[0:1] op_sel_hi:[1,0]
	v_pk_mul_f32 v[38:39], v[44:45], v[42:43]
	v_pk_mul_f32 v[36:37], v[254:255], v[36:37]
	v_cvt_pk_bf16_f32 v42, v2, v3
	v_lshl_add_u64 v[2:3], v[56:57], 0, s[38:39]
	v_pk_mul_f32 v[36:37], v[38:39], v[36:37]
	v_lshl_add_u64 v[2:3], v[2:3], 0, v[72:73]
	v_cvt_pk_bf16_f32 v43, v36, v37
	v_lshl_add_u64 v[2:3], v[2:3], 0, v[126:127]
	global_store_dwordx4 v[2:3], v[40:43], off
	s_nop 1
	s_barrier

.LBB0_1634:
	s_or_b64 exec, exec, s[12:13]
	s_lshl_b32 s12, s2, 2
	s_add_u32 s12, s26, s12
	s_addc_u32 s13, s27, 0
	v_lshl_add_u32 v0, v131, 2, s96
	v_lshl_add_u64 v[84:85], v[84:85], 2, s[12:13]
	s_waitcnt lgkmcnt(0)
	s_barrier
	ds_read2st64_b32 v[94:95], v0 offset1:1
	ds_read2st64_b32 v[96:97], v0 offset0:2 offset1:3
	ds_read2st64_b32 v[98:99], v0 offset0:4 offset1:5
	ds_read2st64_b32 v[100:101], v0 offset0:6 offset1:7
	global_load_dwordx4 v[252:255], v[84:85], off offset:16
	global_load_dwordx4 v[248:251], v[84:85], off
	s_waitcnt vmcnt(5)
	v_lshlrev_b32_e32 v104, 16, v72
	v_and_b32_e32 v105, 0xffff0000, v72
	v_mul_f32_e32 v0, 0xbfb8aa3b, v104
	v_exp_f32_e32 v0, v0
	v_mul_f32_e32 v72, 0xbfb8aa3b, v105
	v_exp_f32_e32 v106, v72
	v_and_b32_e32 v107, 0xffff0000, v73
	v_add_f32_e32 v0, 1.0, v0
	v_rcp_f32_e32 v72, v0
	v_add_f32_e32 v0, 1.0, v106
	v_lshlrev_b32_e32 v106, 16, v73
	v_mul_f32_e32 v73, 0xbfb8aa3b, v106
	v_exp_f32_e32 v108, v73
	v_mul_f32_e32 v73, 0xbfb8aa3b, v107
	v_exp_f32_e32 v109, v73
	v_lshlrev_b32_e32 v110, 16, v74
	v_rcp_f32_e32 v73, v0
	v_add_f32_e32 v0, 1.0, v108
	v_and_b32_e32 v111, 0xffff0000, v74
	v_mul_f32_e32 v74, 0xbfb8aa3b, v110
	v_rcp_f32_e32 v108, v0
	v_add_f32_e32 v0, 1.0, v109
	v_exp_f32_e32 v74, v74
	v_mul_f32_e32 v109, 0xbfb8aa3b, v111
	v_exp_f32_e32 v112, v109
	v_rcp_f32_e32 v109, v0
	v_add_f32_e32 v0, 1.0, v74
	v_rcp_f32_e32 v74, v0
	v_add_f32_e32 v0, 1.0, v112
	v_lshlrev_b32_e32 v112, 16, v75
	v_and_b32_e32 v113, 0xffff0000, v75
	v_mul_f32_e32 v75, 0xbfb8aa3b, v112
	v_exp_f32_e32 v114, v75
	v_mul_f32_e32 v75, 0xbfb8aa3b, v113
	v_exp_f32_e32 v115, v75
	v_rcp_f32_e32 v75, v0
	v_add_f32_e32 v0, 1.0, v114
	v_rcp_f32_e32 v114, v0
	v_add_f32_e32 v0, 1.0, v115
	v_rcp_f32_e32 v115, v0
	v_lshl_add_u32 v0, v129, 2, s96
	v_pk_mul_f32 v[106:107], v[108:109], v[106:107]
	v_pk_mul_f32 v[108:109], v[74:75], v[110:111]
	ds_read2st64_b32 v[74:75], v0 offset1:1
	v_pk_mul_f32 v[110:111], v[114:115], v[112:113]
	ds_read2st64_b32 v[112:113], v0 offset0:2 offset1:3
	ds_read2st64_b32 v[114:115], v0 offset0:4 offset1:5
	ds_read2st64_b32 v[116:117], v0 offset0:6 offset1:7
	s_waitcnt lgkmcnt(7)
	v_mov_b32_e32 v119, v94
	v_lshlrev_b64 v[102:103], 11, v[124:125]
	s_waitcnt lgkmcnt(3)
	v_mov_b32_e32 v118, v74
	v_pk_add_f32 v[118:119], v[118:119], 0 op_sel_hi:[1,0]
	v_mov_b32_e32 v94, v75
	v_pk_add_f32 v[74:75], v[118:119], v[94:95]
	s_waitcnt lgkmcnt(2)
	v_mov_b32_e32 v94, v112
	v_mov_b32_e32 v95, v96
	v_pk_add_f32 v[74:75], v[74:75], v[94:95]
	v_mov_b32_e32 v96, v113
	v_pk_add_f32 v[74:75], v[74:75], v[96:97]
	s_waitcnt lgkmcnt(1)
	v_mov_b32_e32 v94, v114
	v_mov_b32_e32 v95, v98
	v_pk_add_f32 v[74:75], v[74:75], v[94:95]
	v_mov_b32_e32 v98, v115
	v_pk_add_f32 v[74:75], v[74:75], v[98:99]
	s_waitcnt lgkmcnt(0)
	v_mov_b32_e32 v94, v116
	v_mov_b32_e32 v95, v100
	v_pk_add_f32 v[74:75], v[74:75], v[94:95]
	v_mov_b32_e32 v100, v117
	v_pk_add_f32 v[94:95], v[74:75], v[100:101]
	v_mov_b64_e32 v[74:75], s[60:61]
	v_pk_fma_f32 v[94:95], v[94:95], s[58:59], v[74:75] op_sel_hi:[1,0,0]
	v_ashrrev_i32_e32 v133, 31, v132
	v_mul_f32_e32 v0, 0x4b800000, v95
	v_cmp_gt_f32_e32 vcc, s59, v95
	v_lshl_add_u64 v[102:103], s[28:29], 0, v[102:103]
	s_lshl_b32 s38, s2, 1
	v_cndmask_b32_e32 v0, v95, v0, vcc
	v_rsq_f32_e32 v0, v0
	v_pk_mul_f32 v[104:105], v[72:73], v[104:105]
	v_lshl_add_u64 v[102:103], v[102:103], 0, s[38:39]
	v_lshlrev_b64 v[72:73], 1, v[132:133]
	v_mul_f32_e32 v95, 0x45800000, v0
	v_cndmask_b32_e32 v0, v0, v95, vcc
	v_pk_mul_f32 v[80:81], v[80:81], v[0:1] op_sel_hi:[1,0]
	v_pk_mul_f32 v[82:83], v[82:83], v[0:1] op_sel_hi:[1,0]
	v_pk_mul_f32 v[76:77], v[76:77], v[0:1] op_sel_hi:[1,0]
	v_pk_mul_f32 v[78:79], v[78:79], v[0:1] op_sel_hi:[1,0]
	s_waitcnt vmcnt(0)
	v_pk_mul_f32 v[80:81], v[248:249], v[80:81]
	v_pk_mul_f32 v[82:83], v[250:251], v[82:83]
	v_pk_mul_f32 v[76:77], v[252:253], v[76:77]
	v_pk_mul_f32 v[78:79], v[254:255], v[78:79]
	v_lshl_add_u64 v[96:97], v[102:103], 0, v[72:73]
	v_mov_b32_e32 v127, v1
	v_pk_mul_f32 v[80:81], v[104:105], v[80:81]
	v_pk_mul_f32 v[82:83], v[106:107], v[82:83]
	v_pk_mul_f32 v[76:77], v[108:109], v[76:77]
	v_pk_mul_f32 v[78:79], v[110:111], v[78:79]
	v_lshl_add_u64 v[96:97], v[96:97], 0, v[126:127]
	v_cvt_pk_bf16_f32 v80, v80, v81
	v_cvt_pk_bf16_f32 v81, v82, v83
	v_cvt_pk_bf16_f32 v82, v76, v77
	v_cvt_pk_bf16_f32 v83, v78, v79
	global_store_dwordx4 v[96:97], v[80:83], off
	s_nop 1
	s_nop 0
	s_nop 0
	s_nop 0
	v_lshlrev_b32_e32 v86, 16, v68
	v_and_b32_e32 v87, 0xffff0000, v68
	v_lshlrev_b32_e32 v68, 16, v69
	v_mul_f32_e32 v0, 0xbfb8aa3b, v86
	v_mul_f32_e32 v92, 0xbfb8aa3b, v68
	v_exp_f32_e32 v0, v0
	v_exp_f32_e32 v92, v92
	v_and_b32_e32 v69, 0xffff0000, v69
	v_lshlrev_b32_e32 v88, 16, v70
	v_and_b32_e32 v89, 0xffff0000, v70
	v_mul_f32_e32 v70, 0xbfb8aa3b, v87
	v_mul_f32_e32 v93, 0xbfb8aa3b, v69
	v_add_f32_e32 v0, 1.0, v0
	v_mul_f32_e32 v96, 0xbfb8aa3b, v89
	v_exp_f32_e32 v70, v70
	v_exp_f32_e32 v93, v93
	v_add_f32_e32 v97, 1.0, v92
	v_rcp_f32_e32 v92, v0
	v_mul_f32_e32 v0, 0x4b800000, v94
	v_cmp_gt_f32_e32 vcc, s59, v94
	v_exp_f32_e32 v96, v96
	v_add_f32_e32 v70, 1.0, v70
	v_cndmask_b32_e32 v0, v94, v0, vcc
	v_rsq_f32_e32 v0, v0
	v_add_f32_e32 v98, 1.0, v93
	v_add_f32_e32 v99, 1.0, v96
	v_rcp_f32_e32 v93, v70
	v_rcp_f32_e32 v96, v97
	v_rcp_f32_e32 v97, v98
	v_mul_f32_e32 v70, 0x45800000, v0
	v_cndmask_b32_e32 v0, v0, v70, vcc
	v_pk_mul_f32 v[64:65], v[64:65], v[0:1] op_sel_hi:[1,0]
	v_pk_mul_f32 v[66:67], v[66:67], v[0:1] op_sel_hi:[1,0]
	v_pk_mul_f32 v[86:87], v[92:93], v[86:87]
	v_pk_mul_f32 v[68:69], v[96:97], v[68:69]
	v_pk_mul_f32 v[60:61], v[60:61], v[0:1] op_sel_hi:[1,0]
	v_mul_f32_e32 v95, 0xbfb8aa3b, v88
	v_exp_f32_e32 v95, v95
	v_rcp_f32_e32 v99, v99
	v_mov_b32_e32 v131, v125
	v_pk_mul_f32 v[62:63], v[62:63], v[0:1] op_sel_hi:[1,0]
	v_add_f32_e32 v95, 1.0, v95
	v_rcp_f32_e32 v98, v95
	v_lshlrev_b64 v[90:91], 11, v[130:131]
	v_lshl_add_u64 v[90:91], s[28:29], 0, v[90:91]
	v_lshl_add_u32 v0, v177, 2, s96
	v_mov_b32_e32 v129, v125
	s_cmpk_gt_i32 s81, 0x3ff
	s_mov_b64 s[12:13], -1
	s_nop 0
	v_pk_mul_f32 v[64:65], v[248:249], v[64:65]
	v_pk_mul_f32 v[66:67], v[250:251], v[66:67]
	s_nop 0
	v_pk_mul_f32 v[76:77], v[252:253], v[60:61]
	v_pk_mul_f32 v[60:61], v[86:87], v[64:65]
	v_pk_mul_f32 v[64:65], v[68:69], v[66:67]
	v_cvt_pk_bf16_f32 v60, v60, v61
	v_cvt_pk_bf16_f32 v61, v64, v65
	v_lshlrev_b32_e32 v64, 16, v71
	v_and_b32_e32 v65, 0xffff0000, v71
	v_mul_f32_e32 v66, 0xbfb8aa3b, v64
	v_exp_f32_e32 v68, v66
	v_mul_f32_e32 v66, 0xbfb8aa3b, v65
	v_exp_f32_e32 v69, v66
	v_pk_mul_f32 v[62:63], v[254:255], v[62:63]
	v_add_f32_e32 v68, 1.0, v68
	v_rcp_f32_e32 v68, v68
	v_add_f32_e32 v69, 1.0, v69
	v_rcp_f32_e32 v69, v69
	v_pk_mul_f32 v[66:67], v[98:99], v[88:89]
	v_lshlrev_b32_e32 v82, 16, v56
	v_pk_mul_f32 v[66:67], v[66:67], v[76:77]
	v_pk_mul_f32 v[64:65], v[68:69], v[64:65]
	v_and_b32_e32 v83, 0xffff0000, v56
	v_pk_mul_f32 v[64:65], v[64:65], v[62:63]
	v_cvt_pk_bf16_f32 v62, v66, v67
	v_cvt_pk_bf16_f32 v63, v64, v65
	v_lshl_add_u64 v[64:65], v[90:91], 0, s[38:39]
	v_lshl_add_u64 v[64:65], v[64:65], 0, v[72:73]
	v_lshl_add_u64 v[64:65], v[64:65], 0, v[126:127]
	global_store_dwordx4 v[64:65], v[60:63], off
	s_nop 1
	ds_read2st64_b32 v[68:69], v0 offset1:1
	ds_read2st64_b32 v[70:71], v0 offset0:2 offset1:3
	ds_read2st64_b32 v[76:77], v0 offset0:4 offset1:5
	ds_read2st64_b32 v[78:79], v0 offset0:6 offset1:7
	s_nop 0
	s_nop 0
	v_mul_f32_e32 v0, 0xbfb8aa3b, v82
	v_exp_f32_e32 v0, v0
	v_mul_f32_e32 v56, 0xbfb8aa3b, v83
	v_exp_f32_e32 v56, v56
	v_and_b32_e32 v89, 0xffff0000, v58
	v_add_f32_e32 v0, 1.0, v0
	v_rcp_f32_e32 v86, v0
	v_add_f32_e32 v0, 1.0, v56
	v_lshlrev_b32_e32 v56, 16, v57
	v_rcp_f32_e32 v87, v0
	v_and_b32_e32 v57, 0xffff0000, v57
	v_mul_f32_e32 v0, 0xbfb8aa3b, v56
	v_exp_f32_e32 v0, v0
	v_mul_f32_e32 v88, 0xbfb8aa3b, v57
	v_exp_f32_e32 v88, v88
	v_pk_mul_f32 v[82:83], v[86:87], v[82:83]
	v_add_f32_e32 v0, 1.0, v0
	v_rcp_f32_e32 v86, v0
	v_add_f32_e32 v0, 1.0, v88
	v_lshlrev_b32_e32 v88, 16, v58
	v_rcp_f32_e32 v87, v0
	v_mul_f32_e32 v0, 0xbfb8aa3b, v88
	v_exp_f32_e32 v0, v0
	v_mul_f32_e32 v58, 0xbfb8aa3b, v89
	v_exp_f32_e32 v90, v58
	v_pk_mul_f32 v[56:57], v[86:87], v[56:57]
	v_lshlrev_b32_e32 v86, 16, v59
	v_add_f32_e32 v0, 1.0, v0
	v_and_b32_e32 v87, 0xffff0000, v59
	v_mul_f32_e32 v59, 0xbfb8aa3b, v86
	v_rcp_f32_e32 v58, v0
	v_add_f32_e32 v0, 1.0, v90
	v_exp_f32_e32 v90, v59
	v_mul_f32_e32 v59, 0xbfb8aa3b, v87
	v_exp_f32_e32 v91, v59
	v_rcp_f32_e32 v59, v0
	v_add_f32_e32 v0, 1.0, v90
	v_rcp_f32_e32 v90, v0
	v_add_f32_e32 v0, 1.0, v91
	v_rcp_f32_e32 v91, v0
	v_lshl_add_u32 v0, v3, 2, s96
	v_pk_mul_f32 v[58:59], v[58:59], v[88:89]
	ds_read2st64_b32 v[88:89], v0 offset1:1
	v_pk_mul_f32 v[86:87], v[90:91], v[86:87]
	ds_read2st64_b32 v[90:91], v0 offset0:2 offset1:3
	ds_read2st64_b32 v[92:93], v0 offset0:4 offset1:5
	ds_read2st64_b32 v[94:95], v0 offset0:6 offset1:7
	s_waitcnt lgkmcnt(7)
	v_mov_b32_e32 v97, v68
	v_lshlrev_b64 v[80:81], 11, v[128:129]
	s_waitcnt lgkmcnt(3)
	v_mov_b32_e32 v96, v88
	v_pk_add_f32 v[96:97], v[96:97], 0 op_sel_hi:[1,0]
	v_mov_b32_e32 v68, v89
	v_pk_add_f32 v[68:69], v[96:97], v[68:69]
	s_waitcnt lgkmcnt(2)
	v_mov_b32_e32 v88, v90
	v_mov_b32_e32 v89, v70
	v_pk_add_f32 v[68:69], v[68:69], v[88:89]
	v_mov_b32_e32 v70, v91
	v_pk_add_f32 v[68:69], v[68:69], v[70:71]
	s_waitcnt lgkmcnt(1)
	v_mov_b32_e32 v70, v92
	v_mov_b32_e32 v71, v76
	v_pk_add_f32 v[68:69], v[68:69], v[70:71]
	v_mov_b32_e32 v76, v93
	v_pk_add_f32 v[68:69], v[68:69], v[76:77]
	s_waitcnt lgkmcnt(0)
	v_mov_b32_e32 v70, v94
	v_mov_b32_e32 v71, v78
	v_pk_add_f32 v[68:69], v[68:69], v[70:71]
	v_mov_b32_e32 v78, v95
	v_pk_add_f32 v[68:69], v[68:69], v[78:79]
	v_lshl_add_u64 v[80:81], s[28:29], 0, v[80:81]
	v_pk_fma_f32 v[68:69], v[68:69], s[58:59], v[74:75] op_sel_hi:[1,0,0]
	v_lshl_add_u64 v[70:71], v[80:81], 0, s[38:39]
	v_mul_f32_e32 v0, 0x4b800000, v69
	v_cmp_gt_f32_e32 vcc, s59, v69
	v_lshl_add_u64 v[70:71], v[70:71], 0, v[72:73]
	v_lshl_add_u64 v[70:71], v[70:71], 0, v[126:127]
	v_cndmask_b32_e32 v0, v69, v0, vcc
	v_rsq_f32_e32 v0, v0
	s_nop 0
	v_mul_f32_e32 v3, 0x45800000, v0
	v_cndmask_b32_e32 v0, v0, v3, vcc
	v_pk_mul_f32 v[52:53], v[52:53], v[0:1] op_sel_hi:[1,0]
	v_pk_mul_f32 v[54:55], v[54:55], v[0:1] op_sel_hi:[1,0]
	v_pk_mul_f32 v[48:49], v[48:49], v[0:1] op_sel_hi:[1,0]
	v_pk_mul_f32 v[50:51], v[50:51], v[0:1] op_sel_hi:[1,0]
	s_nop 0
	v_pk_mul_f32 v[52:53], v[248:249], v[52:53]
	v_pk_mul_f32 v[54:55], v[250:251], v[54:55]
	v_pk_mul_f32 v[48:49], v[252:253], v[48:49]
	v_pk_mul_f32 v[50:51], v[254:255], v[50:51]
	v_pk_mul_f32 v[52:53], v[82:83], v[52:53]
	v_pk_mul_f32 v[54:55], v[56:57], v[54:55]
	v_pk_mul_f32 v[48:49], v[58:59], v[48:49]
	v_pk_mul_f32 v[50:51], v[86:87], v[50:51]
	v_cvt_pk_bf16_f32 v52, v52, v53
	v_cvt_pk_bf16_f32 v53, v54, v55
	v_cvt_pk_bf16_f32 v54, v48, v49
	v_cvt_pk_bf16_f32 v55, v50, v51
	global_store_dwordx4 v[70:71], v[52:55], off
	s_nop 1
	s_nop 0
	s_nop 0
	s_nop 0
	v_lshlrev_b32_e32 v56, 16, v44
	v_and_b32_e32 v57, 0xffff0000, v44
	v_lshlrev_b32_e32 v44, 16, v45
	v_mul_f32_e32 v0, 0xbfb8aa3b, v56
	v_mul_f32_e32 v60, 0xbfb8aa3b, v44
	v_exp_f32_e32 v0, v0
	v_exp_f32_e32 v60, v60
	v_and_b32_e32 v45, 0xffff0000, v45
	v_mul_f32_e32 v61, 0xbfb8aa3b, v45
	v_add_f32_e32 v0, 1.0, v0
	v_mul_f32_e32 v59, 0xbfb8aa3b, v57
	v_exp_f32_e32 v61, v61
	v_add_f32_e32 v62, 1.0, v60
	v_rcp_f32_e32 v60, v0
	v_mul_f32_e32 v0, 0x4b800000, v68
	v_cmp_gt_f32_e32 vcc, s59, v68
	v_exp_f32_e32 v59, v59
	v_add_f32_e32 v63, 1.0, v61
	v_cndmask_b32_e32 v0, v68, v0, vcc
	v_rsq_f32_e32 v0, v0
	v_add_f32_e32 v59, 1.0, v59
	v_rcp_f32_e32 v62, v62
	v_rcp_f32_e32 v63, v63
	v_rcp_f32_e32 v61, v59
	v_mul_f32_e32 v59, 0x45800000, v0
	v_cndmask_b32_e32 v0, v0, v59, vcc
	v_pk_mul_f32 v[42:43], v[42:43], v[0:1] op_sel_hi:[1,0]
	v_lshlrev_b32_e32 v58, 16, v46
	v_pk_mul_f32 v[44:45], v[62:63], v[44:45]
	v_pk_mul_f32 v[40:41], v[40:41], v[0:1] op_sel_hi:[1,0]
	v_pk_mul_f32 v[56:57], v[60:61], v[56:57]
	v_and_b32_e32 v59, 0xffff0000, v46
	v_mov_b32_e32 v3, v125
	v_lshlrev_b64 v[2:3], 11, v[2:3]
	v_pk_mul_f32 v[36:37], v[36:37], v[0:1] op_sel_hi:[1,0]
	v_lshl_add_u64 v[2:3], s[28:29], 0, v[2:3]
	v_pk_mul_f32 v[38:39], v[38:39], v[0:1] op_sel_hi:[1,0]
	v_lshl_add_u64 v[2:3], v[2:3], 0, s[38:39]
	v_lshl_add_u64 v[2:3], v[2:3], 0, v[72:73]
	v_lshl_add_u64 v[2:3], v[2:3], 0, v[126:127]
	s_nop 0
	v_pk_mul_f32 v[42:43], v[250:251], v[42:43]
	s_nop 0
	v_pk_mul_f32 v[42:43], v[44:45], v[42:43]
	v_mul_f32_e32 v44, 0xbfb8aa3b, v58
	v_exp_f32_e32 v44, v44
	v_pk_mul_f32 v[40:41], v[248:249], v[40:41]
	v_and_b32_e32 v45, 0xffff0000, v47
	v_pk_mul_f32 v[40:41], v[56:57], v[40:41]
	s_nop 0
	v_pk_mul_f32 v[36:37], v[252:253], v[36:37]
	v_cvt_pk_bf16_f32 v40, v40, v41
	v_cvt_pk_bf16_f32 v41, v42, v43
	v_add_f32_e32 v42, 1.0, v44
	v_mul_f32_e32 v43, 0xbfb8aa3b, v59
	v_lshlrev_b32_e32 v44, 16, v47
	v_exp_f32_e32 v43, v43
	v_mul_f32_e32 v46, 0xbfb8aa3b, v44
	v_mul_f32_e32 v47, 0xbfb8aa3b, v45
	v_exp_f32_e32 v46, v46
	v_exp_f32_e32 v47, v47
	v_add_f32_e32 v43, 1.0, v43
	v_rcp_f32_e32 v42, v42
	v_rcp_f32_e32 v43, v43
	v_add_f32_e32 v46, 1.0, v46
	v_add_f32_e32 v47, 1.0, v47
	v_rcp_f32_e32 v46, v46
	v_rcp_f32_e32 v47, v47
	v_pk_mul_f32 v[42:43], v[42:43], v[58:59]
	v_pk_mul_f32 v[38:39], v[254:255], v[38:39]
	v_pk_mul_f32 v[36:37], v[42:43], v[36:37]
	v_pk_mul_f32 v[42:43], v[46:47], v[44:45]
	s_nop 0
	v_pk_mul_f32 v[38:39], v[42:43], v[38:39]
	v_cvt_pk_bf16_f32 v42, v36, v37
	v_cvt_pk_bf16_f32 v43, v38, v39
	global_store_dwordx4 v[2:3], v[40:43], off
	s_nop 1
	s_barrier
	s_cbranch_scc1 .LBB0_1595
	s_add_i32 s2, s74, s82
	s_cmpk_gt_i32 s2, 0x3ff
	s_cbranch_scc1 .LBB0_1637
	v_mov_b32_e32 v0, v204
	s_ashr_i32 s12, s2, 8
	v_ashrrev_i32_e32 v2, 31, v0
	v_lshrrev_b32_e32 v2, 27, v2
	v_add_u32_e32 v3, v0, v2
	s_ashr_i32 s13, s12, 31
	s_add_i32 s2, s75, s80
	v_ashrrev_i32_e32 v2, 5, v3
	v_and_b32_e32 v3, 0x1fffffe0, v3
	s_lshl_b64 s[12:13], s[12:13], 12
	s_and_b32 s2, s2, 0xfc0
	v_sub_u32_e32 v3, v0, v3
	s_or_b32 s12, s12, s2
	v_lshlrev_b32_e32 v4, 3, v3
	v_ashrrev_i32_e32 v3, 31, v2
	s_add_i32 s2, s76, s79
	v_lshl_add_u64 v[2:3], s[12:13], 0, v[2:3]
	v_mov_b64_e32 v[20:21], s[30:31]
	s_and_b32 s2, s2, 0x300
	v_mad_u64_u32 v[6:7], s[14:15], v2, s33, v[20:21]
	v_mad_i32_i24 v7, v3, s33, v7
	s_lshl_b32 s38, s2, 1
	v_lshl_add_u64 v[2:3], v[6:7], 0, s[38:39]
	v_ashrrev_i32_e32 v5, 31, v4
	v_lshl_add_u64 v[2:3], v[4:5], 1, v[2:3]
	v_add_u32_e32 v5, 0x200, v0
	v_ashrrev_i32_e32 v4, 31, v5
	v_lshrrev_b32_e32 v4, 27, v4
	v_add_u32_e32 v6, v5, v4
	v_ashrrev_i32_e32 v4, 5, v6
	v_and_b32_e32 v6, 0x1fffffe0, v6
	v_sub_u32_e32 v5, v5, v6
	v_lshlrev_b32_e32 v6, 3, v5
	v_ashrrev_i32_e32 v5, 31, v4
	v_lshl_add_u64 v[4:5], s[12:13], 0, v[4:5]
	v_mad_u64_u32 v[8:9], s[14:15], v4, s33, v[20:21]
	v_mad_i32_i24 v9, v5, s33, v9
	v_add_co_u32_e32 v2, vcc, s34, v2
	v_lshl_add_u64 v[4:5], v[8:9], 0, s[38:39]
	v_ashrrev_i32_e32 v7, 31, v6
	v_addc_co_u32_e32 v3, vcc, 0, v3, vcc
	v_lshl_add_u64 v[4:5], v[6:7], 1, v[4:5]
	v_add_co_u32_e32 v8, vcc, s34, v4
	s_nop 1
	v_addc_co_u32_e32 v9, vcc, 0, v5, vcc
	global_load_dwordx4 v[4:7], v[2:3], off offset:2048
	s_nop 0
	global_load_dwordx4 v[8:11], v[8:9], off offset:2048
	v_add_u32_e32 v3, 0x400, v0
	v_ashrrev_i32_e32 v2, 31, v3
	v_lshrrev_b32_e32 v2, 27, v2
	v_add_u32_e32 v22, v3, v2
	v_ashrrev_i32_e32 v2, 5, v22
	v_and_b32_e32 v22, 0x1fffffe0, v22
	v_sub_u32_e32 v3, v3, v22
	v_lshlrev_b32_e32 v22, 3, v3
	v_ashrrev_i32_e32 v3, 31, v2
	v_lshl_add_u64 v[2:3], s[12:13], 0, v[2:3]
	v_mad_u64_u32 v[24:25], s[14:15], v2, s33, v[20:21]
	v_mad_i32_i24 v25, v3, s33, v25
	v_lshl_add_u64 v[2:3], v[24:25], 0, s[38:39]
	v_ashrrev_i32_e32 v23, 31, v22
	v_add_u32_e32 v0, 0x600, v0
	v_lshl_add_u64 v[2:3], v[22:23], 1, v[2:3]
	v_ashrrev_i32_e32 v22, 31, v0
	v_lshrrev_b32_e32 v22, 27, v22
	v_add_u32_e32 v23, v0, v22
	v_ashrrev_i32_e32 v22, 5, v23
	v_and_b32_e32 v23, 0x1fffffe0, v23
	v_sub_u32_e32 v0, v0, v23
	v_ashrrev_i32_e32 v23, 31, v22
	v_lshl_add_u64 v[22:23], s[12:13], 0, v[22:23]
	v_mad_u64_u32 v[20:21], s[12:13], v22, s33, v[20:21]
	v_lshlrev_b32_e32 v24, 3, v0
	v_mad_i32_i24 v21, v23, s33, v21
	v_add_co_u32_e32 v2, vcc, s34, v2
	v_lshl_add_u64 v[20:21], v[20:21], 0, s[38:39]
	v_ashrrev_i32_e32 v25, 31, v24
	v_addc_co_u32_e32 v3, vcc, 0, v3, vcc
	v_lshl_add_u64 v[20:21], v[24:25], 1, v[20:21]
	v_add_co_u32_e32 v24, vcc, 0x7a00000, v20
	s_nop 1
	v_addc_co_u32_e32 v25, vcc, 0, v21, vcc
	global_load_dwordx4 v[20:23], v[2:3], off offset:2048
	s_nop 0
	global_load_dwordx4 v[24:27], v[24:25], off offset:2048

.LBB0_1737:
	s_or_b64 exec, exec, s[8:9]
	s_add_i32 s49, s47, s22
	s_lshl_b32 s8, s2, 2
	s_add_u32 s8, s26, s8
	s_addc_u32 s9, s27, 0
	v_lshl_add_u32 v8, v131, 2, s96
	v_lshl_add_u64 v[84:85], v[84:85], 2, s[8:9]
	s_waitcnt lgkmcnt(0)
	s_barrier
	ds_read2st64_b32 v[94:95], v8 offset1:1
	ds_read2st64_b32 v[96:97], v8 offset0:2 offset1:3
	ds_read2st64_b32 v[98:99], v8 offset0:4 offset1:5
	ds_read2st64_b32 v[100:101], v8 offset0:6 offset1:7
	global_load_dwordx4 v[252:255], v[84:85], off offset:16
	global_load_dwordx4 v[248:251], v[84:85], off
	s_waitcnt vmcnt(5)
	v_lshlrev_b32_e32 v104, 16, v72
	v_and_b32_e32 v105, 0xffff0000, v72
	v_mul_f32_e32 v8, 0xbfb8aa3b, v104
	v_lshlrev_b64 v[102:103], 11, v[10:11]
	v_exp_f32_e32 v8, v8
	v_mul_f32_e32 v10, 0xbfb8aa3b, v105
	v_exp_f32_e32 v10, v10
	v_lshlrev_b32_e32 v106, 16, v73
	v_add_f32_e32 v8, 1.0, v8
	v_rcp_f32_e32 v72, v8
	v_add_f32_e32 v8, 1.0, v10
	v_mul_f32_e32 v10, 0xbfb8aa3b, v106
	v_exp_f32_e32 v10, v10
	v_and_b32_e32 v107, 0xffff0000, v73
	v_mul_f32_e32 v73, 0xbfb8aa3b, v107
	v_lshlrev_b32_e32 v110, 16, v74
	v_exp_f32_e32 v109, v73
	v_rcp_f32_e32 v73, v8
	v_add_f32_e32 v8, 1.0, v10
	v_and_b32_e32 v111, 0xffff0000, v74
	v_mul_f32_e32 v10, 0xbfb8aa3b, v110
	v_exp_f32_e32 v10, v10
	v_mul_f32_e32 v74, 0xbfb8aa3b, v111
	v_exp_f32_e32 v112, v74
	v_rcp_f32_e32 v108, v8
	v_add_f32_e32 v8, 1.0, v109
	v_rcp_f32_e32 v109, v8
	v_add_f32_e32 v8, 1.0, v10
	v_rcp_f32_e32 v74, v8
	v_add_f32_e32 v8, 1.0, v112
	v_lshlrev_b32_e32 v112, 16, v75
	v_and_b32_e32 v113, 0xffff0000, v75
	v_mul_f32_e32 v10, 0xbfb8aa3b, v112
	v_exp_f32_e32 v10, v10
	v_mul_f32_e32 v75, 0xbfb8aa3b, v113
	v_exp_f32_e32 v115, v75
	v_rcp_f32_e32 v75, v8
	v_add_f32_e32 v8, 1.0, v10
	v_rcp_f32_e32 v114, v8
	v_add_f32_e32 v8, 1.0, v115
	v_rcp_f32_e32 v115, v8
	v_lshl_add_u32 v8, v129, 2, s96
	v_pk_mul_f32 v[106:107], v[108:109], v[106:107]
	v_pk_mul_f32 v[108:109], v[74:75], v[110:111]
	ds_read2st64_b32 v[74:75], v8 offset1:1
	v_pk_mul_f32 v[110:111], v[114:115], v[112:113]
	ds_read2st64_b32 v[112:113], v8 offset0:2 offset1:3
	ds_read2st64_b32 v[114:115], v8 offset0:4 offset1:5
	ds_read2st64_b32 v[116:117], v8 offset0:6 offset1:7
	s_waitcnt lgkmcnt(7)
	v_mov_b32_e32 v119, v94
	v_ashrrev_i32_e32 v133, 31, v132
	s_waitcnt lgkmcnt(3)
	v_mov_b32_e32 v118, v74
	v_pk_add_f32 v[118:119], v[118:119], 0 op_sel_hi:[1,0]
	v_mov_b32_e32 v94, v75
	v_pk_add_f32 v[74:75], v[118:119], v[94:95]
	s_waitcnt lgkmcnt(2)
	v_mov_b32_e32 v94, v112
	v_mov_b32_e32 v95, v96
	v_pk_add_f32 v[74:75], v[74:75], v[94:95]
	v_mov_b32_e32 v96, v113
	v_pk_add_f32 v[74:75], v[74:75], v[96:97]
	s_waitcnt lgkmcnt(1)
	v_mov_b32_e32 v94, v114
	v_mov_b32_e32 v95, v98
	v_pk_add_f32 v[74:75], v[74:75], v[94:95]
	v_mov_b32_e32 v98, v115
	v_pk_add_f32 v[74:75], v[74:75], v[98:99]
	s_waitcnt lgkmcnt(0)
	v_mov_b32_e32 v94, v116
	v_mov_b32_e32 v95, v100
	v_pk_add_f32 v[74:75], v[74:75], v[94:95]
	v_mov_b32_e32 v100, v117
	v_pk_add_f32 v[94:95], v[74:75], v[100:101]
	v_mov_b64_e32 v[74:75], s[48:49]
	v_pk_fma_f32 v[94:95], v[94:95], s[46:47], v[74:75] op_sel_hi:[1,0,0]
	v_lshl_add_u64 v[102:103], s[28:29], 0, v[102:103]
	v_mul_f32_e32 v8, 0x4b800000, v95
	v_cmp_gt_f32_e32 vcc, s45, v95
	s_lshl_b32 s38, s2, 1
	v_pk_mul_f32 v[104:105], v[72:73], v[104:105]
	v_cndmask_b32_e32 v8, v95, v8, vcc
	v_rsq_f32_e32 v8, v8
	v_lshl_add_u64 v[102:103], v[102:103], 0, s[38:39]
	v_lshlrev_b64 v[72:73], 1, v[132:133]
	v_lshl_add_u64 v[96:97], v[102:103], 0, v[72:73]
	v_mul_f32_e32 v10, 0x45800000, v8
	v_cndmask_b32_e32 v8, v8, v10, vcc
	v_pk_mul_f32 v[80:81], v[80:81], v[8:9] op_sel_hi:[1,0]
	v_pk_mul_f32 v[82:83], v[82:83], v[8:9] op_sel_hi:[1,0]
	v_pk_mul_f32 v[76:77], v[76:77], v[8:9] op_sel_hi:[1,0]
	v_pk_mul_f32 v[78:79], v[78:79], v[8:9] op_sel_hi:[1,0]
	s_waitcnt vmcnt(0)
	v_pk_mul_f32 v[80:81], v[248:249], v[80:81]
	v_pk_mul_f32 v[82:83], v[250:251], v[82:83]
	v_pk_mul_f32 v[76:77], v[252:253], v[76:77]
	v_pk_mul_f32 v[78:79], v[254:255], v[78:79]
	v_mov_b32_e32 v127, v9
	v_pk_mul_f32 v[80:81], v[104:105], v[80:81]
	v_pk_mul_f32 v[82:83], v[106:107], v[82:83]
	v_pk_mul_f32 v[76:77], v[108:109], v[76:77]
	v_pk_mul_f32 v[78:79], v[110:111], v[78:79]
	v_lshl_add_u64 v[96:97], v[96:97], 0, v[126:127]
	v_cvt_pk_bf16_f32 v80, v80, v81
	v_cvt_pk_bf16_f32 v81, v82, v83
	v_cvt_pk_bf16_f32 v82, v76, v77
	v_cvt_pk_bf16_f32 v83, v78, v79
	global_store_dwordx4 v[96:97], v[80:83], off
	s_nop 1
	s_nop 0
	s_nop 0
	s_nop 0
	v_lshlrev_b32_e32 v86, 16, v68
	v_and_b32_e32 v87, 0xffff0000, v68
	v_lshlrev_b32_e32 v68, 16, v69
	v_and_b32_e32 v69, 0xffff0000, v69
	v_mul_f32_e32 v8, 0xbfb8aa3b, v86
	v_mul_f32_e32 v92, 0xbfb8aa3b, v69
	v_exp_f32_e32 v8, v8
	v_exp_f32_e32 v92, v92
	v_lshlrev_b32_e32 v88, 16, v70
	v_and_b32_e32 v89, 0xffff0000, v70
	v_mul_f32_e32 v10, 0xbfb8aa3b, v87
	v_mul_f32_e32 v70, 0xbfb8aa3b, v68
	v_add_f32_e32 v8, 1.0, v8
	v_mul_f32_e32 v93, 0xbfb8aa3b, v88
	v_exp_f32_e32 v10, v10
	v_exp_f32_e32 v70, v70
	v_add_f32_e32 v97, 1.0, v92
	v_rcp_f32_e32 v92, v8
	v_mul_f32_e32 v8, 0x4b800000, v94
	v_cmp_gt_f32_e32 vcc, s45, v94
	v_exp_f32_e32 v93, v93
	v_add_f32_e32 v10, 1.0, v10
	v_cndmask_b32_e32 v8, v94, v8, vcc
	v_rsq_f32_e32 v8, v8
	v_add_f32_e32 v70, 1.0, v70
	v_add_f32_e32 v98, 1.0, v93
	v_rcp_f32_e32 v93, v10
	v_rcp_f32_e32 v96, v70
	v_rcp_f32_e32 v97, v97
	v_mul_f32_e32 v10, 0x45800000, v8
	v_cndmask_b32_e32 v8, v8, v10, vcc
	v_pk_mul_f32 v[64:65], v[64:65], v[8:9] op_sel_hi:[1,0]
	v_pk_mul_f32 v[66:67], v[66:67], v[8:9] op_sel_hi:[1,0]
	v_pk_mul_f32 v[86:87], v[92:93], v[86:87]
	v_pk_mul_f32 v[68:69], v[96:97], v[68:69]
	v_pk_mul_f32 v[60:61], v[60:61], v[8:9] op_sel_hi:[1,0]
	v_mul_f32_e32 v95, 0xbfb8aa3b, v89
	v_exp_f32_e32 v95, v95
	v_rcp_f32_e32 v94, v98
	v_mov_b32_e32 v131, v11
	v_pk_mul_f32 v[62:63], v[62:63], v[8:9] op_sel_hi:[1,0]
	v_add_f32_e32 v95, 1.0, v95
	v_rcp_f32_e32 v95, v95
	v_lshlrev_b64 v[90:91], 11, v[130:131]
	v_lshl_add_u64 v[90:91], s[28:29], 0, v[90:91]
	v_lshl_add_u32 v8, v177, 2, s96
	v_mov_b32_e32 v129, v11
	s_add_i32 s3, s3, s88
	s_add_i32 s72, s72, s83
	s_cmpk_gt_i32 s49, 0x3ff
	s_cselect_b64 s[8:9], -1, 0
	s_nop 0
	v_pk_mul_f32 v[64:65], v[248:249], v[64:65]
	v_pk_mul_f32 v[66:67], v[250:251], v[66:67]
	s_nop 0
	v_pk_mul_f32 v[76:77], v[252:253], v[60:61]
	v_pk_mul_f32 v[60:61], v[86:87], v[64:65]
	v_pk_mul_f32 v[64:65], v[68:69], v[66:67]
	v_cvt_pk_bf16_f32 v60, v60, v61
	v_cvt_pk_bf16_f32 v61, v64, v65
	v_lshlrev_b32_e32 v64, 16, v71
	v_and_b32_e32 v65, 0xffff0000, v71
	v_mul_f32_e32 v10, 0xbfb8aa3b, v64
	v_exp_f32_e32 v10, v10
	v_mul_f32_e32 v66, 0xbfb8aa3b, v65
	v_exp_f32_e32 v69, v66
	v_pk_mul_f32 v[62:63], v[254:255], v[62:63]
	v_add_f32_e32 v10, 1.0, v10
	v_rcp_f32_e32 v68, v10
	v_add_f32_e32 v10, 1.0, v69
	v_rcp_f32_e32 v69, v10
	v_pk_mul_f32 v[66:67], v[94:95], v[88:89]
	v_lshlrev_b32_e32 v82, 16, v56
	v_pk_mul_f32 v[66:67], v[66:67], v[76:77]
	v_pk_mul_f32 v[64:65], v[68:69], v[64:65]
	v_and_b32_e32 v83, 0xffff0000, v56
	v_pk_mul_f32 v[64:65], v[64:65], v[62:63]
	v_cvt_pk_bf16_f32 v62, v66, v67
	v_cvt_pk_bf16_f32 v63, v64, v65
	v_lshl_add_u64 v[64:65], v[90:91], 0, s[38:39]
	v_lshl_add_u64 v[64:65], v[64:65], 0, v[72:73]
	v_lshl_add_u64 v[64:65], v[64:65], 0, v[126:127]
	global_store_dwordx4 v[64:65], v[60:63], off
	s_nop 1
	ds_read2st64_b32 v[68:69], v8 offset1:1
	ds_read2st64_b32 v[70:71], v8 offset0:2 offset1:3
	ds_read2st64_b32 v[76:77], v8 offset0:4 offset1:5
	ds_read2st64_b32 v[78:79], v8 offset0:6 offset1:7
	s_nop 0
	s_nop 0
	v_mul_f32_e32 v8, 0xbfb8aa3b, v82
	v_exp_f32_e32 v8, v8
	v_mul_f32_e32 v10, 0xbfb8aa3b, v83
	v_exp_f32_e32 v10, v10
	v_lshlrev_b32_e32 v56, 16, v57
	v_add_f32_e32 v8, 1.0, v8
	v_rcp_f32_e32 v86, v8
	v_add_f32_e32 v8, 1.0, v10
	v_rcp_f32_e32 v87, v8
	v_and_b32_e32 v57, 0xffff0000, v57
	v_mul_f32_e32 v8, 0xbfb8aa3b, v56
	v_exp_f32_e32 v8, v8
	v_mul_f32_e32 v10, 0xbfb8aa3b, v57
	v_exp_f32_e32 v10, v10
	v_pk_mul_f32 v[82:83], v[86:87], v[82:83]
	v_add_f32_e32 v8, 1.0, v8
	v_rcp_f32_e32 v86, v8
	v_add_f32_e32 v8, 1.0, v10
	v_lshlrev_b32_e32 v88, 16, v58
	v_rcp_f32_e32 v87, v8
	v_and_b32_e32 v89, 0xffff0000, v58
	v_mul_f32_e32 v8, 0xbfb8aa3b, v88
	v_exp_f32_e32 v8, v8
	v_mul_f32_e32 v10, 0xbfb8aa3b, v89
	v_exp_f32_e32 v10, v10
	v_pk_mul_f32 v[56:57], v[86:87], v[56:57]
	v_add_f32_e32 v8, 1.0, v8
	v_lshlrev_b32_e32 v86, 16, v59
	v_rcp_f32_e32 v58, v8
	v_add_f32_e32 v8, 1.0, v10
	v_and_b32_e32 v87, 0xffff0000, v59
	v_mul_f32_e32 v10, 0xbfb8aa3b, v86
	v_exp_f32_e32 v10, v10
	v_mul_f32_e32 v59, 0xbfb8aa3b, v87
	v_exp_f32_e32 v91, v59
	v_rcp_f32_e32 v59, v8
	v_add_f32_e32 v8, 1.0, v10
	v_rcp_f32_e32 v90, v8
	v_add_f32_e32 v8, 1.0, v91
	v_rcp_f32_e32 v91, v8
	v_lshl_add_u32 v8, v125, 2, s96
	v_pk_mul_f32 v[58:59], v[58:59], v[88:89]
	ds_read2st64_b32 v[88:89], v8 offset1:1
	v_pk_mul_f32 v[86:87], v[90:91], v[86:87]
	ds_read2st64_b32 v[90:91], v8 offset0:2 offset1:3
	ds_read2st64_b32 v[92:93], v8 offset0:4 offset1:5
	ds_read2st64_b32 v[94:95], v8 offset0:6 offset1:7
	s_waitcnt lgkmcnt(7)
	v_mov_b32_e32 v97, v68
	v_lshlrev_b64 v[80:81], 11, v[128:129]
	s_waitcnt lgkmcnt(3)
	v_mov_b32_e32 v96, v88
	v_pk_add_f32 v[96:97], v[96:97], 0 op_sel_hi:[1,0]
	v_mov_b32_e32 v68, v89
	v_pk_add_f32 v[68:69], v[96:97], v[68:69]
	s_waitcnt lgkmcnt(2)
	v_mov_b32_e32 v88, v90
	v_mov_b32_e32 v89, v70
	v_pk_add_f32 v[68:69], v[68:69], v[88:89]
	v_mov_b32_e32 v70, v91
	v_pk_add_f32 v[68:69], v[68:69], v[70:71]
	s_waitcnt lgkmcnt(1)
	v_mov_b32_e32 v70, v92
	v_mov_b32_e32 v71, v76
	v_pk_add_f32 v[68:69], v[68:69], v[70:71]
	v_mov_b32_e32 v76, v93
	v_pk_add_f32 v[68:69], v[68:69], v[76:77]
	s_waitcnt lgkmcnt(0)
	v_mov_b32_e32 v70, v94
	v_mov_b32_e32 v71, v78
	v_pk_add_f32 v[68:69], v[68:69], v[70:71]
	v_mov_b32_e32 v78, v95
	v_pk_add_f32 v[68:69], v[68:69], v[78:79]
	v_lshl_add_u64 v[80:81], s[28:29], 0, v[80:81]
	v_pk_fma_f32 v[68:69], v[68:69], s[46:47], v[74:75] op_sel_hi:[1,0,0]
	v_lshl_add_u64 v[70:71], v[80:81], 0, s[38:39]
	v_mul_f32_e32 v8, 0x4b800000, v69
	v_cmp_gt_f32_e32 vcc, s45, v69
	v_lshl_add_u64 v[70:71], v[70:71], 0, v[72:73]
	v_lshl_add_u64 v[70:71], v[70:71], 0, v[126:127]
	v_cndmask_b32_e32 v8, v69, v8, vcc
	v_rsq_f32_e32 v8, v8
	v_mov_b32_e32 v125, v11
	v_and_b32_e32 v11, 0xffff0000, v44
	v_mul_f32_e32 v10, 0x45800000, v8
	v_cndmask_b32_e32 v8, v8, v10, vcc
	v_pk_mul_f32 v[52:53], v[52:53], v[8:9] op_sel_hi:[1,0]
	v_pk_mul_f32 v[54:55], v[54:55], v[8:9] op_sel_hi:[1,0]
	v_pk_mul_f32 v[48:49], v[48:49], v[8:9] op_sel_hi:[1,0]
	v_pk_mul_f32 v[50:51], v[50:51], v[8:9] op_sel_hi:[1,0]
	s_nop 0
	v_pk_mul_f32 v[52:53], v[248:249], v[52:53]
	v_pk_mul_f32 v[54:55], v[250:251], v[54:55]
	v_pk_mul_f32 v[48:49], v[252:253], v[48:49]
	v_pk_mul_f32 v[50:51], v[254:255], v[50:51]
	v_pk_mul_f32 v[52:53], v[82:83], v[52:53]
	v_pk_mul_f32 v[54:55], v[56:57], v[54:55]
	v_pk_mul_f32 v[48:49], v[58:59], v[48:49]
	v_pk_mul_f32 v[50:51], v[86:87], v[50:51]
	v_cvt_pk_bf16_f32 v52, v52, v53
	v_cvt_pk_bf16_f32 v53, v54, v55
	v_cvt_pk_bf16_f32 v54, v48, v49
	v_cvt_pk_bf16_f32 v55, v50, v51
	global_store_dwordx4 v[70:71], v[52:55], off
	s_nop 1
	s_nop 0
	s_nop 0
	s_nop 0
	v_lshlrev_b32_e32 v10, 16, v44
	v_mul_f32_e32 v8, 0xbfb8aa3b, v10
	v_mul_f32_e32 v58, 0xbfb8aa3b, v11
	v_exp_f32_e32 v8, v8
	v_lshlrev_b32_e32 v44, 16, v45
	v_exp_f32_e32 v58, v58
	v_mul_f32_e32 v59, 0xbfb8aa3b, v44
	v_and_b32_e32 v45, 0xffff0000, v45
	v_exp_f32_e32 v59, v59
	v_mul_f32_e32 v60, 0xbfb8aa3b, v45
	v_add_f32_e32 v8, 1.0, v8
	v_exp_f32_e32 v60, v60
	v_add_f32_e32 v61, 1.0, v58
	v_rcp_f32_e32 v58, v8
	v_mul_f32_e32 v8, 0x4b800000, v68
	v_cmp_gt_f32_e32 vcc, s45, v68
	v_add_f32_e32 v62, 1.0, v59
	v_rcp_f32_e32 v59, v61
	v_cndmask_b32_e32 v8, v68, v8, vcc
	v_rsq_f32_e32 v8, v8
	v_add_f32_e32 v63, 1.0, v60
	v_rcp_f32_e32 v60, v62
	v_rcp_f32_e32 v61, v63
	v_pk_mul_f32 v[10:11], v[58:59], v[10:11]
	v_mul_f32_e32 v58, 0x45800000, v8
	v_cndmask_b32_e32 v8, v8, v58, vcc
	v_pk_mul_f32 v[42:43], v[42:43], v[8:9] op_sel_hi:[1,0]
	v_pk_mul_f32 v[44:45], v[60:61], v[44:45]
	v_pk_mul_f32 v[40:41], v[40:41], v[8:9] op_sel_hi:[1,0]
	v_pk_mul_f32 v[36:37], v[36:37], v[8:9] op_sel_hi:[1,0]
	v_lshlrev_b64 v[56:57], 11, v[124:125]
	v_lshl_add_u64 v[56:57], s[28:29], 0, v[56:57]
	s_nop 0
	v_pk_mul_f32 v[42:43], v[250:251], v[42:43]
	v_pk_mul_f32 v[40:41], v[248:249], v[40:41]
	v_pk_mul_f32 v[42:43], v[44:45], v[42:43]
	v_lshlrev_b32_e32 v44, 16, v46
	v_pk_mul_f32 v[10:11], v[10:11], v[40:41]
	v_mul_f32_e32 v40, 0xbfb8aa3b, v44
	v_and_b32_e32 v45, 0xffff0000, v46
	v_exp_f32_e32 v48, v40
	v_cvt_pk_bf16_f32 v40, v10, v11
	v_mul_f32_e32 v11, 0xbfb8aa3b, v45
	v_exp_f32_e32 v11, v11
	v_cvt_pk_bf16_f32 v41, v42, v43
	v_lshlrev_b32_e32 v42, 16, v47
	v_and_b32_e32 v43, 0xffff0000, v47
	v_add_f32_e32 v10, 1.0, v48
	v_add_f32_e32 v11, 1.0, v11
	v_mul_f32_e32 v46, 0xbfb8aa3b, v42
	v_mul_f32_e32 v47, 0xbfb8aa3b, v43
	v_rcp_f32_e32 v10, v10
	v_rcp_f32_e32 v11, v11
	v_exp_f32_e32 v46, v46
	v_exp_f32_e32 v47, v47
	s_nop 0
	v_pk_mul_f32 v[36:37], v[252:253], v[36:37]
	v_pk_mul_f32 v[10:11], v[10:11], v[44:45]
	v_add_f32_e32 v44, 1.0, v46
	v_add_f32_e32 v45, 1.0, v47
	v_rcp_f32_e32 v44, v44
	v_rcp_f32_e32 v45, v45
	v_pk_mul_f32 v[10:11], v[10:11], v[36:37]
	v_pk_mul_f32 v[36:37], v[38:39], v[8:9] op_sel_hi:[1,0]
	v_pk_mul_f32 v[38:39], v[44:45], v[42:43]
	v_pk_mul_f32 v[36:37], v[254:255], v[36:37]
	v_cvt_pk_bf16_f32 v42, v10, v11
	v_lshl_add_u64 v[10:11], v[56:57], 0, s[38:39]
	v_pk_mul_f32 v[36:37], v[38:39], v[36:37]
	v_lshl_add_u64 v[10:11], v[10:11], 0, v[72:73]
	v_cvt_pk_bf16_f32 v43, v36, v37
	v_lshl_add_u64 v[10:11], v[10:11], 0, v[126:127]
	global_store_dwordx4 v[10:11], v[40:43], off
	s_nop 1
	s_barrier

.LBB0_1777:
	s_or_b64 exec, exec, s[8:9]
	s_lshl_b32 s8, s2, 2
	s_add_u32 s8, s26, s8
	s_addc_u32 s9, s27, 0
	v_lshl_add_u32 v8, v131, 2, s96
	v_lshl_add_u64 v[84:85], v[84:85], 2, s[8:9]
	s_waitcnt lgkmcnt(0)
	s_barrier
	ds_read2st64_b32 v[94:95], v8 offset1:1
	ds_read2st64_b32 v[96:97], v8 offset0:2 offset1:3
	ds_read2st64_b32 v[98:99], v8 offset0:4 offset1:5
	ds_read2st64_b32 v[100:101], v8 offset0:6 offset1:7
	global_load_dwordx4 v[252:255], v[84:85], off offset:16
	global_load_dwordx4 v[248:251], v[84:85], off
	s_waitcnt vmcnt(5)
	v_lshlrev_b32_e32 v104, 16, v72
	v_and_b32_e32 v105, 0xffff0000, v72
	v_mul_f32_e32 v8, 0xbfb8aa3b, v104
	v_exp_f32_e32 v8, v8
	v_mul_f32_e32 v72, 0xbfb8aa3b, v105
	v_exp_f32_e32 v106, v72
	v_and_b32_e32 v107, 0xffff0000, v73
	v_add_f32_e32 v8, 1.0, v8
	v_rcp_f32_e32 v72, v8
	v_add_f32_e32 v8, 1.0, v106
	v_lshlrev_b32_e32 v106, 16, v73
	v_mul_f32_e32 v73, 0xbfb8aa3b, v106
	v_exp_f32_e32 v108, v73
	v_mul_f32_e32 v73, 0xbfb8aa3b, v107
	v_exp_f32_e32 v109, v73
	v_lshlrev_b32_e32 v110, 16, v74
	v_rcp_f32_e32 v73, v8
	v_add_f32_e32 v8, 1.0, v108
	v_and_b32_e32 v111, 0xffff0000, v74
	v_mul_f32_e32 v74, 0xbfb8aa3b, v110
	v_rcp_f32_e32 v108, v8
	v_add_f32_e32 v8, 1.0, v109
	v_exp_f32_e32 v74, v74
	v_mul_f32_e32 v109, 0xbfb8aa3b, v111
	v_exp_f32_e32 v112, v109
	v_rcp_f32_e32 v109, v8
	v_add_f32_e32 v8, 1.0, v74
	v_rcp_f32_e32 v74, v8
	v_add_f32_e32 v8, 1.0, v112
	v_lshlrev_b32_e32 v112, 16, v75
	v_and_b32_e32 v113, 0xffff0000, v75
	v_mul_f32_e32 v75, 0xbfb8aa3b, v112
	v_exp_f32_e32 v114, v75
	v_mul_f32_e32 v75, 0xbfb8aa3b, v113
	v_exp_f32_e32 v115, v75
	v_rcp_f32_e32 v75, v8
	v_add_f32_e32 v8, 1.0, v114
	v_rcp_f32_e32 v114, v8
	v_add_f32_e32 v8, 1.0, v115
	v_rcp_f32_e32 v115, v8
	v_lshl_add_u32 v8, v129, 2, s96
	v_pk_mul_f32 v[106:107], v[108:109], v[106:107]
	v_pk_mul_f32 v[108:109], v[74:75], v[110:111]
	ds_read2st64_b32 v[74:75], v8 offset1:1
	v_pk_mul_f32 v[110:111], v[114:115], v[112:113]
	ds_read2st64_b32 v[112:113], v8 offset0:2 offset1:3
	ds_read2st64_b32 v[114:115], v8 offset0:4 offset1:5
	ds_read2st64_b32 v[116:117], v8 offset0:6 offset1:7
	s_waitcnt lgkmcnt(7)
	v_mov_b32_e32 v119, v94
	v_lshlrev_b64 v[102:103], 11, v[124:125]
	s_waitcnt lgkmcnt(3)
	v_mov_b32_e32 v118, v74
	v_pk_add_f32 v[118:119], v[118:119], 0 op_sel_hi:[1,0]
	v_mov_b32_e32 v94, v75
	v_pk_add_f32 v[74:75], v[118:119], v[94:95]
	s_waitcnt lgkmcnt(2)
	v_mov_b32_e32 v94, v112
	v_mov_b32_e32 v95, v96
	v_pk_add_f32 v[74:75], v[74:75], v[94:95]
	v_mov_b32_e32 v96, v113
	v_pk_add_f32 v[74:75], v[74:75], v[96:97]
	s_waitcnt lgkmcnt(1)
	v_mov_b32_e32 v94, v114
	v_mov_b32_e32 v95, v98
	v_pk_add_f32 v[74:75], v[74:75], v[94:95]
	v_mov_b32_e32 v98, v115
	v_pk_add_f32 v[74:75], v[74:75], v[98:99]
	s_waitcnt lgkmcnt(0)
	v_mov_b32_e32 v94, v116
	v_mov_b32_e32 v95, v100
	v_pk_add_f32 v[74:75], v[74:75], v[94:95]
	v_mov_b32_e32 v100, v117
	v_pk_add_f32 v[94:95], v[74:75], v[100:101]
	v_mov_b64_e32 v[74:75], s[48:49]
	v_pk_fma_f32 v[94:95], v[94:95], s[46:47], v[74:75] op_sel_hi:[1,0,0]
	v_ashrrev_i32_e32 v133, 31, v132
	v_mul_f32_e32 v8, 0x4b800000, v95
	v_cmp_gt_f32_e32 vcc, s45, v95
	v_lshl_add_u64 v[102:103], s[28:29], 0, v[102:103]
	s_lshl_b32 s38, s2, 1
	v_cndmask_b32_e32 v8, v95, v8, vcc
	v_rsq_f32_e32 v8, v8
	v_pk_mul_f32 v[104:105], v[72:73], v[104:105]
	v_lshl_add_u64 v[102:103], v[102:103], 0, s[38:39]
	v_lshlrev_b64 v[72:73], 1, v[132:133]
	v_mul_f32_e32 v95, 0x45800000, v8
	v_cndmask_b32_e32 v8, v8, v95, vcc
	v_pk_mul_f32 v[80:81], v[80:81], v[8:9] op_sel_hi:[1,0]
	v_pk_mul_f32 v[82:83], v[82:83], v[8:9] op_sel_hi:[1,0]
	v_pk_mul_f32 v[76:77], v[76:77], v[8:9] op_sel_hi:[1,0]
	v_pk_mul_f32 v[78:79], v[78:79], v[8:9] op_sel_hi:[1,0]
	s_waitcnt vmcnt(0)
	v_pk_mul_f32 v[80:81], v[248:249], v[80:81]
	v_pk_mul_f32 v[82:83], v[250:251], v[82:83]
	v_pk_mul_f32 v[76:77], v[252:253], v[76:77]
	v_pk_mul_f32 v[78:79], v[254:255], v[78:79]
	v_lshl_add_u64 v[96:97], v[102:103], 0, v[72:73]
	v_mov_b32_e32 v127, v9
	v_pk_mul_f32 v[80:81], v[104:105], v[80:81]
	v_pk_mul_f32 v[82:83], v[106:107], v[82:83]
	v_pk_mul_f32 v[76:77], v[108:109], v[76:77]
	v_pk_mul_f32 v[78:79], v[110:111], v[78:79]
	v_lshl_add_u64 v[96:97], v[96:97], 0, v[126:127]
	v_cvt_pk_bf16_f32 v80, v80, v81
	v_cvt_pk_bf16_f32 v81, v82, v83
	v_cvt_pk_bf16_f32 v82, v76, v77
	v_cvt_pk_bf16_f32 v83, v78, v79
	global_store_dwordx4 v[96:97], v[80:83], off
	s_nop 1
	s_nop 0
	s_nop 0
	s_nop 0
	v_lshlrev_b32_e32 v86, 16, v68
	v_and_b32_e32 v87, 0xffff0000, v68
	v_lshlrev_b32_e32 v68, 16, v69
	v_mul_f32_e32 v8, 0xbfb8aa3b, v86
	v_mul_f32_e32 v92, 0xbfb8aa3b, v68
	v_exp_f32_e32 v8, v8
	v_exp_f32_e32 v92, v92
	v_and_b32_e32 v69, 0xffff0000, v69
	v_lshlrev_b32_e32 v88, 16, v70
	v_and_b32_e32 v89, 0xffff0000, v70
	v_mul_f32_e32 v70, 0xbfb8aa3b, v87
	v_mul_f32_e32 v93, 0xbfb8aa3b, v69
	v_add_f32_e32 v8, 1.0, v8
	v_mul_f32_e32 v96, 0xbfb8aa3b, v89
	v_exp_f32_e32 v70, v70
	v_exp_f32_e32 v93, v93
	v_add_f32_e32 v97, 1.0, v92
	v_rcp_f32_e32 v92, v8
	v_mul_f32_e32 v8, 0x4b800000, v94
	v_cmp_gt_f32_e32 vcc, s45, v94
	v_exp_f32_e32 v96, v96
	v_add_f32_e32 v70, 1.0, v70
	v_cndmask_b32_e32 v8, v94, v8, vcc
	v_rsq_f32_e32 v8, v8
	v_add_f32_e32 v98, 1.0, v93
	v_add_f32_e32 v99, 1.0, v96
	v_rcp_f32_e32 v93, v70
	v_rcp_f32_e32 v96, v97
	v_rcp_f32_e32 v97, v98
	v_mul_f32_e32 v70, 0x45800000, v8
	v_cndmask_b32_e32 v8, v8, v70, vcc
	v_pk_mul_f32 v[64:65], v[64:65], v[8:9] op_sel_hi:[1,0]
	v_pk_mul_f32 v[66:67], v[66:67], v[8:9] op_sel_hi:[1,0]
	v_pk_mul_f32 v[86:87], v[92:93], v[86:87]
	v_pk_mul_f32 v[68:69], v[96:97], v[68:69]
	v_pk_mul_f32 v[60:61], v[60:61], v[8:9] op_sel_hi:[1,0]
	v_mul_f32_e32 v95, 0xbfb8aa3b, v88
	v_exp_f32_e32 v95, v95
	v_rcp_f32_e32 v99, v99
	v_mov_b32_e32 v131, v125
	v_pk_mul_f32 v[62:63], v[62:63], v[8:9] op_sel_hi:[1,0]
	v_add_f32_e32 v95, 1.0, v95
	v_rcp_f32_e32 v98, v95
	v_lshlrev_b64 v[90:91], 11, v[130:131]
	v_lshl_add_u64 v[90:91], s[28:29], 0, v[90:91]
	v_lshl_add_u32 v8, v177, 2, s96
	v_mov_b32_e32 v129, v125
	s_cmpk_gt_i32 s47, 0x3ff
	s_mov_b64 s[8:9], -1
	s_nop 0
	v_pk_mul_f32 v[64:65], v[248:249], v[64:65]
	v_pk_mul_f32 v[66:67], v[250:251], v[66:67]
	s_nop 0
	v_pk_mul_f32 v[76:77], v[252:253], v[60:61]
	v_pk_mul_f32 v[60:61], v[86:87], v[64:65]
	v_pk_mul_f32 v[64:65], v[68:69], v[66:67]
	v_cvt_pk_bf16_f32 v60, v60, v61
	v_cvt_pk_bf16_f32 v61, v64, v65
	v_lshlrev_b32_e32 v64, 16, v71
	v_and_b32_e32 v65, 0xffff0000, v71
	v_mul_f32_e32 v66, 0xbfb8aa3b, v64
	v_exp_f32_e32 v68, v66
	v_mul_f32_e32 v66, 0xbfb8aa3b, v65
	v_exp_f32_e32 v69, v66
	v_pk_mul_f32 v[62:63], v[254:255], v[62:63]
	v_add_f32_e32 v68, 1.0, v68
	v_rcp_f32_e32 v68, v68
	v_add_f32_e32 v69, 1.0, v69
	v_rcp_f32_e32 v69, v69
	v_pk_mul_f32 v[66:67], v[98:99], v[88:89]
	v_lshlrev_b32_e32 v82, 16, v56
	v_pk_mul_f32 v[66:67], v[66:67], v[76:77]
	v_pk_mul_f32 v[64:65], v[68:69], v[64:65]
	v_and_b32_e32 v83, 0xffff0000, v56
	v_pk_mul_f32 v[64:65], v[64:65], v[62:63]
	v_cvt_pk_bf16_f32 v62, v66, v67
	v_cvt_pk_bf16_f32 v63, v64, v65
	v_lshl_add_u64 v[64:65], v[90:91], 0, s[38:39]
	v_lshl_add_u64 v[64:65], v[64:65], 0, v[72:73]
	v_lshl_add_u64 v[64:65], v[64:65], 0, v[126:127]
	global_store_dwordx4 v[64:65], v[60:63], off
	s_nop 1
	ds_read2st64_b32 v[68:69], v8 offset1:1
	ds_read2st64_b32 v[70:71], v8 offset0:2 offset1:3
	ds_read2st64_b32 v[76:77], v8 offset0:4 offset1:5
	ds_read2st64_b32 v[78:79], v8 offset0:6 offset1:7
	s_nop 0
	s_nop 0
	v_mul_f32_e32 v8, 0xbfb8aa3b, v82
	v_exp_f32_e32 v8, v8
	v_mul_f32_e32 v56, 0xbfb8aa3b, v83
	v_exp_f32_e32 v56, v56
	v_and_b32_e32 v89, 0xffff0000, v58
	v_add_f32_e32 v8, 1.0, v8
	v_rcp_f32_e32 v86, v8
	v_add_f32_e32 v8, 1.0, v56
	v_lshlrev_b32_e32 v56, 16, v57
	v_rcp_f32_e32 v87, v8
	v_and_b32_e32 v57, 0xffff0000, v57
	v_mul_f32_e32 v8, 0xbfb8aa3b, v56
	v_exp_f32_e32 v8, v8
	v_mul_f32_e32 v88, 0xbfb8aa3b, v57
	v_exp_f32_e32 v88, v88
	v_pk_mul_f32 v[82:83], v[86:87], v[82:83]
	v_add_f32_e32 v8, 1.0, v8
	v_rcp_f32_e32 v86, v8
	v_add_f32_e32 v8, 1.0, v88
	v_lshlrev_b32_e32 v88, 16, v58
	v_rcp_f32_e32 v87, v8
	v_mul_f32_e32 v8, 0xbfb8aa3b, v88
	v_exp_f32_e32 v8, v8
	v_mul_f32_e32 v58, 0xbfb8aa3b, v89
	v_exp_f32_e32 v90, v58
	v_pk_mul_f32 v[56:57], v[86:87], v[56:57]
	v_lshlrev_b32_e32 v86, 16, v59
	v_add_f32_e32 v8, 1.0, v8
	v_and_b32_e32 v87, 0xffff0000, v59
	v_mul_f32_e32 v59, 0xbfb8aa3b, v86
	v_rcp_f32_e32 v58, v8
	v_add_f32_e32 v8, 1.0, v90
	v_exp_f32_e32 v90, v59
	v_mul_f32_e32 v59, 0xbfb8aa3b, v87
	v_exp_f32_e32 v91, v59
	v_rcp_f32_e32 v59, v8
	v_add_f32_e32 v8, 1.0, v90
	v_rcp_f32_e32 v90, v8
	v_add_f32_e32 v8, 1.0, v91
	v_rcp_f32_e32 v91, v8
	v_lshl_add_u32 v8, v11, 2, s96
	v_pk_mul_f32 v[58:59], v[58:59], v[88:89]
	ds_read2st64_b32 v[88:89], v8 offset1:1
	v_pk_mul_f32 v[86:87], v[90:91], v[86:87]
	ds_read2st64_b32 v[90:91], v8 offset0:2 offset1:3
	ds_read2st64_b32 v[92:93], v8 offset0:4 offset1:5
	ds_read2st64_b32 v[94:95], v8 offset0:6 offset1:7
	s_waitcnt lgkmcnt(7)
	v_mov_b32_e32 v97, v68
	v_lshlrev_b64 v[80:81], 11, v[128:129]
	s_waitcnt lgkmcnt(3)
	v_mov_b32_e32 v96, v88
	v_pk_add_f32 v[96:97], v[96:97], 0 op_sel_hi:[1,0]
	v_mov_b32_e32 v68, v89
	v_pk_add_f32 v[68:69], v[96:97], v[68:69]
	s_waitcnt lgkmcnt(2)
	v_mov_b32_e32 v88, v90
	v_mov_b32_e32 v89, v70
	v_pk_add_f32 v[68:69], v[68:69], v[88:89]
	v_mov_b32_e32 v70, v91
	v_pk_add_f32 v[68:69], v[68:69], v[70:71]
	s_waitcnt lgkmcnt(1)
	v_mov_b32_e32 v70, v92
	v_mov_b32_e32 v71, v76
	v_pk_add_f32 v[68:69], v[68:69], v[70:71]
	v_mov_b32_e32 v76, v93
	v_pk_add_f32 v[68:69], v[68:69], v[76:77]
	s_waitcnt lgkmcnt(0)
	v_mov_b32_e32 v70, v94
	v_mov_b32_e32 v71, v78
	v_pk_add_f32 v[68:69], v[68:69], v[70:71]
	v_mov_b32_e32 v78, v95
	v_pk_add_f32 v[68:69], v[68:69], v[78:79]
	v_lshl_add_u64 v[80:81], s[28:29], 0, v[80:81]
	v_pk_fma_f32 v[68:69], v[68:69], s[46:47], v[74:75] op_sel_hi:[1,0,0]
	v_lshl_add_u64 v[70:71], v[80:81], 0, s[38:39]
	v_mul_f32_e32 v8, 0x4b800000, v69
	v_cmp_gt_f32_e32 vcc, s45, v69
	v_lshl_add_u64 v[70:71], v[70:71], 0, v[72:73]
	v_lshl_add_u64 v[70:71], v[70:71], 0, v[126:127]
	v_cndmask_b32_e32 v8, v69, v8, vcc
	v_rsq_f32_e32 v8, v8
	s_nop 0
	v_mul_f32_e32 v11, 0x45800000, v8
	v_cndmask_b32_e32 v8, v8, v11, vcc
	v_pk_mul_f32 v[52:53], v[52:53], v[8:9] op_sel_hi:[1,0]
	v_pk_mul_f32 v[54:55], v[54:55], v[8:9] op_sel_hi:[1,0]
	v_pk_mul_f32 v[48:49], v[48:49], v[8:9] op_sel_hi:[1,0]
	v_pk_mul_f32 v[50:51], v[50:51], v[8:9] op_sel_hi:[1,0]
	s_nop 0
	v_pk_mul_f32 v[52:53], v[248:249], v[52:53]
	v_pk_mul_f32 v[54:55], v[250:251], v[54:55]
	v_pk_mul_f32 v[48:49], v[252:253], v[48:49]
	v_pk_mul_f32 v[50:51], v[254:255], v[50:51]
	v_pk_mul_f32 v[52:53], v[82:83], v[52:53]
	v_pk_mul_f32 v[54:55], v[56:57], v[54:55]
	v_pk_mul_f32 v[48:49], v[58:59], v[48:49]
	v_pk_mul_f32 v[50:51], v[86:87], v[50:51]
	v_cvt_pk_bf16_f32 v52, v52, v53
	v_cvt_pk_bf16_f32 v53, v54, v55
	v_cvt_pk_bf16_f32 v54, v48, v49
	v_cvt_pk_bf16_f32 v55, v50, v51
	global_store_dwordx4 v[70:71], v[52:55], off
	s_nop 1
	s_nop 0
	s_nop 0
	s_nop 0
	v_lshlrev_b32_e32 v56, 16, v44
	v_and_b32_e32 v57, 0xffff0000, v44
	v_lshlrev_b32_e32 v44, 16, v45
	v_mul_f32_e32 v8, 0xbfb8aa3b, v56
	v_mul_f32_e32 v60, 0xbfb8aa3b, v44
	v_exp_f32_e32 v8, v8
	v_exp_f32_e32 v60, v60
	v_and_b32_e32 v45, 0xffff0000, v45
	v_mul_f32_e32 v61, 0xbfb8aa3b, v45
	v_add_f32_e32 v8, 1.0, v8
	v_mul_f32_e32 v59, 0xbfb8aa3b, v57
	v_exp_f32_e32 v61, v61
	v_add_f32_e32 v62, 1.0, v60
	v_rcp_f32_e32 v60, v8
	v_mul_f32_e32 v8, 0x4b800000, v68
	v_cmp_gt_f32_e32 vcc, s45, v68
	v_exp_f32_e32 v59, v59
	v_add_f32_e32 v63, 1.0, v61
	v_cndmask_b32_e32 v8, v68, v8, vcc
	v_rsq_f32_e32 v8, v8
	v_add_f32_e32 v59, 1.0, v59
	v_rcp_f32_e32 v62, v62
	v_rcp_f32_e32 v63, v63
	v_rcp_f32_e32 v61, v59
	v_mul_f32_e32 v59, 0x45800000, v8
	v_cndmask_b32_e32 v8, v8, v59, vcc
	v_pk_mul_f32 v[42:43], v[42:43], v[8:9] op_sel_hi:[1,0]
	v_lshlrev_b32_e32 v58, 16, v46
	v_pk_mul_f32 v[44:45], v[62:63], v[44:45]
	v_pk_mul_f32 v[40:41], v[40:41], v[8:9] op_sel_hi:[1,0]
	v_pk_mul_f32 v[56:57], v[60:61], v[56:57]
	v_and_b32_e32 v59, 0xffff0000, v46
	v_mov_b32_e32 v11, v125
	v_lshlrev_b64 v[10:11], 11, v[10:11]
	v_pk_mul_f32 v[36:37], v[36:37], v[8:9] op_sel_hi:[1,0]
	v_lshl_add_u64 v[10:11], s[28:29], 0, v[10:11]
	v_pk_mul_f32 v[38:39], v[38:39], v[8:9] op_sel_hi:[1,0]
	v_lshl_add_u64 v[10:11], v[10:11], 0, s[38:39]
	v_lshl_add_u64 v[10:11], v[10:11], 0, v[72:73]
	v_lshl_add_u64 v[10:11], v[10:11], 0, v[126:127]
	s_nop 0
	v_pk_mul_f32 v[42:43], v[250:251], v[42:43]
	s_nop 0
	v_pk_mul_f32 v[42:43], v[44:45], v[42:43]
	v_mul_f32_e32 v44, 0xbfb8aa3b, v58
	v_exp_f32_e32 v44, v44
	v_pk_mul_f32 v[40:41], v[248:249], v[40:41]
	v_and_b32_e32 v45, 0xffff0000, v47
	v_pk_mul_f32 v[40:41], v[56:57], v[40:41]
	s_nop 0
	v_pk_mul_f32 v[36:37], v[252:253], v[36:37]
	v_cvt_pk_bf16_f32 v40, v40, v41
	v_cvt_pk_bf16_f32 v41, v42, v43
	v_add_f32_e32 v42, 1.0, v44
	v_mul_f32_e32 v43, 0xbfb8aa3b, v59
	v_lshlrev_b32_e32 v44, 16, v47
	v_exp_f32_e32 v43, v43
	v_mul_f32_e32 v46, 0xbfb8aa3b, v44
	v_mul_f32_e32 v47, 0xbfb8aa3b, v45
	v_exp_f32_e32 v46, v46
	v_exp_f32_e32 v47, v47
	v_add_f32_e32 v43, 1.0, v43
	v_rcp_f32_e32 v42, v42
	v_rcp_f32_e32 v43, v43
	v_add_f32_e32 v46, 1.0, v46
	v_add_f32_e32 v47, 1.0, v47
	v_rcp_f32_e32 v46, v46
	v_rcp_f32_e32 v47, v47
	v_pk_mul_f32 v[42:43], v[42:43], v[58:59]
	v_pk_mul_f32 v[38:39], v[254:255], v[38:39]
	v_pk_mul_f32 v[36:37], v[42:43], v[36:37]
	v_pk_mul_f32 v[42:43], v[46:47], v[44:45]
	s_nop 0
	v_pk_mul_f32 v[38:39], v[42:43], v[38:39]
	v_cvt_pk_bf16_f32 v42, v36, v37
	v_cvt_pk_bf16_f32 v43, v38, v39
	global_store_dwordx4 v[10:11], v[40:43], off
	s_nop 1
	s_barrier
	s_cbranch_scc1 .LBB0_1738
	s_add_i32 s2, s89, s49
	s_cmpk_gt_i32 s2, 0x3ff
	s_cbranch_scc1 .LBB0_1780
	v_mov_b32_e32 v8, v204
	s_ashr_i32 s8, s2, 8
	s_ashr_i32 s9, s8, 31
	v_ashrrev_i32_e32 v0, 31, v8
	s_add_i32 s2, s88, s3
	v_lshrrev_b32_e32 v0, 27, v0
	s_lshl_b64 s[8:9], s[8:9], 12
	s_and_b32 s2, s2, 0xfc0
	v_add_u32_e32 v1, v8, v0
	s_or_b32 s2, s8, s2
	v_ashrrev_i32_e32 v0, 5, v1
	v_and_b32_e32 v1, 0x1fffffe0, v1
	s_add_u32 s8, s2, 0x4000
	v_sub_u32_e32 v1, v8, v1
	s_addc_u32 s9, s9, 0
	v_lshlrev_b32_e32 v2, 3, v1
	v_ashrrev_i32_e32 v1, 31, v0
	v_add_u32_e32 v13, 0x400, v8
	s_add_i32 s2, s83, s72
	v_lshl_add_u64 v[0:1], s[8:9], 0, v[0:1]
	v_mov_b64_e32 v[10:11], s[30:31]
	v_ashrrev_i32_e32 v12, 31, v13
	s_and_b32 s2, s2, 0x300
	v_mad_u64_u32 v[4:5], s[10:11], v0, s0, v[10:11]
	v_lshrrev_b32_e32 v12, 27, v12
	v_mad_i32_i24 v5, v1, s0, v5
	s_lshl_b32 s38, s2, 1
	v_add_u32_e32 v14, v13, v12
	v_lshl_add_u64 v[0:1], v[4:5], 0, s[38:39]
	v_ashrrev_i32_e32 v3, 31, v2
	v_ashrrev_i32_e32 v12, 5, v14
	v_and_b32_e32 v14, 0x1fffffe0, v14
	v_lshl_add_u64 v[0:1], v[2:3], 1, v[0:1]
	v_add_u32_e32 v3, 0x200, v8
	v_sub_u32_e32 v13, v13, v14
	v_ashrrev_i32_e32 v2, 31, v3
	v_lshlrev_b32_e32 v14, 3, v13
	v_ashrrev_i32_e32 v13, 31, v12
	v_lshrrev_b32_e32 v2, 27, v2
	v_lshl_add_u64 v[12:13], s[8:9], 0, v[12:13]
	v_add_u32_e32 v4, v3, v2
	v_mad_u64_u32 v[16:17], s[10:11], v12, s0, v[10:11]
	v_ashrrev_i32_e32 v2, 5, v4
	v_and_b32_e32 v4, 0x1fffffe0, v4
	v_mad_i32_i24 v17, v13, s0, v17
	v_sub_u32_e32 v3, v3, v4
	v_lshl_add_u64 v[12:13], v[16:17], 0, s[38:39]
	v_ashrrev_i32_e32 v15, 31, v14
	v_add_u32_e32 v8, 0x600, v8
	v_lshlrev_b32_e32 v4, 3, v3
	v_ashrrev_i32_e32 v3, 31, v2
	v_lshl_add_u64 v[12:13], v[14:15], 1, v[12:13]
	v_ashrrev_i32_e32 v14, 31, v8
	v_lshl_add_u64 v[2:3], s[8:9], 0, v[2:3]
	v_lshrrev_b32_e32 v14, 27, v14
	v_mad_u64_u32 v[6:7], s[10:11], v2, s0, v[10:11]
	v_add_u32_e32 v15, v8, v14
	v_mad_i32_i24 v7, v3, s0, v7
	v_ashrrev_i32_e32 v14, 5, v15
	v_and_b32_e32 v15, 0x1fffffe0, v15
	v_add_co_u32_e32 v0, vcc, s1, v0
	v_lshl_add_u64 v[2:3], v[6:7], 0, s[38:39]
	v_ashrrev_i32_e32 v5, 31, v4
	v_sub_u32_e32 v8, v8, v15
	v_ashrrev_i32_e32 v15, 31, v14
	v_addc_co_u32_e32 v1, vcc, 0, v1, vcc
	v_lshl_add_u64 v[2:3], v[4:5], 1, v[2:3]
	v_lshl_add_u64 v[14:15], s[8:9], 0, v[14:15]
	v_add_co_u32_e32 v4, vcc, s1, v2
	v_mad_u64_u32 v[10:11], s[8:9], v14, s0, v[10:11]
	s_nop 0
	v_addc_co_u32_e32 v5, vcc, 0, v3, vcc
	v_lshlrev_b32_e32 v16, 3, v8
	v_mad_i32_i24 v11, v15, s0, v11
	v_add_co_u32_e32 v12, vcc, s1, v12
	v_lshl_add_u64 v[10:11], v[10:11], 0, s[38:39]
	v_ashrrev_i32_e32 v17, 31, v16
	v_addc_co_u32_e32 v13, vcc, 0, v13, vcc
	v_lshl_add_u64 v[10:11], v[16:17], 1, v[10:11]
	v_add_co_u32_e32 v10, vcc, 0x7a00000, v10
	global_load_dwordx4 v[0:3], v[0:1], off offset:2048
	s_nop 0
	global_load_dwordx4 v[4:7], v[4:5], off offset:2048
	v_addc_co_u32_e32 v11, vcc, 0, v11, vcc
	global_load_dwordx4 v[12:15], v[12:13], off offset:2048
	s_nop 0
	global_load_dwordx4 v[16:19], v[10:11], off offset:2048

.LBB0_1981:
	ds_read_b128 v[164:167], v155
	ds_read_b128 v[168:171], v155 offset:1024
	ds_read_b128 v[172:175], v155 offset:2048
	ds_read_b128 v[176:179], v155 offset:3072
	s_add_u32 s42, s10, 0xfffc0080
	s_addc_u32 s43, s11, -1
	s_cmp_eq_u32 s66, 12
	s_cselect_b32 s45, s9, s43
	s_cselect_b32 s44, s37, s42
	s_cselect_b32 s43, s35, s65
	s_cselect_b32 s42, s63, s64
	v_lshl_add_u64 v[146:147], s[10:11], 0, v[136:137]
	s_add_i32 m0, s46, 0xc000
	ds_read_b128 v[180:183], v159
	ds_read_b128 v[184:187], v159 offset:1024
	ds_read_b128 v[188:191], v159 offset:2048
	ds_read_b128 v[192:195], v159 offset:3072
	ds_read_b128 v[196:199], v159 offset:4096
	ds_read_b128 v[200:203], v159 offset:5120
	ds_read_b128 v[206:209], v159 offset:6144
	ds_read_b128 v[210:213], v159 offset:7168
	global_load_lds_dwordx4 v[146:147], off
	v_lshl_add_u64 v[146:147], s[10:11], 0, v[138:139]
	s_add_i32 m0, s46, 0xe000
	s_nop 0
	global_load_lds_dwordx4 v[146:147], off
	s_waitcnt lgkmcnt(8)
	s_barrier
	s_waitcnt lgkmcnt(0)
	s_setprio 1
	s_waitcnt lgkmcnt(0)
	v_mfma_f32_16x16x32_bf16 v[124:127], v[164:167], v[180:183], v[124:127]
	v_mfma_f32_16x16x32_bf16 v[120:123], v[172:175], v[180:183], v[120:123]
	v_mfma_f32_16x16x32_bf16 v[108:111], v[164:167], v[188:191], v[108:111]
	v_mfma_f32_16x16x32_bf16 v[104:107], v[172:175], v[188:191], v[104:107]
	v_mfma_f32_16x16x32_bf16 v[92:95], v[164:167], v[196:199], v[92:95]
	v_mfma_f32_16x16x32_bf16 v[88:91], v[172:175], v[196:199], v[88:91]
	v_mfma_f32_16x16x32_bf16 v[76:79], v[164:167], v[206:209], v[76:79]
	v_mfma_f32_16x16x32_bf16 v[72:75], v[172:175], v[206:209], v[72:75]
	v_mfma_f32_16x16x32_bf16 v[124:127], v[168:171], v[184:187], v[124:127]
	v_mfma_f32_16x16x32_bf16 v[120:123], v[176:179], v[184:187], v[120:123]
	v_mfma_f32_16x16x32_bf16 v[108:111], v[168:171], v[192:195], v[108:111]
	v_mfma_f32_16x16x32_bf16 v[104:107], v[176:179], v[192:195], v[104:107]
	v_mfma_f32_16x16x32_bf16 v[92:95], v[168:171], v[200:203], v[92:95]
	v_mfma_f32_16x16x32_bf16 v[88:91], v[176:179], v[200:203], v[88:91]
	v_mfma_f32_16x16x32_bf16 v[76:79], v[168:171], v[210:213], v[76:79]
	v_mfma_f32_16x16x32_bf16 v[72:75], v[176:179], v[210:213], v[72:75]
	s_setprio 0
	s_barrier
	s_add_i32 s67, s55, s33
	v_lshl_add_u64 v[146:147], s[42:43], 0, v[130:131]
	s_mov_b32 m0, s67
	ds_read_b128 v[214:217], v162
	ds_read_b128 v[218:221], v162 offset:1024
	ds_read_b128 v[222:225], v162 offset:2048
	ds_read_b128 v[226:229], v162 offset:3072
	global_load_lds_dwordx4 v[146:147], off
	v_lshl_add_u64 v[152:153], s[42:43], 0, v[134:135]
	s_add_i32 m0, s67, 0x2000
	s_nop 0
	global_load_lds_dwordx4 v[152:153], off
	s_barrier
	s_waitcnt lgkmcnt(0)
	s_setprio 1
	s_waitcnt lgkmcnt(0)
	v_mfma_f32_16x16x32_bf16 v[116:119], v[214:217], v[180:183], v[116:119]
	v_mfma_f32_16x16x32_bf16 v[112:115], v[222:225], v[180:183], v[112:115]
	v_mfma_f32_16x16x32_bf16 v[100:103], v[214:217], v[188:191], v[100:103]
	v_mfma_f32_16x16x32_bf16 v[96:99], v[222:225], v[188:191], v[96:99]
	v_mfma_f32_16x16x32_bf16 v[84:87], v[214:217], v[196:199], v[84:87]
	v_mfma_f32_16x16x32_bf16 v[80:83], v[222:225], v[196:199], v[80:83]
	v_mfma_f32_16x16x32_bf16 v[68:71], v[214:217], v[206:209], v[68:71]
	v_mfma_f32_16x16x32_bf16 v[64:67], v[222:225], v[206:209], v[64:67]
	v_mfma_f32_16x16x32_bf16 v[116:119], v[218:221], v[184:187], v[116:119]
	v_mfma_f32_16x16x32_bf16 v[112:115], v[226:229], v[184:187], v[112:115]
	v_mfma_f32_16x16x32_bf16 v[100:103], v[218:221], v[192:195], v[100:103]
	v_mfma_f32_16x16x32_bf16 v[96:99], v[226:229], v[192:195], v[96:99]
	v_mfma_f32_16x16x32_bf16 v[84:87], v[218:221], v[200:203], v[84:87]
	v_mfma_f32_16x16x32_bf16 v[80:83], v[226:229], v[200:203], v[80:83]
	v_mfma_f32_16x16x32_bf16 v[68:71], v[218:221], v[210:213], v[68:71]
	v_mfma_f32_16x16x32_bf16 v[64:67], v[226:229], v[210:213], v[64:67]
	s_setprio 0
	s_mov_b32 m0, s46
	v_lshl_add_u64 v[156:157], s[44:45], 0, v[128:129]
	s_barrier
	ds_read_b128 v[180:183], v159 offset:16384
	ds_read_b128 v[184:187], v159 offset:17408
	ds_read_b128 v[188:191], v159 offset:18432
	ds_read_b128 v[192:195], v159 offset:19456
	ds_read_b128 v[196:199], v159 offset:20480
	ds_read_b128 v[200:203], v159 offset:21504
	ds_read_b128 v[206:209], v159 offset:22528
	ds_read_b128 v[210:213], v159 offset:23552
	global_load_lds_dwordx4 v[156:157], off
	v_lshl_add_u64 v[160:161], s[44:45], 0, v[132:133]
	s_mov_b32 m0, s47
	s_nop 0
	global_load_lds_dwordx4 v[160:161], off
	s_barrier
	s_waitcnt lgkmcnt(0)
	s_setprio 1
	s_waitcnt lgkmcnt(0)
	v_mfma_f32_16x16x32_bf16 v[60:63], v[164:167], v[180:183], v[60:63]
	v_mfma_f32_16x16x32_bf16 v[56:59], v[172:175], v[180:183], v[56:59]
	v_mfma_f32_16x16x32_bf16 v[44:47], v[164:167], v[188:191], v[44:47]
	v_mfma_f32_16x16x32_bf16 v[40:43], v[172:175], v[188:191], v[40:43]
	v_mfma_f32_16x16x32_bf16 v[28:31], v[164:167], v[196:199], v[28:31]
	v_mfma_f32_16x16x32_bf16 v[24:27], v[172:175], v[196:199], v[24:27]
	v_mfma_f32_16x16x32_bf16 v[12:15], v[164:167], v[206:209], v[12:15]
	v_mfma_f32_16x16x32_bf16 v[8:11], v[172:175], v[206:209], v[8:11]
	v_mfma_f32_16x16x32_bf16 v[60:63], v[168:171], v[184:187], v[60:63]
	v_mfma_f32_16x16x32_bf16 v[56:59], v[176:179], v[184:187], v[56:59]
	v_mfma_f32_16x16x32_bf16 v[44:47], v[168:171], v[192:195], v[44:47]
	v_mfma_f32_16x16x32_bf16 v[40:43], v[176:179], v[192:195], v[40:43]
	v_mfma_f32_16x16x32_bf16 v[28:31], v[168:171], v[200:203], v[28:31]
	v_mfma_f32_16x16x32_bf16 v[24:27], v[176:179], v[200:203], v[24:27]
	v_mfma_f32_16x16x32_bf16 v[12:15], v[168:171], v[210:213], v[12:15]
	v_mfma_f32_16x16x32_bf16 v[8:11], v[176:179], v[210:213], v[8:11]
	s_setprio 0
	s_barrier
	s_add_u32 s68, s42, 0x40000
	s_addc_u32 s69, s43, 0
	s_add_i32 s67, s56, s33
	v_lshl_add_u64 v[164:165], s[68:69], 0, v[130:131]
	s_mov_b32 m0, s67
	s_nop 0
	global_load_lds_dwordx4 v[164:165], off
	v_lshl_add_u64 v[164:165], s[68:69], 0, v[134:135]
	s_add_i32 m0, s67, 0x2000
	s_nop 0
	global_load_lds_dwordx4 v[164:165], off
	s_waitcnt vmcnt(6)
	s_cmp_gt_u32 s66, 10
	s_cbranch_scc1 .Lds_P16_a_done
	s_cmp_lt_u32 s66, 6
	s_cbranch_scc1 .Lds_P16_a_st
	s_cmp_eq_u32 s66, 6
	s_cbranch_scc1 .Lds_P16_a_pf
	s_cmp_eq_u32 s66, 8
	s_cbranch_scc1 .Lds_P16_a_c8
	v_ffbh_u32_e32 v252, v241
	v_min_u32_e32 v252, 32, v252
	v_lshlrev_b64 v[240:241], v252, v[240:241]
	v_min_u32_e32 v240, 1, v240
	v_or_b32_e32 v241, v241, v240
	v_cvt_f32_u32_e32 v241, v241
	v_sub_u32_e32 v252, -2, v252
	v_ldexp_f32 v241, v241, v252
	v_add_f32_e32 v241, 0x358637bd, v241
	v_rsq_f32_e32 v252, v241
	v_ffbh_u32_e32 v253, v243
	v_min_u32_e32 v253, 32, v253
	v_lshlrev_b64 v[242:243], v253, v[242:243]
	v_min_u32_e32 v242, 1, v242
	v_or_b32_e32 v243, v243, v242
	v_cvt_f32_u32_e32 v243, v243
	v_sub_u32_e32 v253, -2, v253
	v_ldexp_f32 v243, v243, v253
	v_add_f32_e32 v243, 0x358637bd, v243
	v_rsq_f32_e32 v253, v243
	s_branch .Lds_P16_a_done

.Lds_P16_a_pf:
	s_lshl_b32 s82, s8, 11
	s_add_u32 s100, s16, s82
	s_addc_u32 s101, s17, 0
	v_lshlrev_b32_e32 v252, 3, v145
	global_load_dwordx2 v[230:231], v252, s[100:101]
	global_load_dwordx2 v[232:233], v252, s[100:101] offset:128
	global_load_dwordx2 v[234:235], v252, s[100:101] offset:256
	global_load_dwordx2 v[236:237], v252, s[100:101] offset:384
	global_load_dwordx2 v[240:241], v252, s[100:101] offset:1024
	global_load_dwordx2 v[242:243], v252, s[100:101] offset:1152
	global_load_dwordx2 v[244:245], v252, s[100:101] offset:1280
	global_load_dwordx2 v[246:247], v252, s[100:101] offset:1408
	s_branch .Lds_P16_a_done
.Lds_P16_a_st:
	s_cmp_eq_u32 s32, 0
	s_cbranch_scc1 .Lds_P16_a_done
	s_cmp_eq_u32 s66, 0
	s_cbranch_scc1 .Lds_P16_a_0
	s_cmp_eq_u32 s66, 2
	s_cbranch_scc1 .Lds_P16_a_1
	s_add_u32 s100, s98, 0x160000
	s_addc_u32 s101, s99, 0
	global_store_dwordx4 v239, v[248:251], s[100:101]
	s_branch .Lds_P16_a_done

.Lds_P16_a_done:
	s_barrier
	s_setprio 1
	v_mfma_f32_16x16x32_bf16 v[52:55], v[214:217], v[180:183], v[52:55]
	v_mfma_f32_16x16x32_bf16 v[48:51], v[222:225], v[180:183], v[48:51]
	v_mfma_f32_16x16x32_bf16 v[36:39], v[214:217], v[188:191], v[36:39]
	v_mfma_f32_16x16x32_bf16 v[32:35], v[222:225], v[188:191], v[32:35]
	v_mfma_f32_16x16x32_bf16 v[20:23], v[214:217], v[196:199], v[20:23]
	v_mfma_f32_16x16x32_bf16 v[16:19], v[222:225], v[196:199], v[16:19]
	v_mfma_f32_16x16x32_bf16 v[4:7], v[214:217], v[206:209], v[4:7]
	v_mfma_f32_16x16x32_bf16 v[0:3], v[222:225], v[206:209], v[0:3]
	v_mfma_f32_16x16x32_bf16 v[52:55], v[218:221], v[184:187], v[52:55]
	v_mfma_f32_16x16x32_bf16 v[48:51], v[226:229], v[184:187], v[48:51]
	v_mfma_f32_16x16x32_bf16 v[36:39], v[218:221], v[192:195], v[36:39]
	v_mfma_f32_16x16x32_bf16 v[32:35], v[226:229], v[192:195], v[32:35]
	v_mfma_f32_16x16x32_bf16 v[20:23], v[218:221], v[200:203], v[20:23]
	v_mfma_f32_16x16x32_bf16 v[16:19], v[226:229], v[200:203], v[16:19]
	v_mfma_f32_16x16x32_bf16 v[4:7], v[218:221], v[210:213], v[4:7]
	v_mfma_f32_16x16x32_bf16 v[0:3], v[226:229], v[210:213], v[0:3]
	s_setprio 0
	s_add_i32 s67, 0, 0x18000
	v_add_u32_e32 v144, s67, v149
	s_barrier
	ds_read_b128 v[164:167], v144
	ds_read_b128 v[168:171], v144 offset:1024
	ds_read_b128 v[172:175], v144 offset:2048
	ds_read_b128 v[176:179], v144 offset:3072
	s_add_u32 s44, s44, 0x40000
	s_addc_u32 s45, s45, 0
	s_mov_b32 m0, s48
	v_lshl_add_u64 v[214:215], s[44:45], 0, v[128:129]
	ds_read_b128 v[180:183], v159 offset:32768
	ds_read_b128 v[184:187], v159 offset:33792
	ds_read_b128 v[188:191], v159 offset:34816
	ds_read_b128 v[192:195], v159 offset:35840
	ds_read_b128 v[196:199], v159 offset:36864
	ds_read_b128 v[200:203], v159 offset:37888
	ds_read_b128 v[206:209], v159 offset:38912
	ds_read_b128 v[210:213], v159 offset:39936
	global_load_lds_dwordx4 v[214:215], off
	v_lshl_add_u64 v[214:215], s[44:45], 0, v[132:133]
	s_mov_b32 m0, s49
	s_nop 0
	global_load_lds_dwordx4 v[214:215], off
	s_waitcnt lgkmcnt(8)
	s_barrier
	s_waitcnt lgkmcnt(0)
	s_setprio 1
	s_waitcnt lgkmcnt(0)
	v_mfma_f32_16x16x32_bf16 v[124:127], v[164:167], v[180:183], v[124:127]
	v_mfma_f32_16x16x32_bf16 v[120:123], v[172:175], v[180:183], v[120:123]
	v_mfma_f32_16x16x32_bf16 v[108:111], v[164:167], v[188:191], v[108:111]
	v_mfma_f32_16x16x32_bf16 v[104:107], v[172:175], v[188:191], v[104:107]
	v_mfma_f32_16x16x32_bf16 v[92:95], v[164:167], v[196:199], v[92:95]
	v_mfma_f32_16x16x32_bf16 v[88:91], v[172:175], v[196:199], v[88:91]
	v_mfma_f32_16x16x32_bf16 v[76:79], v[164:167], v[206:209], v[76:79]
	v_mfma_f32_16x16x32_bf16 v[72:75], v[172:175], v[206:209], v[72:75]
	v_mfma_f32_16x16x32_bf16 v[124:127], v[168:171], v[184:187], v[124:127]
	v_mfma_f32_16x16x32_bf16 v[120:123], v[176:179], v[184:187], v[120:123]
	v_mfma_f32_16x16x32_bf16 v[108:111], v[168:171], v[192:195], v[108:111]
	v_mfma_f32_16x16x32_bf16 v[104:107], v[176:179], v[192:195], v[104:107]
	v_mfma_f32_16x16x32_bf16 v[92:95], v[168:171], v[200:203], v[92:95]
	v_mfma_f32_16x16x32_bf16 v[88:91], v[176:179], v[200:203], v[88:91]
	v_mfma_f32_16x16x32_bf16 v[76:79], v[168:171], v[210:213], v[76:79]
	v_mfma_f32_16x16x32_bf16 v[72:75], v[176:179], v[210:213], v[72:75]
	s_setprio 0
	s_barrier
	s_add_i32 s44, 0, 0x1c000
	s_add_i32 s45, s67, s33
	v_add_u32_e32 v144, s44, v149
	v_lshl_add_u64 v[146:147], v[146:147], 0, s[18:19]
	s_mov_b32 m0, s45
	ds_read_b128 v[214:217], v144
	ds_read_b128 v[218:221], v144 offset:1024
	ds_read_b128 v[222:225], v144 offset:2048
	ds_read_b128 v[226:229], v144 offset:3072
	global_load_lds_dwordx4 v[146:147], off
	v_lshl_add_u64 v[146:147], v[152:153], 0, s[18:19]
	s_add_i32 m0, s45, 0x2000
	s_nop 0
	global_load_lds_dwordx4 v[146:147], off
	s_barrier
	s_waitcnt lgkmcnt(0)
	s_setprio 1
	s_waitcnt lgkmcnt(0)
	v_mfma_f32_16x16x32_bf16 v[116:119], v[214:217], v[180:183], v[116:119]
	v_mfma_f32_16x16x32_bf16 v[112:115], v[222:225], v[180:183], v[112:115]
	v_mfma_f32_16x16x32_bf16 v[100:103], v[214:217], v[188:191], v[100:103]
	v_mfma_f32_16x16x32_bf16 v[96:99], v[222:225], v[188:191], v[96:99]
	v_mfma_f32_16x16x32_bf16 v[84:87], v[214:217], v[196:199], v[84:87]
	v_mfma_f32_16x16x32_bf16 v[80:83], v[222:225], v[196:199], v[80:83]
	v_mfma_f32_16x16x32_bf16 v[68:71], v[214:217], v[206:209], v[68:71]
	v_mfma_f32_16x16x32_bf16 v[64:67], v[222:225], v[206:209], v[64:67]
	v_mfma_f32_16x16x32_bf16 v[116:119], v[218:221], v[184:187], v[116:119]
	v_mfma_f32_16x16x32_bf16 v[112:115], v[226:229], v[184:187], v[112:115]
	v_mfma_f32_16x16x32_bf16 v[100:103], v[218:221], v[192:195], v[100:103]
	v_mfma_f32_16x16x32_bf16 v[96:99], v[226:229], v[192:195], v[96:99]
	v_mfma_f32_16x16x32_bf16 v[84:87], v[218:221], v[200:203], v[84:87]
	v_mfma_f32_16x16x32_bf16 v[80:83], v[226:229], v[200:203], v[80:83]
	v_mfma_f32_16x16x32_bf16 v[68:71], v[218:221], v[210:213], v[68:71]
	v_mfma_f32_16x16x32_bf16 v[64:67], v[226:229], v[210:213], v[64:67]
	s_setprio 0
	s_mov_b32 m0, s51
	v_lshl_add_u64 v[146:147], v[156:157], 0, s[18:19]
	s_barrier
	ds_read_b128 v[180:183], v159 offset:49152
	ds_read_b128 v[184:187], v159 offset:50176
	ds_read_b128 v[188:191], v159 offset:51200
	ds_read_b128 v[192:195], v159 offset:52224
	ds_read_b128 v[196:199], v159 offset:53248
	ds_read_b128 v[200:203], v159 offset:54272
	ds_read_b128 v[206:209], v159 offset:55296
	ds_read_b128 v[210:213], v159 offset:56320
	global_load_lds_dwordx4 v[146:147], off
	v_lshl_add_u64 v[146:147], v[160:161], 0, s[18:19]
	s_mov_b32 m0, s52
	s_nop 0
	global_load_lds_dwordx4 v[146:147], off
	s_barrier
	s_waitcnt lgkmcnt(0)
	s_setprio 1
	s_waitcnt lgkmcnt(0)
	v_mfma_f32_16x16x32_bf16 v[60:63], v[164:167], v[180:183], v[60:63]
	v_mfma_f32_16x16x32_bf16 v[56:59], v[172:175], v[180:183], v[56:59]
	v_mfma_f32_16x16x32_bf16 v[44:47], v[164:167], v[188:191], v[44:47]
	v_mfma_f32_16x16x32_bf16 v[40:43], v[172:175], v[188:191], v[40:43]
	v_mfma_f32_16x16x32_bf16 v[28:31], v[164:167], v[196:199], v[28:31]
	v_mfma_f32_16x16x32_bf16 v[24:27], v[172:175], v[196:199], v[24:27]
	v_mfma_f32_16x16x32_bf16 v[12:15], v[164:167], v[206:209], v[12:15]
	v_mfma_f32_16x16x32_bf16 v[8:11], v[172:175], v[206:209], v[8:11]
	v_mfma_f32_16x16x32_bf16 v[60:63], v[168:171], v[184:187], v[60:63]
	v_mfma_f32_16x16x32_bf16 v[56:59], v[176:179], v[184:187], v[56:59]
	v_mfma_f32_16x16x32_bf16 v[44:47], v[168:171], v[192:195], v[44:47]
	v_mfma_f32_16x16x32_bf16 v[40:43], v[176:179], v[192:195], v[40:43]
	v_mfma_f32_16x16x32_bf16 v[28:31], v[168:171], v[200:203], v[28:31]
	v_mfma_f32_16x16x32_bf16 v[24:27], v[176:179], v[200:203], v[24:27]
	v_mfma_f32_16x16x32_bf16 v[12:15], v[168:171], v[210:213], v[12:15]
	v_mfma_f32_16x16x32_bf16 v[8:11], v[176:179], v[210:213], v[8:11]
	s_setprio 0
	s_barrier
	s_add_u32 s42, s42, 0x40080
	s_addc_u32 s43, s43, 0
	s_add_i32 s44, s44, s33
	v_lshl_add_u64 v[146:147], s[42:43], 0, v[130:131]
	s_mov_b32 m0, s44
	s_nop 0
	global_load_lds_dwordx4 v[146:147], off
	v_lshl_add_u64 v[146:147], s[42:43], 0, v[134:135]
	s_add_i32 m0, s44, 0x2000
	s_nop 0
	global_load_lds_dwordx4 v[146:147], off
	s_waitcnt vmcnt(6)
	s_cmp_gt_u32 s66, 10
	s_cbranch_scc1 .Lds_P16_b_done
	s_cmp_lt_u32 s66, 6
	s_cbranch_scc1 .Lds_P16_b_st
	s_cmp_eq_u32 s66, 6
	s_cbranch_scc1 .Lds_P16_b_done
	s_cmp_eq_u32 s66, 8
	s_cbranch_scc1 .Lds_P16_b_c8
	v_ffbh_u32_e32 v254, v245
	v_min_u32_e32 v254, 32, v254
	v_lshlrev_b64 v[244:245], v254, v[244:245]
	v_min_u32_e32 v244, 1, v244
	v_or_b32_e32 v245, v245, v244
	v_cvt_f32_u32_e32 v245, v245
	v_sub_u32_e32 v254, -2, v254
	v_ldexp_f32 v245, v245, v254
	v_add_f32_e32 v245, 0x358637bd, v245
	v_rsq_f32_e32 v254, v245
	v_ffbh_u32_e32 v255, v247
	v_min_u32_e32 v255, 32, v255
	v_lshlrev_b64 v[246:247], v255, v[246:247]
	v_min_u32_e32 v246, 1, v246
	v_or_b32_e32 v247, v247, v246
	v_cvt_f32_u32_e32 v247, v247
	v_sub_u32_e32 v255, -2, v255
	v_ldexp_f32 v247, v247, v255
	v_add_f32_e32 v247, 0x358637bd, v247
	v_rsq_f32_e32 v255, v247
	s_branch .Lds_P16_b_done

.Lds_P16_b_st:
	s_cmp_eq_u32 s32, 0
	s_cbranch_scc1 .Lds_P16_b_done
	s_cmp_eq_u32 s66, 0
	s_cbranch_scc1 .Lds_P16_b_0
	s_cmp_eq_u32 s66, 2
	s_cbranch_scc1 .Lds_P16_b_1
	s_add_u32 s100, s98, 0x160000
	s_addc_u32 s101, s99, 0
	global_store_dwordx4 v239, v[252:255], s[100:101] offset:256
	s_branch .Lds_P16_b_done

.Lepi_P16_start:
	s_mul_i32 s82, s8, 0x200000
	s_lshl_b32 s84, s62, 9
	s_add_u32 s82, s82, s84
	s_add_u32 s84, s14, s82
	s_addc_u32 s85, s15, 0
	v_pk_mul_f32 v[124:125], v[124:125], v[248:249] op_sel_hi:[1,0]
	v_pk_mul_f32 v[126:127], v[126:127], v[248:249] op_sel_hi:[1,0]
	v_pk_mul_f32 v[120:121], v[120:121], v[248:249] op_sel_hi:[1,0]
	v_pk_mul_f32 v[122:123], v[122:123], v[248:249] op_sel_hi:[1,0]
	v_max_f32_e32 v124, 0, v124
	v_max_f32_e32 v125, 0, v125
	v_max_f32_e32 v126, 0, v126
	v_max_f32_e32 v127, 0, v127
	v_max_f32_e32 v120, 0, v120
	v_max_f32_e32 v121, 0, v121
	v_max_f32_e32 v122, 0, v122
	v_max_f32_e32 v123, 0, v123
	v_pk_mul_f32 v[124:125], v[124:125], v[124:125]
	v_pk_mul_f32 v[126:127], v[126:127], v[126:127]
	v_pk_mul_f32 v[120:121], v[120:121], v[120:121]
	v_pk_mul_f32 v[122:123], v[122:123], v[122:123]
	v_cvt_pk_bf16_f32 v124, v124, v125
	v_cvt_pk_bf16_f32 v125, v126, v127
	v_cvt_pk_bf16_f32 v126, v120, v121
	v_cvt_pk_bf16_f32 v127, v122, v123
	global_store_dwordx4 v239, v[124:127], s[84:85]
	v_pk_mul_f32 v[116:117], v[116:117], v[248:249] op_sel_hi:[1,0]
	v_pk_mul_f32 v[118:119], v[118:119], v[248:249] op_sel_hi:[1,0]
	v_pk_mul_f32 v[112:113], v[112:113], v[248:249] op_sel_hi:[1,0]
	v_pk_mul_f32 v[114:115], v[114:115], v[248:249] op_sel_hi:[1,0]
	v_max_f32_e32 v116, 0, v116
	v_max_f32_e32 v117, 0, v117
	v_max_f32_e32 v118, 0, v118
	v_max_f32_e32 v119, 0, v119
	v_max_f32_e32 v112, 0, v112
	v_max_f32_e32 v113, 0, v113
	v_max_f32_e32 v114, 0, v114
	v_max_f32_e32 v115, 0, v115
	v_pk_mul_f32 v[116:117], v[116:117], v[116:117]
	v_pk_mul_f32 v[118:119], v[118:119], v[118:119]
	v_pk_mul_f32 v[112:113], v[112:113], v[112:113]
	v_pk_mul_f32 v[114:115], v[114:115], v[114:115]
	v_cvt_pk_bf16_f32 v116, v116, v117
	v_cvt_pk_bf16_f32 v117, v118, v119
	v_cvt_pk_bf16_f32 v118, v112, v113
	v_cvt_pk_bf16_f32 v119, v114, v115
	global_store_dwordx4 v239, v[116:119], s[84:85] offset:256
	v_pk_mul_f32 v[108:109], v[108:109], v[248:249] op_sel:[0,1] op_sel_hi:[1,1]
	v_pk_mul_f32 v[110:111], v[110:111], v[248:249] op_sel:[0,1] op_sel_hi:[1,1]
	v_pk_mul_f32 v[104:105], v[104:105], v[248:249] op_sel:[0,1] op_sel_hi:[1,1]
	v_pk_mul_f32 v[106:107], v[106:107], v[248:249] op_sel:[0,1] op_sel_hi:[1,1]
	v_max_f32_e32 v108, 0, v108
	v_max_f32_e32 v109, 0, v109
	v_max_f32_e32 v110, 0, v110
	v_max_f32_e32 v111, 0, v111
	v_max_f32_e32 v104, 0, v104
	v_max_f32_e32 v105, 0, v105
	v_max_f32_e32 v106, 0, v106
	v_max_f32_e32 v107, 0, v107
	v_pk_mul_f32 v[108:109], v[108:109], v[108:109]
	v_pk_mul_f32 v[110:111], v[110:111], v[110:111]
	v_pk_mul_f32 v[104:105], v[104:105], v[104:105]
	v_pk_mul_f32 v[106:107], v[106:107], v[106:107]
	v_cvt_pk_bf16_f32 v108, v108, v109
	v_cvt_pk_bf16_f32 v109, v110, v111
	v_cvt_pk_bf16_f32 v110, v104, v105
	v_cvt_pk_bf16_f32 v111, v106, v107
	s_add_u32 s100, s84, 0x20000
	s_addc_u32 s101, s85, 0
	global_store_dwordx4 v239, v[108:111], s[100:101]
	v_pk_mul_f32 v[100:101], v[100:101], v[248:249] op_sel:[0,1] op_sel_hi:[1,1]
	v_pk_mul_f32 v[102:103], v[102:103], v[248:249] op_sel:[0,1] op_sel_hi:[1,1]
	v_pk_mul_f32 v[96:97], v[96:97], v[248:249] op_sel:[0,1] op_sel_hi:[1,1]
	v_pk_mul_f32 v[98:99], v[98:99], v[248:249] op_sel:[0,1] op_sel_hi:[1,1]
	v_max_f32_e32 v100, 0, v100
	v_max_f32_e32 v101, 0, v101
	v_max_f32_e32 v102, 0, v102
	v_max_f32_e32 v103, 0, v103
	v_max_f32_e32 v96, 0, v96
	v_max_f32_e32 v97, 0, v97
	v_max_f32_e32 v98, 0, v98
	v_max_f32_e32 v99, 0, v99
	v_pk_mul_f32 v[100:101], v[100:101], v[100:101]
	v_pk_mul_f32 v[102:103], v[102:103], v[102:103]
	v_pk_mul_f32 v[96:97], v[96:97], v[96:97]
	v_pk_mul_f32 v[98:99], v[98:99], v[98:99]
	v_cvt_pk_bf16_f32 v100, v100, v101
	v_cvt_pk_bf16_f32 v101, v102, v103
	v_cvt_pk_bf16_f32 v102, v96, v97
	v_cvt_pk_bf16_f32 v103, v98, v99
	s_add_u32 s100, s84, 0x20000
	s_addc_u32 s101, s85, 0
	global_store_dwordx4 v239, v[100:103], s[100:101] offset:256
	v_pk_mul_f32 v[92:93], v[92:93], v[250:251] op_sel_hi:[1,0]
	v_pk_mul_f32 v[94:95], v[94:95], v[250:251] op_sel_hi:[1,0]
	v_pk_mul_f32 v[88:89], v[88:89], v[250:251] op_sel_hi:[1,0]
	v_pk_mul_f32 v[90:91], v[90:91], v[250:251] op_sel_hi:[1,0]
	v_max_f32_e32 v92, 0, v92
	v_max_f32_e32 v93, 0, v93
	v_max_f32_e32 v94, 0, v94
	v_max_f32_e32 v95, 0, v95
	v_max_f32_e32 v88, 0, v88
	v_max_f32_e32 v89, 0, v89
	v_max_f32_e32 v90, 0, v90
	v_max_f32_e32 v91, 0, v91
	v_pk_mul_f32 v[92:93], v[92:93], v[92:93]
	v_pk_mul_f32 v[94:95], v[94:95], v[94:95]
	v_pk_mul_f32 v[88:89], v[88:89], v[88:89]
	v_pk_mul_f32 v[90:91], v[90:91], v[90:91]
	v_cvt_pk_bf16_f32 v92, v92, v93
	v_cvt_pk_bf16_f32 v93, v94, v95
	v_cvt_pk_bf16_f32 v94, v88, v89
	v_cvt_pk_bf16_f32 v95, v90, v91
	s_add_u32 s100, s84, 0x40000
	s_addc_u32 s101, s85, 0
	global_store_dwordx4 v239, v[92:95], s[100:101]
	v_pk_mul_f32 v[84:85], v[84:85], v[250:251] op_sel_hi:[1,0]
	v_pk_mul_f32 v[86:87], v[86:87], v[250:251] op_sel_hi:[1,0]
	v_pk_mul_f32 v[80:81], v[80:81], v[250:251] op_sel_hi:[1,0]
	v_pk_mul_f32 v[82:83], v[82:83], v[250:251] op_sel_hi:[1,0]
	v_max_f32_e32 v84, 0, v84
	v_max_f32_e32 v85, 0, v85
	v_max_f32_e32 v86, 0, v86
	v_max_f32_e32 v87, 0, v87
	v_max_f32_e32 v80, 0, v80
	v_max_f32_e32 v81, 0, v81
	v_max_f32_e32 v82, 0, v82
	v_max_f32_e32 v83, 0, v83
	v_pk_mul_f32 v[84:85], v[84:85], v[84:85]
	v_pk_mul_f32 v[86:87], v[86:87], v[86:87]
	v_pk_mul_f32 v[80:81], v[80:81], v[80:81]
	v_pk_mul_f32 v[82:83], v[82:83], v[82:83]
	v_cvt_pk_bf16_f32 v84, v84, v85
	v_cvt_pk_bf16_f32 v85, v86, v87
	v_cvt_pk_bf16_f32 v86, v80, v81
	v_cvt_pk_bf16_f32 v87, v82, v83
	s_add_u32 s100, s84, 0x40000
	s_addc_u32 s101, s85, 0
	global_store_dwordx4 v239, v[84:87], s[100:101] offset:256
	v_pk_mul_f32 v[76:77], v[76:77], v[250:251] op_sel:[0,1] op_sel_hi:[1,1]
	v_pk_mul_f32 v[78:79], v[78:79], v[250:251] op_sel:[0,1] op_sel_hi:[1,1]
	v_pk_mul_f32 v[72:73], v[72:73], v[250:251] op_sel:[0,1] op_sel_hi:[1,1]
	v_pk_mul_f32 v[74:75], v[74:75], v[250:251] op_sel:[0,1] op_sel_hi:[1,1]
	v_max_f32_e32 v76, 0, v76
	v_max_f32_e32 v77, 0, v77
	v_max_f32_e32 v78, 0, v78
	v_max_f32_e32 v79, 0, v79
	v_max_f32_e32 v72, 0, v72
	v_max_f32_e32 v73, 0, v73
	v_max_f32_e32 v74, 0, v74
	v_max_f32_e32 v75, 0, v75
	v_pk_mul_f32 v[76:77], v[76:77], v[76:77]
	v_pk_mul_f32 v[78:79], v[78:79], v[78:79]
	v_pk_mul_f32 v[72:73], v[72:73], v[72:73]
	v_pk_mul_f32 v[74:75], v[74:75], v[74:75]
	v_cvt_pk_bf16_f32 v76, v76, v77
	v_cvt_pk_bf16_f32 v77, v78, v79
	v_cvt_pk_bf16_f32 v78, v72, v73
	v_cvt_pk_bf16_f32 v79, v74, v75
	s_add_u32 s100, s84, 0x60000
	s_addc_u32 s101, s85, 0
	global_store_dwordx4 v239, v[76:79], s[100:101]
	v_pk_mul_f32 v[68:69], v[68:69], v[250:251] op_sel:[0,1] op_sel_hi:[1,1]
	v_pk_mul_f32 v[70:71], v[70:71], v[250:251] op_sel:[0,1] op_sel_hi:[1,1]
	v_pk_mul_f32 v[64:65], v[64:65], v[250:251] op_sel:[0,1] op_sel_hi:[1,1]
	v_pk_mul_f32 v[66:67], v[66:67], v[250:251] op_sel:[0,1] op_sel_hi:[1,1]
	v_max_f32_e32 v68, 0, v68
	v_max_f32_e32 v69, 0, v69
	v_max_f32_e32 v70, 0, v70
	v_max_f32_e32 v71, 0, v71
	v_max_f32_e32 v64, 0, v64
	v_max_f32_e32 v65, 0, v65
	v_max_f32_e32 v66, 0, v66
	v_max_f32_e32 v67, 0, v67
	v_pk_mul_f32 v[68:69], v[68:69], v[68:69]
	v_pk_mul_f32 v[70:71], v[70:71], v[70:71]
	v_pk_mul_f32 v[64:65], v[64:65], v[64:65]
	v_pk_mul_f32 v[66:67], v[66:67], v[66:67]
	v_cvt_pk_bf16_f32 v68, v68, v69
	v_cvt_pk_bf16_f32 v69, v70, v71
	v_cvt_pk_bf16_f32 v70, v64, v65
	v_cvt_pk_bf16_f32 v71, v66, v67
	s_add_u32 s100, s84, 0x60000
	s_addc_u32 s101, s85, 0
	global_store_dwordx4 v239, v[68:71], s[100:101] offset:256
	v_pk_mul_f32 v[60:61], v[60:61], v[252:253] op_sel_hi:[1,0]
	v_pk_mul_f32 v[62:63], v[62:63], v[252:253] op_sel_hi:[1,0]
	v_pk_mul_f32 v[56:57], v[56:57], v[252:253] op_sel_hi:[1,0]
	v_pk_mul_f32 v[58:59], v[58:59], v[252:253] op_sel_hi:[1,0]
	v_max_f32_e32 v60, 0, v60
	v_max_f32_e32 v61, 0, v61
	v_max_f32_e32 v62, 0, v62
	v_max_f32_e32 v63, 0, v63
	v_max_f32_e32 v56, 0, v56
	v_max_f32_e32 v57, 0, v57
	v_max_f32_e32 v58, 0, v58
	v_max_f32_e32 v59, 0, v59
	v_pk_mul_f32 v[60:61], v[60:61], v[60:61]
	v_pk_mul_f32 v[62:63], v[62:63], v[62:63]
	v_pk_mul_f32 v[56:57], v[56:57], v[56:57]
	v_pk_mul_f32 v[58:59], v[58:59], v[58:59]
	v_cvt_pk_bf16_f32 v60, v60, v61
	v_cvt_pk_bf16_f32 v61, v62, v63
	v_cvt_pk_bf16_f32 v62, v56, v57
	v_cvt_pk_bf16_f32 v63, v58, v59
	s_add_u32 s100, s84, 0x100000
	s_addc_u32 s101, s85, 0
	global_store_dwordx4 v239, v[60:63], s[100:101]
	v_pk_mul_f32 v[52:53], v[52:53], v[252:253] op_sel_hi:[1,0]
	v_pk_mul_f32 v[54:55], v[54:55], v[252:253] op_sel_hi:[1,0]
	v_pk_mul_f32 v[48:49], v[48:49], v[252:253] op_sel_hi:[1,0]
	v_pk_mul_f32 v[50:51], v[50:51], v[252:253] op_sel_hi:[1,0]
	v_max_f32_e32 v52, 0, v52
	v_max_f32_e32 v53, 0, v53
	v_max_f32_e32 v54, 0, v54
	v_max_f32_e32 v55, 0, v55
	v_max_f32_e32 v48, 0, v48
	v_max_f32_e32 v49, 0, v49
	v_max_f32_e32 v50, 0, v50
	v_max_f32_e32 v51, 0, v51
	v_pk_mul_f32 v[52:53], v[52:53], v[52:53]
	v_pk_mul_f32 v[54:55], v[54:55], v[54:55]
	v_pk_mul_f32 v[48:49], v[48:49], v[48:49]
	v_pk_mul_f32 v[50:51], v[50:51], v[50:51]
	v_cvt_pk_bf16_f32 v52, v52, v53
	v_cvt_pk_bf16_f32 v53, v54, v55
	v_cvt_pk_bf16_f32 v54, v48, v49
	v_cvt_pk_bf16_f32 v55, v50, v51
	s_add_u32 s100, s84, 0x100000
	s_addc_u32 s101, s85, 0
	global_store_dwordx4 v239, v[52:55], s[100:101] offset:256
	v_pk_mul_f32 v[44:45], v[44:45], v[252:253] op_sel:[0,1] op_sel_hi:[1,1]
	v_pk_mul_f32 v[46:47], v[46:47], v[252:253] op_sel:[0,1] op_sel_hi:[1,1]
	v_pk_mul_f32 v[40:41], v[40:41], v[252:253] op_sel:[0,1] op_sel_hi:[1,1]
	v_pk_mul_f32 v[42:43], v[42:43], v[252:253] op_sel:[0,1] op_sel_hi:[1,1]
	v_max_f32_e32 v44, 0, v44
	v_max_f32_e32 v45, 0, v45
	v_max_f32_e32 v46, 0, v46
	v_max_f32_e32 v47, 0, v47
	v_max_f32_e32 v40, 0, v40
	v_max_f32_e32 v41, 0, v41
	v_max_f32_e32 v42, 0, v42
	v_max_f32_e32 v43, 0, v43
	v_pk_mul_f32 v[44:45], v[44:45], v[44:45]
	v_pk_mul_f32 v[46:47], v[46:47], v[46:47]
	v_pk_mul_f32 v[40:41], v[40:41], v[40:41]
	v_pk_mul_f32 v[42:43], v[42:43], v[42:43]
	v_cvt_pk_bf16_f32 v230, v44, v45
	v_cvt_pk_bf16_f32 v231, v46, v47
	v_cvt_pk_bf16_f32 v232, v40, v41
	v_cvt_pk_bf16_f32 v233, v42, v43
	v_pk_mul_f32 v[36:37], v[36:37], v[252:253] op_sel:[0,1] op_sel_hi:[1,1]
	v_pk_mul_f32 v[38:39], v[38:39], v[252:253] op_sel:[0,1] op_sel_hi:[1,1]
	v_pk_mul_f32 v[32:33], v[32:33], v[252:253] op_sel:[0,1] op_sel_hi:[1,1]
	v_pk_mul_f32 v[34:35], v[34:35], v[252:253] op_sel:[0,1] op_sel_hi:[1,1]
	v_max_f32_e32 v36, 0, v36
	v_max_f32_e32 v37, 0, v37
	v_max_f32_e32 v38, 0, v38
	v_max_f32_e32 v39, 0, v39
	v_max_f32_e32 v32, 0, v32
	v_max_f32_e32 v33, 0, v33
	v_max_f32_e32 v34, 0, v34
	v_max_f32_e32 v35, 0, v35
	v_pk_mul_f32 v[36:37], v[36:37], v[36:37]
	v_pk_mul_f32 v[38:39], v[38:39], v[38:39]
	v_pk_mul_f32 v[32:33], v[32:33], v[32:33]
	v_pk_mul_f32 v[34:35], v[34:35], v[34:35]
	v_cvt_pk_bf16_f32 v234, v36, v37
	v_cvt_pk_bf16_f32 v235, v38, v39
	v_cvt_pk_bf16_f32 v236, v32, v33
	v_cvt_pk_bf16_f32 v237, v34, v35
	v_pk_mul_f32 v[28:29], v[28:29], v[254:255] op_sel_hi:[1,0]
	v_pk_mul_f32 v[30:31], v[30:31], v[254:255] op_sel_hi:[1,0]
	v_pk_mul_f32 v[24:25], v[24:25], v[254:255] op_sel_hi:[1,0]
	v_pk_mul_f32 v[26:27], v[26:27], v[254:255] op_sel_hi:[1,0]
	v_max_f32_e32 v28, 0, v28
	v_max_f32_e32 v29, 0, v29
	v_max_f32_e32 v30, 0, v30
	v_max_f32_e32 v31, 0, v31
	v_max_f32_e32 v24, 0, v24
	v_max_f32_e32 v25, 0, v25
	v_max_f32_e32 v26, 0, v26
	v_max_f32_e32 v27, 0, v27
	v_pk_mul_f32 v[28:29], v[28:29], v[28:29]
	v_pk_mul_f32 v[30:31], v[30:31], v[30:31]
	v_pk_mul_f32 v[24:25], v[24:25], v[24:25]
	v_pk_mul_f32 v[26:27], v[26:27], v[26:27]
	v_cvt_pk_bf16_f32 v240, v28, v29
	v_cvt_pk_bf16_f32 v241, v30, v31
	v_cvt_pk_bf16_f32 v242, v24, v25
	v_cvt_pk_bf16_f32 v243, v26, v27
	v_pk_mul_f32 v[20:21], v[20:21], v[254:255] op_sel_hi:[1,0]
	v_pk_mul_f32 v[22:23], v[22:23], v[254:255] op_sel_hi:[1,0]
	v_pk_mul_f32 v[16:17], v[16:17], v[254:255] op_sel_hi:[1,0]
	v_pk_mul_f32 v[18:19], v[18:19], v[254:255] op_sel_hi:[1,0]
	v_max_f32_e32 v20, 0, v20
	v_max_f32_e32 v21, 0, v21
	v_max_f32_e32 v22, 0, v22
	v_max_f32_e32 v23, 0, v23
	v_max_f32_e32 v16, 0, v16
	v_max_f32_e32 v17, 0, v17
	v_max_f32_e32 v18, 0, v18
	v_max_f32_e32 v19, 0, v19
	v_pk_mul_f32 v[20:21], v[20:21], v[20:21]
	v_pk_mul_f32 v[22:23], v[22:23], v[22:23]
	v_pk_mul_f32 v[16:17], v[16:17], v[16:17]
	v_pk_mul_f32 v[18:19], v[18:19], v[18:19]
	v_cvt_pk_bf16_f32 v244, v20, v21
	v_cvt_pk_bf16_f32 v245, v22, v23
	v_cvt_pk_bf16_f32 v246, v16, v17
	v_cvt_pk_bf16_f32 v247, v18, v19
	v_pk_mul_f32 v[12:13], v[12:13], v[254:255] op_sel:[0,1] op_sel_hi:[1,1]
	v_pk_mul_f32 v[14:15], v[14:15], v[254:255] op_sel:[0,1] op_sel_hi:[1,1]
	v_pk_mul_f32 v[8:9], v[8:9], v[254:255] op_sel:[0,1] op_sel_hi:[1,1]
	v_pk_mul_f32 v[10:11], v[10:11], v[254:255] op_sel:[0,1] op_sel_hi:[1,1]
	v_max_f32_e32 v12, 0, v12
	v_max_f32_e32 v13, 0, v13
	v_max_f32_e32 v14, 0, v14
	v_max_f32_e32 v15, 0, v15
	v_max_f32_e32 v8, 0, v8
	v_max_f32_e32 v9, 0, v9
	v_max_f32_e32 v10, 0, v10
	v_max_f32_e32 v11, 0, v11
	v_pk_mul_f32 v[12:13], v[12:13], v[12:13]
	v_pk_mul_f32 v[14:15], v[14:15], v[14:15]
	v_pk_mul_f32 v[8:9], v[8:9], v[8:9]
	v_pk_mul_f32 v[10:11], v[10:11], v[10:11]
	v_cvt_pk_bf16_f32 v248, v12, v13
	v_cvt_pk_bf16_f32 v249, v14, v15
	v_cvt_pk_bf16_f32 v250, v8, v9
	v_cvt_pk_bf16_f32 v251, v10, v11
	v_pk_mul_f32 v[4:5], v[4:5], v[254:255] op_sel:[0,1] op_sel_hi:[1,1]
	v_pk_mul_f32 v[6:7], v[6:7], v[254:255] op_sel:[0,1] op_sel_hi:[1,1]
	v_pk_mul_f32 v[0:1], v[0:1], v[254:255] op_sel:[0,1] op_sel_hi:[1,1]
	v_pk_mul_f32 v[2:3], v[2:3], v[254:255] op_sel:[0,1] op_sel_hi:[1,1]
	v_max_f32_e32 v4, 0, v4
	v_max_f32_e32 v5, 0, v5
	v_max_f32_e32 v6, 0, v6
	v_max_f32_e32 v7, 0, v7
	v_max_f32_e32 v0, 0, v0
	v_max_f32_e32 v1, 0, v1
	v_max_f32_e32 v2, 0, v2
	v_max_f32_e32 v3, 0, v3
	v_pk_mul_f32 v[4:5], v[4:5], v[4:5]
	v_pk_mul_f32 v[6:7], v[6:7], v[6:7]
	v_pk_mul_f32 v[0:1], v[0:1], v[0:1]
	v_pk_mul_f32 v[2:3], v[2:3], v[2:3]
	v_cvt_pk_bf16_f32 v252, v4, v5
	v_cvt_pk_bf16_f32 v253, v6, v7
	v_cvt_pk_bf16_f32 v254, v0, v1
	v_cvt_pk_bf16_f32 v255, v2, v3
	s_mov_b64 s[42:43], s[40:41]
	s_and_b64 vcc, exec, s[6:7]
	s_mov_b32 s62, s34
	s_mov_b32 s8, s36
	s_mov_b64 s[10:11], s[38:39]
	s_mov_b64 s[98:99], s[84:85]
	s_mov_b32 s32, 1
	s_cbranch_vccz .LBB0_1974
	s_add_u32 s100, s84, 0x120000
	s_addc_u32 s101, s85, 0
	global_store_dwordx4 v239, v[230:233], s[100:101]
	s_add_u32 s100, s84, 0x120000
	s_addc_u32 s101, s85, 0
	global_store_dwordx4 v239, v[234:237], s[100:101] offset:256
	s_add_u32 s100, s84, 0x140000
	s_addc_u32 s101, s85, 0
	global_store_dwordx4 v239, v[240:243], s[100:101]
	s_add_u32 s100, s84, 0x140000
	s_addc_u32 s101, s85, 0
	global_store_dwordx4 v239, v[244:247], s[100:101] offset:256
	s_add_u32 s100, s84, 0x160000
	s_addc_u32 s101, s85, 0
	global_store_dwordx4 v239, v[248:251], s[100:101]
	s_add_u32 s100, s84, 0x160000
	s_addc_u32 s101, s85, 0
	global_store_dwordx4 v239, v[252:255], s[100:101] offset:256
	s_waitcnt vmcnt(0)
	s_cmpk_gt_u32 s0, 0xff
	s_cbranch_scc1 .LBB0_1985
	s_barrier
